# GEMM k-loops: B operand via LDS-DMA (global_load_lds_dwordx4, source-side swizzle) into a 3-stage LDS ring, no B staging VGPRs/ds_writes, loop unrolled x6 with static tail
# speedup vs baseline: 1.0049x; 1.0049x over previous
.LBB0_215:
	s_mul_hi_i32 s0, s8, 0x2aaaaaab
	s_lshr_b32 s1, s0, 31
	s_ashr_i32 s0, s0, 5
	s_add_i32 s0, s0, s1
	s_lshl_b32 s1, s0, 3
	s_sub_i32 s2, 17, s1
	s_min_u32 s2, s2, 8
	v_cvt_f32_ubyte0_e32 v0, s2
	v_rcp_iflag_f32_e32 v0, v0
	s_sub_i32 s5, 0, s2
	s_mulk_i32 s0, 0xff40
	s_add_i32 s3, s0, s8
	v_mul_f32_e32 v0, 0x4f7ffffe, v0
	v_cvt_u32_f32_e32 v0, v0
	s_abs_i32 s4, s3
	s_ashr_i32 s0, s3, 31
	v_mov_b32_e32 v181, v179
	v_readfirstlane_b32 s6, v0
	s_mul_i32 s5, s5, s6
	s_mul_hi_u32 s5, s6, s5
	s_add_i32 s6, s6, s5
	s_mul_hi_u32 s5, s4, s6
	s_mul_i32 s6, s5, s2
	s_sub_i32 s4, s4, s6
	s_add_i32 s6, s5, 1
	s_sub_i32 s7, s4, s2
	s_cmp_ge_u32 s4, s2
	s_cselect_b32 s5, s6, s5
	s_cselect_b32 s4, s7, s4
	s_add_i32 s6, s5, 1
	s_cmp_ge_u32 s4, s2
	s_cselect_b32 s4, s6, s5
	s_xor_b32 s4, s4, s0
	s_sub_i32 s0, s4, s0
	s_mul_i32 s2, s2, s0
	s_sub_i32 s2, s3, s2
	s_add_i32 s1, s1, s11
	s_add_i32 s2, s1, s2
	v_ashrrev_i32_e32 v233, 6, v181
	v_lshlrev_b32_e32 v0, 1, v233
	v_lshl_add_u32 v0, s2, 3, v0
	v_ashrrev_i32_e32 v1, 31, v0
	v_bfe_u32 v183, v181, 5, 1
	v_lshlrev_b64 v[0:1], 16, v[0:1]
	v_and_b32_e32 v231, 31, v181
	v_lshl_add_u64 v[0:1], s[64:65], 0, v[0:1]
	v_lshlrev_b32_e32 v176, 9, v183
	s_ashr_i32 s1, s0, 31
	v_lshl_add_u64 v[0:1], v[0:1], 0, v[176:177]
	v_lshlrev_b32_e32 v176, 4, v231
	v_ashrrev_i32_e32 v12, 2, v181
	s_lshl_b64 s[4:5], s[0:1], 18
	v_lshl_add_u64 v[184:185], v[0:1], 0, v[176:177]
	s_add_u32 s4, s9, s4
	v_lshlrev_b32_e32 v0, 5, v12
	s_addc_u32 s5, s10, s5
	v_ashrrev_i32_e32 v1, 31, v0
	v_lshlrev_b32_e32 v2, 4, v181
	v_lshl_add_u64 v[0:1], v[0:1], 1, s[4:5]
	v_and_b32_e32 v176, 48, v2
	v_lshl_add_u64 v[186:187], v[0:1], 0, v[176:177]
	s_movk_i32 s1, 0x2000
	v_add_co_u32_e32 v8, vcc, s1, v186
	v_mul_u32_u24_e32 v10, 40, v231
	s_nop 0
	v_addc_co_u32_e32 v9, vcc, 0, v187, vcc
	v_lshlrev_b32_e32 v11, 4, v183
	v_lshl_add_u32 v235, v10, 1, v11
	v_add_co_u32_e32 v10, vcc, s41, v184
	s_movk_i32 s3, 0x50
	s_nop 0
	v_addc_co_u32_e32 v11, vcc, 0, v185, vcc
	v_and_b32_e32 v232, 63, v181
	v_lshlrev_b32_e32 v234, 3, v181
	v_bfe_u32 v197, v181, 4, 2
	v_lshlrev_b32_e32 v197, 1, v197
	v_mov_b32_e32 v176, 0x78
	v_lshrrev_b32_e32 v197, v197, v176
	v_and_b32_e32 v197, 3, v197
	v_and_b32_e32 v196, 3, v181
	v_xor_b32_e32 v197, v197, v196
	v_lshlrev_b32_e32 v197, 4, v197
	v_and_b32_e32 v188, 0xffffffcf, v186
	v_or_b32_e32 v188, v188, v197
	v_mov_b32_e32 v189, v187
	v_lshrrev_b32_e32 v176, 6, v181
	v_lshlrev_b32_e32 v197, 11, v176
	v_lshlrev_b32_e32 v176, 10, v176
	v_lshl_add_u64 v[188:189], v[188:189], 0, v[176:177]
	v_readfirstlane_b32 vcc_lo, v197
	v_bfe_u32 v197, v181, 4, 1
	v_lshlrev_b32_e32 v176, 9, v183
	v_lshl_add_u32 v176, v197, 8, v176
	v_lshl_add_u64 v[184:185], v[184:185], 0, v[176:177]
	v_mov_b32_e32 v176, s41
	v_lshl_add_u64 v[186:187], v[184:185], 0, v[176:177]
	v_mov_b32_e32 v176, 0x78
	v_bfe_u32 v197, v181, 2, 2
	v_lshlrev_b32_e32 v197, 1, v197
	v_lshrrev_b32_e32 v197, v197, v176
	v_and_b32_e32 v197, 3, v197
	v_bfe_u32 v196, v181, 4, 2
	v_xor_b32_e32 v197, v197, v196
	v_lshlrev_b32_e32 v197, 4, v197
	v_and_b32_e32 v196, 15, v181
	v_lshl_add_u32 v196, v196, 6, v197
	s_mov_b32 s96, 0
	s_mov_b32 m0, vcc_lo
	v_lshl_add_u64 v[160:161], v[188:189], 0, s[96:97]
	global_load_lds_dwordx4 v[160:161], off
	global_load_lds_dwordx4 v[160:161], off offset:1024
	s_mov_b32 s96, 0
	v_lshl_add_u64 v[198:199], v[184:185], 0, s[96:97]
	v_lshl_add_u64 v[200:201], v[186:187], 0, s[96:97]
	global_load_dwordx4 v[128:131], v[198:199], off
	global_load_dwordx4 v[132:135], v[198:199], off offset:256
	global_load_dwordx4 v[136:139], v[200:201], off
	global_load_dwordx4 v[140:143], v[200:201], off offset:256
	s_movk_i32 s96, 0x2000
	s_add_i32 m0, vcc_lo, 8192
	v_lshl_add_u64 v[160:161], v[188:189], 0, s[96:97]
	global_load_lds_dwordx4 v[160:161], off
	global_load_lds_dwordx4 v[160:161], off offset:1024
	s_movk_i32 s96, 0x800
	v_lshl_add_u64 v[198:199], v[184:185], 0, s[96:97]
	v_lshl_add_u64 v[200:201], v[186:187], 0, s[96:97]
	global_load_dwordx4 v[144:147], v[198:199], off
	global_load_dwordx4 v[148:151], v[198:199], off offset:256
	global_load_dwordx4 v[152:155], v[200:201], off
	global_load_dwordx4 v[156:159], v[200:201], off offset:256
	v_mov_b32_e32 v0, 0
	v_mov_b32_e32 v1, 0
	v_mov_b32_e32 v2, 0
	v_mov_b32_e32 v3, 0
	v_mov_b32_e32 v4, 0
	v_mov_b32_e32 v5, 0
	v_mov_b32_e32 v6, 0
	v_mov_b32_e32 v7, 0
	v_mov_b32_e32 v8, 0
	v_mov_b32_e32 v9, 0
	v_mov_b32_e32 v10, 0
	v_mov_b32_e32 v11, 0
	v_mov_b32_e32 v12, 0
	v_mov_b32_e32 v13, 0
	v_mov_b32_e32 v14, 0
	v_mov_b32_e32 v15, 0
	v_mov_b32_e32 v16, 0
	v_mov_b32_e32 v17, 0
	v_mov_b32_e32 v18, 0
	v_mov_b32_e32 v19, 0
	v_mov_b32_e32 v20, 0
	v_mov_b32_e32 v21, 0
	v_mov_b32_e32 v22, 0
	v_mov_b32_e32 v23, 0
	v_mov_b32_e32 v24, 0
	v_mov_b32_e32 v25, 0
	v_mov_b32_e32 v26, 0
	v_mov_b32_e32 v27, 0
	v_mov_b32_e32 v28, 0
	v_mov_b32_e32 v29, 0
	v_mov_b32_e32 v30, 0
	v_mov_b32_e32 v31, 0
	v_mov_b32_e32 v32, 0
	v_mov_b32_e32 v33, 0
	v_mov_b32_e32 v34, 0
	v_mov_b32_e32 v35, 0
	v_mov_b32_e32 v36, 0
	v_mov_b32_e32 v37, 0
	v_mov_b32_e32 v38, 0
	v_mov_b32_e32 v39, 0
	v_mov_b32_e32 v40, 0
	v_mov_b32_e32 v41, 0
	v_mov_b32_e32 v42, 0
	v_mov_b32_e32 v43, 0
	v_mov_b32_e32 v44, 0
	v_mov_b32_e32 v45, 0
	v_mov_b32_e32 v46, 0
	v_mov_b32_e32 v47, 0
	v_mov_b32_e32 v48, 0
	v_mov_b32_e32 v49, 0
	v_mov_b32_e32 v50, 0
	v_mov_b32_e32 v51, 0
	v_mov_b32_e32 v52, 0
	v_mov_b32_e32 v53, 0
	v_mov_b32_e32 v54, 0
	v_mov_b32_e32 v55, 0
	v_mov_b32_e32 v56, 0
	v_mov_b32_e32 v57, 0
	v_mov_b32_e32 v58, 0
	v_mov_b32_e32 v59, 0
	v_mov_b32_e32 v60, 0
	v_mov_b32_e32 v61, 0
	v_mov_b32_e32 v62, 0
	v_mov_b32_e32 v63, 0
	v_mov_b32_e32 v64, 0
	v_mov_b32_e32 v65, 0
	v_mov_b32_e32 v66, 0
	v_mov_b32_e32 v67, 0
	v_mov_b32_e32 v68, 0
	v_mov_b32_e32 v69, 0
	v_mov_b32_e32 v70, 0
	v_mov_b32_e32 v71, 0
	v_mov_b32_e32 v72, 0
	v_mov_b32_e32 v73, 0
	v_mov_b32_e32 v74, 0
	v_mov_b32_e32 v75, 0
	v_mov_b32_e32 v76, 0
	v_mov_b32_e32 v77, 0
	v_mov_b32_e32 v78, 0
	v_mov_b32_e32 v79, 0
	v_mov_b32_e32 v80, 0
	v_mov_b32_e32 v81, 0
	v_mov_b32_e32 v82, 0
	v_mov_b32_e32 v83, 0
	v_mov_b32_e32 v84, 0
	v_mov_b32_e32 v85, 0
	v_mov_b32_e32 v86, 0
	v_mov_b32_e32 v87, 0
	v_mov_b32_e32 v88, 0
	v_mov_b32_e32 v89, 0
	v_mov_b32_e32 v90, 0
	v_mov_b32_e32 v91, 0
	v_mov_b32_e32 v92, 0
	v_mov_b32_e32 v93, 0
	v_mov_b32_e32 v94, 0
	v_mov_b32_e32 v95, 0
	v_mov_b32_e32 v96, 0
	v_mov_b32_e32 v97, 0
	v_mov_b32_e32 v98, 0
	v_mov_b32_e32 v99, 0
	v_mov_b32_e32 v100, 0
	v_mov_b32_e32 v101, 0
	v_mov_b32_e32 v102, 0
	v_mov_b32_e32 v103, 0
	v_mov_b32_e32 v104, 0
	v_mov_b32_e32 v105, 0
	v_mov_b32_e32 v106, 0
	v_mov_b32_e32 v107, 0
	v_mov_b32_e32 v108, 0
	v_mov_b32_e32 v109, 0
	v_mov_b32_e32 v110, 0
	v_mov_b32_e32 v111, 0
	v_mov_b32_e32 v112, 0
	v_mov_b32_e32 v113, 0
	v_mov_b32_e32 v114, 0
	v_mov_b32_e32 v115, 0
	v_mov_b32_e32 v116, 0
	v_mov_b32_e32 v117, 0
	v_mov_b32_e32 v118, 0
	v_mov_b32_e32 v119, 0
	v_mov_b32_e32 v120, 0
	v_mov_b32_e32 v121, 0
	v_mov_b32_e32 v122, 0
	v_mov_b32_e32 v123, 0
	v_mov_b32_e32 v124, 0
	v_mov_b32_e32 v125, 0
	v_mov_b32_e32 v126, 0
	v_mov_b32_e32 v127, 0
	s_mov_b32 s1, 0
	s_waitcnt vmcnt(4)
	s_barrier
.Lg16_proj_k:
	s_add_i32 s3, s1, 2
	s_lshl_b32 s96, s3, 13
	s_add_i32 m0, vcc_lo, 16384
	v_lshl_add_u64 v[160:161], v[188:189], 0, s[96:97]
	global_load_lds_dwordx4 v[160:161], off
	global_load_lds_dwordx4 v[160:161], off offset:1024
	ds_read_b128 v[236:239], v196 offset:0
	ds_read_b128 v[240:243], v196 offset:1024
	ds_read_b128 v[244:247], v196 offset:2048
	ds_read_b128 v[248:251], v196 offset:3072
	s_add_i32 s3, s1, 2
	s_lshl_b32 s96, s3, 11
	v_lshl_add_u64 v[198:199], v[184:185], 0, s[96:97]
	v_lshl_add_u64 v[200:201], v[186:187], 0, s[96:97]
	s_waitcnt vmcnt(8) lgkmcnt(3)
	v_mfma_f32_16x16x32_bf16 v[16:19], v[128:131], v[236:239], v[16:19]
	v_mfma_f32_16x16x32_bf16 v[24:27], v[132:135], v[236:239], v[24:27]
	v_mfma_f32_16x16x32_bf16 v[0:3], v[136:139], v[236:239], v[0:3]
	v_mfma_f32_16x16x32_bf16 v[8:11], v[140:143], v[236:239], v[8:11]
	ds_read_b128 v[236:239], v196 offset:4096
	s_waitcnt lgkmcnt(3)
	v_mfma_f32_16x16x32_bf16 v[20:23], v[128:131], v[240:243], v[20:23]
	v_mfma_f32_16x16x32_bf16 v[28:31], v[132:135], v[240:243], v[28:31]
	v_mfma_f32_16x16x32_bf16 v[4:7], v[136:139], v[240:243], v[4:7]
	v_mfma_f32_16x16x32_bf16 v[12:15], v[140:143], v[240:243], v[12:15]
	ds_read_b128 v[240:243], v196 offset:5120
	s_waitcnt lgkmcnt(3)
	v_mfma_f32_16x16x32_bf16 v[112:115], v[128:131], v[244:247], v[112:115]
	v_mfma_f32_16x16x32_bf16 v[120:123], v[132:135], v[244:247], v[120:123]
	v_mfma_f32_16x16x32_bf16 v[96:99], v[136:139], v[244:247], v[96:99]
	v_mfma_f32_16x16x32_bf16 v[104:107], v[140:143], v[244:247], v[104:107]
	ds_read_b128 v[244:247], v196 offset:6144
	s_waitcnt lgkmcnt(3)
	v_mfma_f32_16x16x32_bf16 v[116:119], v[128:131], v[248:251], v[116:119]
	v_mfma_f32_16x16x32_bf16 v[124:127], v[132:135], v[248:251], v[124:127]
	v_mfma_f32_16x16x32_bf16 v[100:103], v[136:139], v[248:251], v[100:103]
	v_mfma_f32_16x16x32_bf16 v[108:111], v[140:143], v[248:251], v[108:111]
	ds_read_b128 v[248:251], v196 offset:7168
	s_waitcnt lgkmcnt(3)
	v_mfma_f32_16x16x32_bf16 v[80:83], v[128:131], v[236:239], v[80:83]
	v_mfma_f32_16x16x32_bf16 v[88:91], v[132:135], v[236:239], v[88:91]
	v_mfma_f32_16x16x32_bf16 v[48:51], v[136:139], v[236:239], v[48:51]
	v_mfma_f32_16x16x32_bf16 v[56:59], v[140:143], v[236:239], v[56:59]
	s_waitcnt lgkmcnt(2)
	v_mfma_f32_16x16x32_bf16 v[84:87], v[128:131], v[240:243], v[84:87]
	v_mfma_f32_16x16x32_bf16 v[92:95], v[132:135], v[240:243], v[92:95]
	v_mfma_f32_16x16x32_bf16 v[52:55], v[136:139], v[240:243], v[52:55]
	v_mfma_f32_16x16x32_bf16 v[60:63], v[140:143], v[240:243], v[60:63]
	s_waitcnt lgkmcnt(1)
	v_mfma_f32_16x16x32_bf16 v[64:67], v[128:131], v[244:247], v[64:67]
	v_mfma_f32_16x16x32_bf16 v[72:75], v[132:135], v[244:247], v[72:75]
	v_mfma_f32_16x16x32_bf16 v[32:35], v[136:139], v[244:247], v[32:35]
	v_mfma_f32_16x16x32_bf16 v[40:43], v[140:143], v[244:247], v[40:43]
	s_waitcnt lgkmcnt(0)
	v_mfma_f32_16x16x32_bf16 v[68:71], v[128:131], v[248:251], v[68:71]
	v_mfma_f32_16x16x32_bf16 v[76:79], v[132:135], v[248:251], v[76:79]
	v_mfma_f32_16x16x32_bf16 v[36:39], v[136:139], v[248:251], v[36:39]
	v_mfma_f32_16x16x32_bf16 v[44:47], v[140:143], v[248:251], v[44:47]
	global_load_dwordx4 v[128:131], v[198:199], off
	global_load_dwordx4 v[132:135], v[198:199], off offset:256
	global_load_dwordx4 v[136:139], v[200:201], off
	global_load_dwordx4 v[140:143], v[200:201], off offset:256
	s_waitcnt vmcnt(10)
	s_barrier
	s_add_i32 s3, s1, 3
	s_lshl_b32 s96, s3, 13
	s_mov_b32 m0, vcc_lo
	v_lshl_add_u64 v[160:161], v[188:189], 0, s[96:97]
	global_load_lds_dwordx4 v[160:161], off
	global_load_lds_dwordx4 v[160:161], off offset:1024
	ds_read_b128 v[236:239], v196 offset:8192
	ds_read_b128 v[240:243], v196 offset:9216
	ds_read_b128 v[244:247], v196 offset:10240
	ds_read_b128 v[248:251], v196 offset:11264
	s_add_i32 s3, s1, 3
	s_lshl_b32 s96, s3, 11
	v_lshl_add_u64 v[198:199], v[184:185], 0, s[96:97]
	v_lshl_add_u64 v[200:201], v[186:187], 0, s[96:97]
	s_waitcnt vmcnt(8) lgkmcnt(3)
	v_mfma_f32_16x16x32_bf16 v[16:19], v[144:147], v[236:239], v[16:19]
	v_mfma_f32_16x16x32_bf16 v[24:27], v[148:151], v[236:239], v[24:27]
	v_mfma_f32_16x16x32_bf16 v[0:3], v[152:155], v[236:239], v[0:3]
	v_mfma_f32_16x16x32_bf16 v[8:11], v[156:159], v[236:239], v[8:11]
	ds_read_b128 v[236:239], v196 offset:12288
	s_waitcnt lgkmcnt(3)
	v_mfma_f32_16x16x32_bf16 v[20:23], v[144:147], v[240:243], v[20:23]
	v_mfma_f32_16x16x32_bf16 v[28:31], v[148:151], v[240:243], v[28:31]
	v_mfma_f32_16x16x32_bf16 v[4:7], v[152:155], v[240:243], v[4:7]
	v_mfma_f32_16x16x32_bf16 v[12:15], v[156:159], v[240:243], v[12:15]
	ds_read_b128 v[240:243], v196 offset:13312
	s_waitcnt lgkmcnt(3)
	v_mfma_f32_16x16x32_bf16 v[112:115], v[144:147], v[244:247], v[112:115]
	v_mfma_f32_16x16x32_bf16 v[120:123], v[148:151], v[244:247], v[120:123]
	v_mfma_f32_16x16x32_bf16 v[96:99], v[152:155], v[244:247], v[96:99]
	v_mfma_f32_16x16x32_bf16 v[104:107], v[156:159], v[244:247], v[104:107]
	ds_read_b128 v[244:247], v196 offset:14336
	s_waitcnt lgkmcnt(3)
	v_mfma_f32_16x16x32_bf16 v[116:119], v[144:147], v[248:251], v[116:119]
	v_mfma_f32_16x16x32_bf16 v[124:127], v[148:151], v[248:251], v[124:127]
	v_mfma_f32_16x16x32_bf16 v[100:103], v[152:155], v[248:251], v[100:103]
	v_mfma_f32_16x16x32_bf16 v[108:111], v[156:159], v[248:251], v[108:111]
	ds_read_b128 v[248:251], v196 offset:15360
	s_waitcnt lgkmcnt(3)
	v_mfma_f32_16x16x32_bf16 v[80:83], v[144:147], v[236:239], v[80:83]
	v_mfma_f32_16x16x32_bf16 v[88:91], v[148:151], v[236:239], v[88:91]
	v_mfma_f32_16x16x32_bf16 v[48:51], v[152:155], v[236:239], v[48:51]
	v_mfma_f32_16x16x32_bf16 v[56:59], v[156:159], v[236:239], v[56:59]
	s_waitcnt lgkmcnt(2)
	v_mfma_f32_16x16x32_bf16 v[84:87], v[144:147], v[240:243], v[84:87]
	v_mfma_f32_16x16x32_bf16 v[92:95], v[148:151], v[240:243], v[92:95]
	v_mfma_f32_16x16x32_bf16 v[52:55], v[152:155], v[240:243], v[52:55]
	v_mfma_f32_16x16x32_bf16 v[60:63], v[156:159], v[240:243], v[60:63]
	s_waitcnt lgkmcnt(1)
	v_mfma_f32_16x16x32_bf16 v[64:67], v[144:147], v[244:247], v[64:67]
	v_mfma_f32_16x16x32_bf16 v[72:75], v[148:151], v[244:247], v[72:75]
	v_mfma_f32_16x16x32_bf16 v[32:35], v[152:155], v[244:247], v[32:35]
	v_mfma_f32_16x16x32_bf16 v[40:43], v[156:159], v[244:247], v[40:43]
	s_waitcnt lgkmcnt(0)
	v_mfma_f32_16x16x32_bf16 v[68:71], v[144:147], v[248:251], v[68:71]
	v_mfma_f32_16x16x32_bf16 v[76:79], v[148:151], v[248:251], v[76:79]
	v_mfma_f32_16x16x32_bf16 v[36:39], v[152:155], v[248:251], v[36:39]
	v_mfma_f32_16x16x32_bf16 v[44:47], v[156:159], v[248:251], v[44:47]
	global_load_dwordx4 v[144:147], v[198:199], off
	global_load_dwordx4 v[148:151], v[198:199], off offset:256
	global_load_dwordx4 v[152:155], v[200:201], off
	global_load_dwordx4 v[156:159], v[200:201], off offset:256
	s_waitcnt vmcnt(10)
	s_barrier
	s_add_i32 s3, s1, 4
	s_lshl_b32 s96, s3, 13
	s_add_i32 m0, vcc_lo, 8192
	v_lshl_add_u64 v[160:161], v[188:189], 0, s[96:97]
	global_load_lds_dwordx4 v[160:161], off
	global_load_lds_dwordx4 v[160:161], off offset:1024
	ds_read_b128 v[236:239], v196 offset:16384
	ds_read_b128 v[240:243], v196 offset:17408
	ds_read_b128 v[244:247], v196 offset:18432
	ds_read_b128 v[248:251], v196 offset:19456
	s_add_i32 s3, s1, 4
	s_lshl_b32 s96, s3, 11
	v_lshl_add_u64 v[198:199], v[184:185], 0, s[96:97]
	v_lshl_add_u64 v[200:201], v[186:187], 0, s[96:97]
	s_waitcnt vmcnt(8) lgkmcnt(3)
	v_mfma_f32_16x16x32_bf16 v[16:19], v[128:131], v[236:239], v[16:19]
	v_mfma_f32_16x16x32_bf16 v[24:27], v[132:135], v[236:239], v[24:27]
	v_mfma_f32_16x16x32_bf16 v[0:3], v[136:139], v[236:239], v[0:3]
	v_mfma_f32_16x16x32_bf16 v[8:11], v[140:143], v[236:239], v[8:11]
	ds_read_b128 v[236:239], v196 offset:20480
	s_waitcnt lgkmcnt(3)
	v_mfma_f32_16x16x32_bf16 v[20:23], v[128:131], v[240:243], v[20:23]
	v_mfma_f32_16x16x32_bf16 v[28:31], v[132:135], v[240:243], v[28:31]
	v_mfma_f32_16x16x32_bf16 v[4:7], v[136:139], v[240:243], v[4:7]
	v_mfma_f32_16x16x32_bf16 v[12:15], v[140:143], v[240:243], v[12:15]
	ds_read_b128 v[240:243], v196 offset:21504
	s_waitcnt lgkmcnt(3)
	v_mfma_f32_16x16x32_bf16 v[112:115], v[128:131], v[244:247], v[112:115]
	v_mfma_f32_16x16x32_bf16 v[120:123], v[132:135], v[244:247], v[120:123]
	v_mfma_f32_16x16x32_bf16 v[96:99], v[136:139], v[244:247], v[96:99]
	v_mfma_f32_16x16x32_bf16 v[104:107], v[140:143], v[244:247], v[104:107]
	ds_read_b128 v[244:247], v196 offset:22528
	s_waitcnt lgkmcnt(3)
	v_mfma_f32_16x16x32_bf16 v[116:119], v[128:131], v[248:251], v[116:119]
	v_mfma_f32_16x16x32_bf16 v[124:127], v[132:135], v[248:251], v[124:127]
	v_mfma_f32_16x16x32_bf16 v[100:103], v[136:139], v[248:251], v[100:103]
	v_mfma_f32_16x16x32_bf16 v[108:111], v[140:143], v[248:251], v[108:111]
	ds_read_b128 v[248:251], v196 offset:23552
	s_waitcnt lgkmcnt(3)
	v_mfma_f32_16x16x32_bf16 v[80:83], v[128:131], v[236:239], v[80:83]
	v_mfma_f32_16x16x32_bf16 v[88:91], v[132:135], v[236:239], v[88:91]
	v_mfma_f32_16x16x32_bf16 v[48:51], v[136:139], v[236:239], v[48:51]
	v_mfma_f32_16x16x32_bf16 v[56:59], v[140:143], v[236:239], v[56:59]
	s_waitcnt lgkmcnt(2)
	v_mfma_f32_16x16x32_bf16 v[84:87], v[128:131], v[240:243], v[84:87]
	v_mfma_f32_16x16x32_bf16 v[92:95], v[132:135], v[240:243], v[92:95]
	v_mfma_f32_16x16x32_bf16 v[52:55], v[136:139], v[240:243], v[52:55]
	v_mfma_f32_16x16x32_bf16 v[60:63], v[140:143], v[240:243], v[60:63]
	s_waitcnt lgkmcnt(1)
	v_mfma_f32_16x16x32_bf16 v[64:67], v[128:131], v[244:247], v[64:67]
	v_mfma_f32_16x16x32_bf16 v[72:75], v[132:135], v[244:247], v[72:75]
	v_mfma_f32_16x16x32_bf16 v[32:35], v[136:139], v[244:247], v[32:35]
	v_mfma_f32_16x16x32_bf16 v[40:43], v[140:143], v[244:247], v[40:43]
	s_waitcnt lgkmcnt(0)
	v_mfma_f32_16x16x32_bf16 v[68:71], v[128:131], v[248:251], v[68:71]
	v_mfma_f32_16x16x32_bf16 v[76:79], v[132:135], v[248:251], v[76:79]
	v_mfma_f32_16x16x32_bf16 v[36:39], v[136:139], v[248:251], v[36:39]
	v_mfma_f32_16x16x32_bf16 v[44:47], v[140:143], v[248:251], v[44:47]
	global_load_dwordx4 v[128:131], v[198:199], off
	global_load_dwordx4 v[132:135], v[198:199], off offset:256
	global_load_dwordx4 v[136:139], v[200:201], off
	global_load_dwordx4 v[140:143], v[200:201], off offset:256
	s_waitcnt vmcnt(10)
	s_barrier
	s_add_i32 s3, s1, 5
	s_lshl_b32 s96, s3, 13
	s_add_i32 m0, vcc_lo, 16384
	v_lshl_add_u64 v[160:161], v[188:189], 0, s[96:97]
	global_load_lds_dwordx4 v[160:161], off
	global_load_lds_dwordx4 v[160:161], off offset:1024
	ds_read_b128 v[236:239], v196 offset:0
	ds_read_b128 v[240:243], v196 offset:1024
	ds_read_b128 v[244:247], v196 offset:2048
	ds_read_b128 v[248:251], v196 offset:3072
	s_add_i32 s3, s1, 5
	s_lshl_b32 s96, s3, 11
	v_lshl_add_u64 v[198:199], v[184:185], 0, s[96:97]
	v_lshl_add_u64 v[200:201], v[186:187], 0, s[96:97]
	s_waitcnt vmcnt(8) lgkmcnt(3)
	v_mfma_f32_16x16x32_bf16 v[16:19], v[144:147], v[236:239], v[16:19]
	v_mfma_f32_16x16x32_bf16 v[24:27], v[148:151], v[236:239], v[24:27]
	v_mfma_f32_16x16x32_bf16 v[0:3], v[152:155], v[236:239], v[0:3]
	v_mfma_f32_16x16x32_bf16 v[8:11], v[156:159], v[236:239], v[8:11]
	ds_read_b128 v[236:239], v196 offset:4096
	s_waitcnt lgkmcnt(3)
	v_mfma_f32_16x16x32_bf16 v[20:23], v[144:147], v[240:243], v[20:23]
	v_mfma_f32_16x16x32_bf16 v[28:31], v[148:151], v[240:243], v[28:31]
	v_mfma_f32_16x16x32_bf16 v[4:7], v[152:155], v[240:243], v[4:7]
	v_mfma_f32_16x16x32_bf16 v[12:15], v[156:159], v[240:243], v[12:15]
	ds_read_b128 v[240:243], v196 offset:5120
	s_waitcnt lgkmcnt(3)
	v_mfma_f32_16x16x32_bf16 v[112:115], v[144:147], v[244:247], v[112:115]
	v_mfma_f32_16x16x32_bf16 v[120:123], v[148:151], v[244:247], v[120:123]
	v_mfma_f32_16x16x32_bf16 v[96:99], v[152:155], v[244:247], v[96:99]
	v_mfma_f32_16x16x32_bf16 v[104:107], v[156:159], v[244:247], v[104:107]
	ds_read_b128 v[244:247], v196 offset:6144
	s_waitcnt lgkmcnt(3)
	v_mfma_f32_16x16x32_bf16 v[116:119], v[144:147], v[248:251], v[116:119]
	v_mfma_f32_16x16x32_bf16 v[124:127], v[148:151], v[248:251], v[124:127]
	v_mfma_f32_16x16x32_bf16 v[100:103], v[152:155], v[248:251], v[100:103]
	v_mfma_f32_16x16x32_bf16 v[108:111], v[156:159], v[248:251], v[108:111]
	ds_read_b128 v[248:251], v196 offset:7168
	s_waitcnt lgkmcnt(3)
	v_mfma_f32_16x16x32_bf16 v[80:83], v[144:147], v[236:239], v[80:83]
	v_mfma_f32_16x16x32_bf16 v[88:91], v[148:151], v[236:239], v[88:91]
	v_mfma_f32_16x16x32_bf16 v[48:51], v[152:155], v[236:239], v[48:51]
	v_mfma_f32_16x16x32_bf16 v[56:59], v[156:159], v[236:239], v[56:59]
	s_waitcnt lgkmcnt(2)
	v_mfma_f32_16x16x32_bf16 v[84:87], v[144:147], v[240:243], v[84:87]
	v_mfma_f32_16x16x32_bf16 v[92:95], v[148:151], v[240:243], v[92:95]
	v_mfma_f32_16x16x32_bf16 v[52:55], v[152:155], v[240:243], v[52:55]
	v_mfma_f32_16x16x32_bf16 v[60:63], v[156:159], v[240:243], v[60:63]
	s_waitcnt lgkmcnt(1)
	v_mfma_f32_16x16x32_bf16 v[64:67], v[144:147], v[244:247], v[64:67]
	v_mfma_f32_16x16x32_bf16 v[72:75], v[148:151], v[244:247], v[72:75]
	v_mfma_f32_16x16x32_bf16 v[32:35], v[152:155], v[244:247], v[32:35]
	v_mfma_f32_16x16x32_bf16 v[40:43], v[156:159], v[244:247], v[40:43]
	s_waitcnt lgkmcnt(0)
	v_mfma_f32_16x16x32_bf16 v[68:71], v[144:147], v[248:251], v[68:71]
	v_mfma_f32_16x16x32_bf16 v[76:79], v[148:151], v[248:251], v[76:79]
	v_mfma_f32_16x16x32_bf16 v[36:39], v[152:155], v[248:251], v[36:39]
	v_mfma_f32_16x16x32_bf16 v[44:47], v[156:159], v[248:251], v[44:47]
	global_load_dwordx4 v[144:147], v[198:199], off
	global_load_dwordx4 v[148:151], v[198:199], off offset:256
	global_load_dwordx4 v[152:155], v[200:201], off
	global_load_dwordx4 v[156:159], v[200:201], off offset:256
	s_waitcnt vmcnt(10)
	s_barrier
	s_add_i32 s3, s1, 6
	s_lshl_b32 s96, s3, 13
	s_mov_b32 m0, vcc_lo
	v_lshl_add_u64 v[160:161], v[188:189], 0, s[96:97]
	global_load_lds_dwordx4 v[160:161], off
	global_load_lds_dwordx4 v[160:161], off offset:1024
	ds_read_b128 v[236:239], v196 offset:8192
	ds_read_b128 v[240:243], v196 offset:9216
	ds_read_b128 v[244:247], v196 offset:10240
	ds_read_b128 v[248:251], v196 offset:11264
	s_add_i32 s3, s1, 6
	s_lshl_b32 s96, s3, 11
	v_lshl_add_u64 v[198:199], v[184:185], 0, s[96:97]
	v_lshl_add_u64 v[200:201], v[186:187], 0, s[96:97]
	s_waitcnt vmcnt(8) lgkmcnt(3)
	v_mfma_f32_16x16x32_bf16 v[16:19], v[128:131], v[236:239], v[16:19]
	v_mfma_f32_16x16x32_bf16 v[24:27], v[132:135], v[236:239], v[24:27]
	v_mfma_f32_16x16x32_bf16 v[0:3], v[136:139], v[236:239], v[0:3]
	v_mfma_f32_16x16x32_bf16 v[8:11], v[140:143], v[236:239], v[8:11]
	ds_read_b128 v[236:239], v196 offset:12288
	s_waitcnt lgkmcnt(3)
	v_mfma_f32_16x16x32_bf16 v[20:23], v[128:131], v[240:243], v[20:23]
	v_mfma_f32_16x16x32_bf16 v[28:31], v[132:135], v[240:243], v[28:31]
	v_mfma_f32_16x16x32_bf16 v[4:7], v[136:139], v[240:243], v[4:7]
	v_mfma_f32_16x16x32_bf16 v[12:15], v[140:143], v[240:243], v[12:15]
	ds_read_b128 v[240:243], v196 offset:13312
	s_waitcnt lgkmcnt(3)
	v_mfma_f32_16x16x32_bf16 v[112:115], v[128:131], v[244:247], v[112:115]
	v_mfma_f32_16x16x32_bf16 v[120:123], v[132:135], v[244:247], v[120:123]
	v_mfma_f32_16x16x32_bf16 v[96:99], v[136:139], v[244:247], v[96:99]
	v_mfma_f32_16x16x32_bf16 v[104:107], v[140:143], v[244:247], v[104:107]
	ds_read_b128 v[244:247], v196 offset:14336
	s_waitcnt lgkmcnt(3)
	v_mfma_f32_16x16x32_bf16 v[116:119], v[128:131], v[248:251], v[116:119]
	v_mfma_f32_16x16x32_bf16 v[124:127], v[132:135], v[248:251], v[124:127]
	v_mfma_f32_16x16x32_bf16 v[100:103], v[136:139], v[248:251], v[100:103]
	v_mfma_f32_16x16x32_bf16 v[108:111], v[140:143], v[248:251], v[108:111]
	ds_read_b128 v[248:251], v196 offset:15360
	s_waitcnt lgkmcnt(3)
	v_mfma_f32_16x16x32_bf16 v[80:83], v[128:131], v[236:239], v[80:83]
	v_mfma_f32_16x16x32_bf16 v[88:91], v[132:135], v[236:239], v[88:91]
	v_mfma_f32_16x16x32_bf16 v[48:51], v[136:139], v[236:239], v[48:51]
	v_mfma_f32_16x16x32_bf16 v[56:59], v[140:143], v[236:239], v[56:59]
	s_waitcnt lgkmcnt(2)
	v_mfma_f32_16x16x32_bf16 v[84:87], v[128:131], v[240:243], v[84:87]
	v_mfma_f32_16x16x32_bf16 v[92:95], v[132:135], v[240:243], v[92:95]
	v_mfma_f32_16x16x32_bf16 v[52:55], v[136:139], v[240:243], v[52:55]
	v_mfma_f32_16x16x32_bf16 v[60:63], v[140:143], v[240:243], v[60:63]
	s_waitcnt lgkmcnt(1)
	v_mfma_f32_16x16x32_bf16 v[64:67], v[128:131], v[244:247], v[64:67]
	v_mfma_f32_16x16x32_bf16 v[72:75], v[132:135], v[244:247], v[72:75]
	v_mfma_f32_16x16x32_bf16 v[32:35], v[136:139], v[244:247], v[32:35]
	v_mfma_f32_16x16x32_bf16 v[40:43], v[140:143], v[244:247], v[40:43]
	s_waitcnt lgkmcnt(0)
	v_mfma_f32_16x16x32_bf16 v[68:71], v[128:131], v[248:251], v[68:71]
	v_mfma_f32_16x16x32_bf16 v[76:79], v[132:135], v[248:251], v[76:79]
	v_mfma_f32_16x16x32_bf16 v[36:39], v[136:139], v[248:251], v[36:39]
	v_mfma_f32_16x16x32_bf16 v[44:47], v[140:143], v[248:251], v[44:47]
	global_load_dwordx4 v[128:131], v[198:199], off
	global_load_dwordx4 v[132:135], v[198:199], off offset:256
	global_load_dwordx4 v[136:139], v[200:201], off
	global_load_dwordx4 v[140:143], v[200:201], off offset:256
	s_waitcnt vmcnt(10)
	s_barrier
	s_add_i32 s3, s1, 7
	s_lshl_b32 s96, s3, 13
	s_add_i32 m0, vcc_lo, 8192
	v_lshl_add_u64 v[160:161], v[188:189], 0, s[96:97]
	global_load_lds_dwordx4 v[160:161], off
	global_load_lds_dwordx4 v[160:161], off offset:1024
	ds_read_b128 v[236:239], v196 offset:16384
	ds_read_b128 v[240:243], v196 offset:17408
	ds_read_b128 v[244:247], v196 offset:18432
	ds_read_b128 v[248:251], v196 offset:19456
	s_add_i32 s3, s1, 7
	s_lshl_b32 s96, s3, 11
	v_lshl_add_u64 v[198:199], v[184:185], 0, s[96:97]
	v_lshl_add_u64 v[200:201], v[186:187], 0, s[96:97]
	s_waitcnt vmcnt(8) lgkmcnt(3)
	v_mfma_f32_16x16x32_bf16 v[16:19], v[144:147], v[236:239], v[16:19]
	v_mfma_f32_16x16x32_bf16 v[24:27], v[148:151], v[236:239], v[24:27]
	v_mfma_f32_16x16x32_bf16 v[0:3], v[152:155], v[236:239], v[0:3]
	v_mfma_f32_16x16x32_bf16 v[8:11], v[156:159], v[236:239], v[8:11]
	ds_read_b128 v[236:239], v196 offset:20480
	s_waitcnt lgkmcnt(3)
	v_mfma_f32_16x16x32_bf16 v[20:23], v[144:147], v[240:243], v[20:23]
	v_mfma_f32_16x16x32_bf16 v[28:31], v[148:151], v[240:243], v[28:31]
	v_mfma_f32_16x16x32_bf16 v[4:7], v[152:155], v[240:243], v[4:7]
	v_mfma_f32_16x16x32_bf16 v[12:15], v[156:159], v[240:243], v[12:15]
	ds_read_b128 v[240:243], v196 offset:21504
	s_waitcnt lgkmcnt(3)
	v_mfma_f32_16x16x32_bf16 v[112:115], v[144:147], v[244:247], v[112:115]
	v_mfma_f32_16x16x32_bf16 v[120:123], v[148:151], v[244:247], v[120:123]
	v_mfma_f32_16x16x32_bf16 v[96:99], v[152:155], v[244:247], v[96:99]
	v_mfma_f32_16x16x32_bf16 v[104:107], v[156:159], v[244:247], v[104:107]
	ds_read_b128 v[244:247], v196 offset:22528
	s_waitcnt lgkmcnt(3)
	v_mfma_f32_16x16x32_bf16 v[116:119], v[144:147], v[248:251], v[116:119]
	v_mfma_f32_16x16x32_bf16 v[124:127], v[148:151], v[248:251], v[124:127]
	v_mfma_f32_16x16x32_bf16 v[100:103], v[152:155], v[248:251], v[100:103]
	v_mfma_f32_16x16x32_bf16 v[108:111], v[156:159], v[248:251], v[108:111]
	ds_read_b128 v[248:251], v196 offset:23552
	s_waitcnt lgkmcnt(3)
	v_mfma_f32_16x16x32_bf16 v[80:83], v[144:147], v[236:239], v[80:83]
	v_mfma_f32_16x16x32_bf16 v[88:91], v[148:151], v[236:239], v[88:91]
	v_mfma_f32_16x16x32_bf16 v[48:51], v[152:155], v[236:239], v[48:51]
	v_mfma_f32_16x16x32_bf16 v[56:59], v[156:159], v[236:239], v[56:59]
	s_waitcnt lgkmcnt(2)
	v_mfma_f32_16x16x32_bf16 v[84:87], v[144:147], v[240:243], v[84:87]
	v_mfma_f32_16x16x32_bf16 v[92:95], v[148:151], v[240:243], v[92:95]
	v_mfma_f32_16x16x32_bf16 v[52:55], v[152:155], v[240:243], v[52:55]
	v_mfma_f32_16x16x32_bf16 v[60:63], v[156:159], v[240:243], v[60:63]
	s_waitcnt lgkmcnt(1)
	v_mfma_f32_16x16x32_bf16 v[64:67], v[144:147], v[244:247], v[64:67]
	v_mfma_f32_16x16x32_bf16 v[72:75], v[148:151], v[244:247], v[72:75]
	v_mfma_f32_16x16x32_bf16 v[32:35], v[152:155], v[244:247], v[32:35]
	v_mfma_f32_16x16x32_bf16 v[40:43], v[156:159], v[244:247], v[40:43]
	s_waitcnt lgkmcnt(0)
	v_mfma_f32_16x16x32_bf16 v[68:71], v[144:147], v[248:251], v[68:71]
	v_mfma_f32_16x16x32_bf16 v[76:79], v[148:151], v[248:251], v[76:79]
	v_mfma_f32_16x16x32_bf16 v[36:39], v[152:155], v[248:251], v[36:39]
	v_mfma_f32_16x16x32_bf16 v[44:47], v[156:159], v[248:251], v[44:47]
	global_load_dwordx4 v[144:147], v[198:199], off
	global_load_dwordx4 v[148:151], v[198:199], off offset:256
	global_load_dwordx4 v[152:155], v[200:201], off
	global_load_dwordx4 v[156:159], v[200:201], off offset:256
	s_waitcnt vmcnt(10)
	s_barrier
	s_add_i32 s1, s1, 6
	s_cmp_lt_u32 s1, 30
	s_cbranch_scc1 .Lg16_proj_k
	ds_read_b128 v[236:239], v196 offset:0
	ds_read_b128 v[240:243], v196 offset:1024
	ds_read_b128 v[244:247], v196 offset:2048
	ds_read_b128 v[248:251], v196 offset:3072
	s_waitcnt vmcnt(6) lgkmcnt(3)
	v_mfma_f32_16x16x32_bf16 v[16:19], v[128:131], v[236:239], v[16:19]
	v_mfma_f32_16x16x32_bf16 v[24:27], v[132:135], v[236:239], v[24:27]
	v_mfma_f32_16x16x32_bf16 v[0:3], v[136:139], v[236:239], v[0:3]
	v_mfma_f32_16x16x32_bf16 v[8:11], v[140:143], v[236:239], v[8:11]
	ds_read_b128 v[236:239], v196 offset:4096
	s_waitcnt lgkmcnt(3)
	v_mfma_f32_16x16x32_bf16 v[20:23], v[128:131], v[240:243], v[20:23]
	v_mfma_f32_16x16x32_bf16 v[28:31], v[132:135], v[240:243], v[28:31]
	v_mfma_f32_16x16x32_bf16 v[4:7], v[136:139], v[240:243], v[4:7]
	v_mfma_f32_16x16x32_bf16 v[12:15], v[140:143], v[240:243], v[12:15]
	ds_read_b128 v[240:243], v196 offset:5120
	s_waitcnt lgkmcnt(3)
	v_mfma_f32_16x16x32_bf16 v[112:115], v[128:131], v[244:247], v[112:115]
	v_mfma_f32_16x16x32_bf16 v[120:123], v[132:135], v[244:247], v[120:123]
	v_mfma_f32_16x16x32_bf16 v[96:99], v[136:139], v[244:247], v[96:99]
	v_mfma_f32_16x16x32_bf16 v[104:107], v[140:143], v[244:247], v[104:107]
	ds_read_b128 v[244:247], v196 offset:6144
	s_waitcnt lgkmcnt(3)
	v_mfma_f32_16x16x32_bf16 v[116:119], v[128:131], v[248:251], v[116:119]
	v_mfma_f32_16x16x32_bf16 v[124:127], v[132:135], v[248:251], v[124:127]
	v_mfma_f32_16x16x32_bf16 v[100:103], v[136:139], v[248:251], v[100:103]
	v_mfma_f32_16x16x32_bf16 v[108:111], v[140:143], v[248:251], v[108:111]
	ds_read_b128 v[248:251], v196 offset:7168
	s_waitcnt lgkmcnt(3)
	v_mfma_f32_16x16x32_bf16 v[80:83], v[128:131], v[236:239], v[80:83]
	v_mfma_f32_16x16x32_bf16 v[88:91], v[132:135], v[236:239], v[88:91]
	v_mfma_f32_16x16x32_bf16 v[48:51], v[136:139], v[236:239], v[48:51]
	v_mfma_f32_16x16x32_bf16 v[56:59], v[140:143], v[236:239], v[56:59]
	s_waitcnt lgkmcnt(2)
	v_mfma_f32_16x16x32_bf16 v[84:87], v[128:131], v[240:243], v[84:87]
	v_mfma_f32_16x16x32_bf16 v[92:95], v[132:135], v[240:243], v[92:95]
	v_mfma_f32_16x16x32_bf16 v[52:55], v[136:139], v[240:243], v[52:55]
	v_mfma_f32_16x16x32_bf16 v[60:63], v[140:143], v[240:243], v[60:63]
	s_waitcnt lgkmcnt(1)
	v_mfma_f32_16x16x32_bf16 v[64:67], v[128:131], v[244:247], v[64:67]
	v_mfma_f32_16x16x32_bf16 v[72:75], v[132:135], v[244:247], v[72:75]
	v_mfma_f32_16x16x32_bf16 v[32:35], v[136:139], v[244:247], v[32:35]
	v_mfma_f32_16x16x32_bf16 v[40:43], v[140:143], v[244:247], v[40:43]
	s_waitcnt lgkmcnt(0)
	v_mfma_f32_16x16x32_bf16 v[68:71], v[128:131], v[248:251], v[68:71]
	v_mfma_f32_16x16x32_bf16 v[76:79], v[132:135], v[248:251], v[76:79]
	v_mfma_f32_16x16x32_bf16 v[36:39], v[136:139], v[248:251], v[36:39]
	v_mfma_f32_16x16x32_bf16 v[44:47], v[140:143], v[248:251], v[44:47]
	s_waitcnt vmcnt(4)
	s_barrier
	ds_read_b128 v[236:239], v196 offset:8192
	ds_read_b128 v[240:243], v196 offset:9216
	ds_read_b128 v[244:247], v196 offset:10240
	ds_read_b128 v[248:251], v196 offset:11264
	s_waitcnt vmcnt(0) lgkmcnt(3)
	v_mfma_f32_16x16x32_bf16 v[16:19], v[144:147], v[236:239], v[16:19]
	v_mfma_f32_16x16x32_bf16 v[24:27], v[148:151], v[236:239], v[24:27]
	v_mfma_f32_16x16x32_bf16 v[0:3], v[152:155], v[236:239], v[0:3]
	v_mfma_f32_16x16x32_bf16 v[8:11], v[156:159], v[236:239], v[8:11]
	ds_read_b128 v[236:239], v196 offset:12288
	s_waitcnt lgkmcnt(3)
	v_mfma_f32_16x16x32_bf16 v[20:23], v[144:147], v[240:243], v[20:23]
	v_mfma_f32_16x16x32_bf16 v[28:31], v[148:151], v[240:243], v[28:31]
	v_mfma_f32_16x16x32_bf16 v[4:7], v[152:155], v[240:243], v[4:7]
	v_mfma_f32_16x16x32_bf16 v[12:15], v[156:159], v[240:243], v[12:15]
	ds_read_b128 v[240:243], v196 offset:13312
	s_waitcnt lgkmcnt(3)
	v_mfma_f32_16x16x32_bf16 v[112:115], v[144:147], v[244:247], v[112:115]
	v_mfma_f32_16x16x32_bf16 v[120:123], v[148:151], v[244:247], v[120:123]
	v_mfma_f32_16x16x32_bf16 v[96:99], v[152:155], v[244:247], v[96:99]
	v_mfma_f32_16x16x32_bf16 v[104:107], v[156:159], v[244:247], v[104:107]
	ds_read_b128 v[244:247], v196 offset:14336
	s_waitcnt lgkmcnt(3)
	v_mfma_f32_16x16x32_bf16 v[116:119], v[144:147], v[248:251], v[116:119]
	v_mfma_f32_16x16x32_bf16 v[124:127], v[148:151], v[248:251], v[124:127]
	v_mfma_f32_16x16x32_bf16 v[100:103], v[152:155], v[248:251], v[100:103]
	v_mfma_f32_16x16x32_bf16 v[108:111], v[156:159], v[248:251], v[108:111]
	ds_read_b128 v[248:251], v196 offset:15360
	s_waitcnt lgkmcnt(3)
	v_mfma_f32_16x16x32_bf16 v[80:83], v[144:147], v[236:239], v[80:83]
	v_mfma_f32_16x16x32_bf16 v[88:91], v[148:151], v[236:239], v[88:91]
	v_mfma_f32_16x16x32_bf16 v[48:51], v[152:155], v[236:239], v[48:51]
	v_mfma_f32_16x16x32_bf16 v[56:59], v[156:159], v[236:239], v[56:59]
	s_waitcnt lgkmcnt(2)
	v_mfma_f32_16x16x32_bf16 v[84:87], v[144:147], v[240:243], v[84:87]
	v_mfma_f32_16x16x32_bf16 v[92:95], v[148:151], v[240:243], v[92:95]
	v_mfma_f32_16x16x32_bf16 v[52:55], v[152:155], v[240:243], v[52:55]
	v_mfma_f32_16x16x32_bf16 v[60:63], v[156:159], v[240:243], v[60:63]
	s_waitcnt lgkmcnt(1)
	v_mfma_f32_16x16x32_bf16 v[64:67], v[144:147], v[244:247], v[64:67]
	v_mfma_f32_16x16x32_bf16 v[72:75], v[148:151], v[244:247], v[72:75]
	v_mfma_f32_16x16x32_bf16 v[32:35], v[152:155], v[244:247], v[32:35]
	v_mfma_f32_16x16x32_bf16 v[40:43], v[156:159], v[244:247], v[40:43]
	s_waitcnt lgkmcnt(0)
	v_mfma_f32_16x16x32_bf16 v[68:71], v[144:147], v[248:251], v[68:71]
	v_mfma_f32_16x16x32_bf16 v[76:79], v[148:151], v[248:251], v[76:79]
	v_mfma_f32_16x16x32_bf16 v[36:39], v[152:155], v[248:251], v[36:39]
	v_mfma_f32_16x16x32_bf16 v[44:47], v[156:159], v[248:251], v[44:47]
	s_barrier
	s_nop 7
	v_permlane16_swap_b32_e32 v16, v20
	v_permlane16_swap_b32_e32 v17, v21
	v_permlane16_swap_b32_e32 v18, v22
	v_permlane16_swap_b32_e32 v19, v23
	v_permlane16_swap_b32_e32 v24, v28
	v_permlane16_swap_b32_e32 v25, v29
	v_permlane16_swap_b32_e32 v26, v30
	v_permlane16_swap_b32_e32 v27, v31
	v_permlane16_swap_b32_e32 v112, v116
	v_permlane16_swap_b32_e32 v113, v117
	v_permlane16_swap_b32_e32 v114, v118
	v_permlane16_swap_b32_e32 v115, v119
	v_permlane16_swap_b32_e32 v120, v124
	v_permlane16_swap_b32_e32 v121, v125
	v_permlane16_swap_b32_e32 v122, v126
	v_permlane16_swap_b32_e32 v123, v127
	v_permlane16_swap_b32_e32 v80, v84
	v_permlane16_swap_b32_e32 v81, v85
	v_permlane16_swap_b32_e32 v82, v86
	v_permlane16_swap_b32_e32 v83, v87
	v_permlane16_swap_b32_e32 v88, v92
	v_permlane16_swap_b32_e32 v89, v93
	v_permlane16_swap_b32_e32 v90, v94
	v_permlane16_swap_b32_e32 v91, v95
	v_permlane16_swap_b32_e32 v64, v68
	v_permlane16_swap_b32_e32 v65, v69
	v_permlane16_swap_b32_e32 v66, v70
	v_permlane16_swap_b32_e32 v67, v71
	v_permlane16_swap_b32_e32 v72, v76
	v_permlane16_swap_b32_e32 v73, v77
	v_permlane16_swap_b32_e32 v74, v78
	v_permlane16_swap_b32_e32 v75, v79
	v_permlane16_swap_b32_e32 v0, v4
	v_permlane16_swap_b32_e32 v1, v5
	v_permlane16_swap_b32_e32 v2, v6
	v_permlane16_swap_b32_e32 v3, v7
	v_permlane16_swap_b32_e32 v8, v12
	v_permlane16_swap_b32_e32 v9, v13
	v_permlane16_swap_b32_e32 v10, v14
	v_permlane16_swap_b32_e32 v11, v15
	v_permlane16_swap_b32_e32 v96, v100
	v_permlane16_swap_b32_e32 v97, v101
	v_permlane16_swap_b32_e32 v98, v102
	v_permlane16_swap_b32_e32 v99, v103
	v_permlane16_swap_b32_e32 v104, v108
	v_permlane16_swap_b32_e32 v105, v109
	v_permlane16_swap_b32_e32 v106, v110
	v_permlane16_swap_b32_e32 v107, v111
	v_permlane16_swap_b32_e32 v48, v52
	v_permlane16_swap_b32_e32 v49, v53
	v_permlane16_swap_b32_e32 v50, v54
	v_permlane16_swap_b32_e32 v51, v55
	v_permlane16_swap_b32_e32 v56, v60
	v_permlane16_swap_b32_e32 v57, v61
	v_permlane16_swap_b32_e32 v58, v62
	v_permlane16_swap_b32_e32 v59, v63
	v_permlane16_swap_b32_e32 v32, v36
	v_permlane16_swap_b32_e32 v33, v37
	v_permlane16_swap_b32_e32 v34, v38
	v_permlane16_swap_b32_e32 v35, v39
	v_permlane16_swap_b32_e32 v40, v44
	v_permlane16_swap_b32_e32 v41, v45
	v_permlane16_swap_b32_e32 v42, v46
	v_permlane16_swap_b32_e32 v43, v47
	v_permlane32_swap_b32_e32 v16, v20
	v_permlane32_swap_b32_e32 v17, v21
	v_permlane32_swap_b32_e32 v18, v22
	v_permlane32_swap_b32_e32 v19, v23
	v_permlane32_swap_b32_e32 v24, v28
	v_permlane32_swap_b32_e32 v25, v29
	v_permlane32_swap_b32_e32 v26, v30
	v_permlane32_swap_b32_e32 v27, v31
	v_permlane32_swap_b32_e32 v112, v116
	v_permlane32_swap_b32_e32 v113, v117
	v_permlane32_swap_b32_e32 v114, v118
	v_permlane32_swap_b32_e32 v115, v119
	v_permlane32_swap_b32_e32 v120, v124
	v_permlane32_swap_b32_e32 v121, v125
	v_permlane32_swap_b32_e32 v122, v126
	v_permlane32_swap_b32_e32 v123, v127
	v_permlane32_swap_b32_e32 v80, v84
	v_permlane32_swap_b32_e32 v81, v85
	v_permlane32_swap_b32_e32 v82, v86
	v_permlane32_swap_b32_e32 v83, v87
	v_permlane32_swap_b32_e32 v88, v92
	v_permlane32_swap_b32_e32 v89, v93
	v_permlane32_swap_b32_e32 v90, v94
	v_permlane32_swap_b32_e32 v91, v95
	v_permlane32_swap_b32_e32 v64, v68
	v_permlane32_swap_b32_e32 v65, v69
	v_permlane32_swap_b32_e32 v66, v70
	v_permlane32_swap_b32_e32 v67, v71
	v_permlane32_swap_b32_e32 v72, v76
	v_permlane32_swap_b32_e32 v73, v77
	v_permlane32_swap_b32_e32 v74, v78
	v_permlane32_swap_b32_e32 v75, v79
	v_permlane32_swap_b32_e32 v0, v4
	v_permlane32_swap_b32_e32 v1, v5
	v_permlane32_swap_b32_e32 v2, v6
	v_permlane32_swap_b32_e32 v3, v7
	v_permlane32_swap_b32_e32 v8, v12
	v_permlane32_swap_b32_e32 v9, v13
	v_permlane32_swap_b32_e32 v10, v14
	v_permlane32_swap_b32_e32 v11, v15
	v_permlane32_swap_b32_e32 v96, v100
	v_permlane32_swap_b32_e32 v97, v101
	v_permlane32_swap_b32_e32 v98, v102
	v_permlane32_swap_b32_e32 v99, v103
	v_permlane32_swap_b32_e32 v104, v108
	v_permlane32_swap_b32_e32 v105, v109
	v_permlane32_swap_b32_e32 v106, v110
	v_permlane32_swap_b32_e32 v107, v111
	v_permlane32_swap_b32_e32 v48, v52
	v_permlane32_swap_b32_e32 v49, v53
	v_permlane32_swap_b32_e32 v50, v54
	v_permlane32_swap_b32_e32 v51, v55
	v_permlane32_swap_b32_e32 v56, v60
	v_permlane32_swap_b32_e32 v57, v61
	v_permlane32_swap_b32_e32 v58, v62
	v_permlane32_swap_b32_e32 v59, v63
	v_permlane32_swap_b32_e32 v32, v36
	v_permlane32_swap_b32_e32 v33, v37
	v_permlane32_swap_b32_e32 v34, v38
	v_permlane32_swap_b32_e32 v35, v39
	v_permlane32_swap_b32_e32 v40, v44
	v_permlane32_swap_b32_e32 v41, v45
	v_permlane32_swap_b32_e32 v42, v46
	v_permlane32_swap_b32_e32 v43, v47
	s_waitcnt vmcnt(0)
	s_lshl_b32 s12, s2, 8
	s_cmp_eq_u32 s0, 23
	s_mov_b64 s[2:3], -1
	s_cbranch_scc1 .LBB0_347
	s_movk_i32 s1, 0x2400
	s_waitcnt vmcnt(6)
	v_and_b32_e32 v130, 0xffffffc0, v181
	s_cmp_gt_i32 s0, 10
	v_mul_lo_u32 v129, v233, s1
	v_and_b32_e32 v128, 56, v234
	v_add_u32_e32 v131, s12, v130
	s_cselect_b64 s[2:3], -1, 0
	s_cmp_gt_u32 s0, 19
	v_mul_u32_u24_e32 v130, 0x120, v183
	s_waitcnt vmcnt(0)
	v_lshl_or_b32 v132, v128, 1, v129
	v_lshl_or_b32 v128, s0, 7, v128
	s_cselect_b64 s[0:1], -1, 0
	v_lshl_add_u32 v129, v130, 1, v129
	v_lshl_or_b32 v130, v231, 1, v129
	v_cvt_pk_bf16_f32 v112, v112, s0
	ds_write_b16 v130, v112 offset:64
	v_cvt_pk_bf16_f32 v112, v17, s0
	v_cvt_pk_bf16_f32 v96, v96, s0
	ds_write_b16 v130, v112 offset:144
	v_cvt_pk_bf16_f32 v112, v113, s0
	ds_write_b16 v130, v96 offset:4672
	v_cvt_pk_bf16_f32 v96, v1, s0
	ds_write_b16 v130, v112 offset:208
	v_cvt_pk_bf16_f32 v112, v18, s0
	ds_write_b16 v130, v96 offset:4752
	v_cvt_pk_bf16_f32 v96, v97, s0
	ds_write_b16 v130, v112 offset:288
	v_cvt_pk_bf16_f32 v112, v114, s0
	ds_write_b16 v130, v96 offset:4816
	v_cvt_pk_bf16_f32 v96, v2, s0
	ds_write_b16 v130, v112 offset:352
	v_cvt_pk_bf16_f32 v112, v19, s0
	ds_write_b16 v130, v96 offset:4896
	v_cvt_pk_bf16_f32 v96, v98, s0
	ds_write_b16 v130, v112 offset:432
	v_cvt_pk_bf16_f32 v112, v115, s0
	ds_write_b16 v130, v96 offset:4960
	v_cvt_pk_bf16_f32 v96, v3, s0
	ds_write_b16 v130, v112 offset:496
	v_cvt_pk_bf16_f32 v112, v20, s0
	ds_write_b16 v130, v96 offset:5040
	v_cvt_pk_bf16_f32 v96, v99, s0
	ds_write_b16 v130, v112 offset:1152
	v_cvt_pk_bf16_f32 v112, v116, s0
	ds_write_b16 v130, v96 offset:5104
	v_cvt_pk_bf16_f32 v96, v4, s0
	ds_write_b16 v130, v112 offset:1216
	v_cvt_pk_bf16_f32 v112, v21, s0
	ds_write_b16 v130, v96 offset:5760
	v_cvt_pk_bf16_f32 v96, v100, s0
	ds_write_b16 v130, v112 offset:1296
	v_cvt_pk_bf16_f32 v112, v117, s0
	ds_write_b16 v130, v96 offset:5824
	v_cvt_pk_bf16_f32 v96, v5, s0
	ds_write_b16 v130, v112 offset:1360
	v_cvt_pk_bf16_f32 v112, v22, s0
	ds_write_b16 v130, v96 offset:5904
	v_cvt_pk_bf16_f32 v96, v101, s0
	ds_write_b16 v130, v112 offset:1440
	v_cvt_pk_bf16_f32 v112, v118, s0
	ds_write_b16 v130, v96 offset:5968
	v_cvt_pk_bf16_f32 v96, v6, s0
	ds_write_b16 v130, v112 offset:1504
	v_cvt_pk_bf16_f32 v112, v23, s0
	ds_write_b16 v130, v96 offset:6048
	v_cvt_pk_bf16_f32 v96, v102, s0
	ds_write_b16 v130, v112 offset:1584
	v_cvt_pk_bf16_f32 v112, v119, s0
	ds_write_b16 v130, v96 offset:6112
	v_cvt_pk_bf16_f32 v96, v7, s0
	ds_write_b16 v130, v112 offset:1648
	v_cvt_pk_bf16_f32 v112, v24, s0
	ds_write_b16 v130, v96 offset:6192
	v_cvt_pk_bf16_f32 v96, v103, s0
	ds_write_b16 v130, v112 offset:2304
	v_cvt_pk_bf16_f32 v112, v120, s0
	ds_write_b16 v130, v96 offset:6256
	v_cvt_pk_bf16_f32 v96, v8, s0
	ds_write_b16 v130, v112 offset:2368
	v_cvt_pk_bf16_f32 v112, v25, s0
	ds_write_b16 v130, v96 offset:6912
	v_cvt_pk_bf16_f32 v96, v104, s0
	ds_write_b16 v130, v112 offset:2448
	v_cvt_pk_bf16_f32 v112, v121, s0
	ds_write_b16 v130, v96 offset:6976
	v_cvt_pk_bf16_f32 v96, v9, s0
	ds_write_b16 v130, v112 offset:2512
	v_cvt_pk_bf16_f32 v112, v26, s0
	ds_write_b16 v130, v96 offset:7056
	v_cvt_pk_bf16_f32 v96, v105, s0
	ds_write_b16 v130, v112 offset:2592
	v_cvt_pk_bf16_f32 v112, v122, s0
	ds_write_b16 v130, v96 offset:7120
	v_cvt_pk_bf16_f32 v96, v10, s0
	ds_write_b16 v130, v112 offset:2656
	v_cvt_pk_bf16_f32 v112, v27, s0
	ds_write_b16 v130, v96 offset:7200
	v_cvt_pk_bf16_f32 v96, v106, s0
	ds_write_b16 v130, v112 offset:2736
	v_cvt_pk_bf16_f32 v112, v123, s0
	ds_write_b16 v130, v96 offset:7264
	v_cvt_pk_bf16_f32 v96, v11, s0
	ds_write_b16 v130, v112 offset:2800
	v_cvt_pk_bf16_f32 v112, v28, s0
	ds_write_b16 v130, v96 offset:7344
	v_cvt_pk_bf16_f32 v96, v107, s0
	ds_write_b16 v130, v112 offset:3456
	v_cvt_pk_bf16_f32 v112, v124, s0
	ds_write_b16 v130, v96 offset:7408
	v_cvt_pk_bf16_f32 v96, v12, s0
	ds_write_b16 v130, v112 offset:3520
	v_cvt_pk_bf16_f32 v112, v29, s0
	ds_write_b16 v130, v96 offset:8064
	v_cvt_pk_bf16_f32 v96, v108, s0
	ds_write_b16 v130, v112 offset:3600
	v_cvt_pk_bf16_f32 v112, v125, s0
	ds_write_b16 v130, v96 offset:8128
	v_cvt_pk_bf16_f32 v96, v13, s0
	ds_write_b16 v130, v112 offset:3664
	v_cvt_pk_bf16_f32 v112, v30, s0
	ds_write_b16 v130, v96 offset:8208
	v_cvt_pk_bf16_f32 v96, v109, s0
	ds_write_b16 v130, v112 offset:3744
	v_cvt_pk_bf16_f32 v112, v126, s0
	ds_write_b16 v130, v96 offset:8272
	v_cvt_pk_bf16_f32 v96, v14, s0
	ds_write_b16 v130, v112 offset:3808
	v_cvt_pk_bf16_f32 v112, v31, s0
	ds_write_b16 v130, v96 offset:8352
	v_cvt_pk_bf16_f32 v96, v110, s0
	ds_write_b16 v130, v112 offset:3888
	v_cvt_pk_bf16_f32 v112, v127, s0
	ds_write_b16 v130, v96 offset:8416
	v_cvt_pk_bf16_f32 v96, v15, s0
	v_cvt_pk_bf16_f32 v133, v16, s0
	ds_write_b16 v130, v112 offset:3952
	v_cvt_pk_bf16_f32 v112, v0, s0
	ds_write_b16 v130, v96 offset:8496
	v_cvt_pk_bf16_f32 v96, v111, s0
	ds_write_b16 v130, v133
	ds_write_b16 v130, v112 offset:4608
	ds_write_b16 v130, v96 offset:8560
	v_lshrrev_b32_e32 v109, 3, v232
	s_waitcnt lgkmcnt(0)
	v_mad_u32_u24 v96, v109, s42, v132
	ds_read_b128 v[96:99], v96
	v_mov_b32_e32 v176, v128
	v_or_b32_e32 v110, v131, v109
	s_mov_b64 s[4:5], -1
	s_and_b64 vcc, exec, s[2:3]
	s_cbranch_vccz .LBB0_224
	s_and_b64 vcc, exec, s[0:1]
	s_cbranch_vccz .LBB0_221
	v_readlane_b32 s16, v254, 15
	v_readlane_b32 s18, v254, 17
	v_readlane_b32 s19, v254, 18
	v_readlane_b32 s17, v254, 16
	v_readlane_b32 s20, v254, 19
	v_mov_b64_e32 v[100:101], s[18:19]
	v_mad_i64_i32 v[100:101], s[4:5], v110, s89, v[100:101]
	s_movk_i32 s4, 0xec00
	v_lshl_add_u64 v[100:101], v[176:177], 1, v[100:101]
	s_mov_b32 s5, -1
	v_readlane_b32 s21, v254, 20
	v_readlane_b32 s22, v254, 21
	v_readlane_b32 s23, v254, 22
	v_readlane_b32 s24, v254, 23
	v_readlane_b32 s25, v254, 24
	v_readlane_b32 s26, v254, 25
	v_readlane_b32 s27, v254, 26
	v_readlane_b32 s28, v254, 27
	v_readlane_b32 s29, v254, 28
	v_readlane_b32 s30, v254, 29
	v_readlane_b32 s31, v254, 30
	v_lshl_add_u64 v[100:101], v[100:101], 0, s[4:5]
	s_mov_b64 s[4:5], 0

.LBB0_923:
	s_ashr_i32 s2, s4, 31
	s_lshr_b32 s2, s2, 26
	s_add_i32 s2, s4, s2
	s_ashr_i32 s3, s2, 6
	s_lshl_b32 s3, s3, 3
	s_sub_i32 s8, s25, s3
	s_min_i32 s8, s8, 8
	s_abs_i32 s9, s8
	v_cvt_f32_u32_e32 v0, s9
	s_sub_i32 s12, 0, s9
	s_andn2_b32 s2, s2, 63
	s_sub_i32 s10, s4, s2
	v_rcp_iflag_f32_e32 v0, v0
	s_abs_i32 s2, s10
	s_xor_b32 s11, s10, s8
	s_ashr_i32 s11, s11, 31
	v_mul_f32_e32 v0, 0x4f7ffffe, v0
	v_cvt_u32_f32_e32 v0, v0
	v_mov_b32_e32 v181, v179
	v_readfirstlane_b32 s13, v0
	s_mul_i32 s12, s12, s13
	s_mul_hi_u32 s12, s13, s12
	s_add_i32 s13, s13, s12
	s_mul_hi_u32 s12, s2, s13
	s_mul_i32 s13, s12, s9
	s_sub_i32 s2, s2, s13
	s_add_i32 s14, s12, 1
	s_sub_i32 s13, s2, s9
	s_cmp_ge_u32 s2, s9
	s_cselect_b32 s12, s14, s12
	s_cselect_b32 s2, s13, s2
	s_add_i32 s13, s12, 1
	s_cmp_ge_u32 s2, s9
	s_cselect_b32 s2, s13, s12
	s_xor_b32 s2, s2, s11
	s_sub_i32 s2, s2, s11
	s_mul_i32 s8, s8, s2
	s_add_i32 s3, s3, s7
	s_sub_i32 s8, s10, s8
	v_ashrrev_i32_e32 v237, 6, v181
	s_add_i32 s8, s3, s8
	v_lshlrev_b32_e32 v0, 1, v237
	v_lshl_add_u32 v0, s8, 3, v0
	v_ashrrev_i32_e32 v1, 31, v0
	v_bfe_u32 v183, v181, 5, 1
	v_lshlrev_b64 v[0:1], 16, v[0:1]
	v_and_b32_e32 v238, 31, v181
	v_lshl_add_u64 v[0:1], s[64:65], 0, v[0:1]
	v_lshlrev_b32_e32 v176, 9, v183
	s_ashr_i32 s3, s2, 31
	v_lshl_add_u64 v[0:1], v[0:1], 0, v[176:177]
	v_lshlrev_b32_e32 v176, 4, v238
	v_ashrrev_i32_e32 v40, 2, v181
	s_lshl_b64 s[10:11], s[2:3], 18
	v_lshl_add_u64 v[184:185], v[0:1], 0, v[176:177]
	s_add_u32 s10, s5, s10
	v_lshlrev_b32_e32 v0, 5, v40
	s_addc_u32 s11, s6, s11
	v_ashrrev_i32_e32 v1, 31, v0
	v_lshlrev_b32_e32 v2, 4, v181
	v_lshl_add_u64 v[0:1], v[0:1], 1, s[10:11]
	v_and_b32_e32 v176, 48, v2
	v_lshl_add_u64 v[186:187], v[0:1], 0, v[176:177]
	s_movk_i32 s3, 0x2000
	v_add_co_u32_e32 v36, vcc, s3, v186
	v_mul_u32_u24_e32 v38, 40, v238
	s_nop 0
	v_addc_co_u32_e32 v37, vcc, 0, v187, vcc
	v_lshlrev_b32_e32 v39, 4, v183
	v_lshl_add_u32 v240, v38, 1, v39
	v_add_co_u32_e32 v38, vcc, s41, v184
	s_movk_i32 s9, 0x50
	s_nop 0
	v_addc_co_u32_e32 v39, vcc, 0, v185, vcc
	v_and_b32_e32 v239, 63, v181
	v_bfe_u32 v247, v181, 4, 2
	v_lshlrev_b32_e32 v247, 1, v247
	v_mov_b32_e32 v176, 0x78
	v_lshrrev_b32_e32 v247, v247, v176
	v_and_b32_e32 v247, 3, v247
	v_and_b32_e32 v246, 3, v181
	v_xor_b32_e32 v247, v247, v246
	v_lshlrev_b32_e32 v247, 4, v247
	v_and_b32_e32 v188, 0xffffffcf, v186
	v_or_b32_e32 v188, v188, v247
	v_mov_b32_e32 v189, v187
	v_lshrrev_b32_e32 v176, 6, v181
	v_lshlrev_b32_e32 v247, 11, v176
	v_lshlrev_b32_e32 v176, 10, v176
	v_lshl_add_u64 v[188:189], v[188:189], 0, v[176:177]
	v_readfirstlane_b32 vcc_lo, v247
	v_bfe_u32 v247, v181, 4, 1
	v_lshlrev_b32_e32 v176, 9, v183
	v_lshl_add_u32 v176, v247, 8, v176
	v_lshl_add_u64 v[184:185], v[184:185], 0, v[176:177]
	v_mov_b32_e32 v176, s41
	v_lshl_add_u64 v[186:187], v[184:185], 0, v[176:177]
	v_mov_b32_e32 v176, 0x78
	v_bfe_u32 v247, v181, 2, 2
	v_lshlrev_b32_e32 v247, 1, v247
	v_lshrrev_b32_e32 v247, v247, v176
	v_and_b32_e32 v247, 3, v247
	v_bfe_u32 v246, v181, 4, 2
	v_xor_b32_e32 v247, v247, v246
	v_lshlrev_b32_e32 v247, 4, v247
	v_and_b32_e32 v246, 15, v181
	v_lshl_add_u32 v246, v246, 6, v247
	s_mov_b32 s96, 0
	s_mov_b32 m0, vcc_lo
	v_lshl_add_u64 v[160:161], v[188:189], 0, s[96:97]
	global_load_lds_dwordx4 v[160:161], off
	global_load_lds_dwordx4 v[160:161], off offset:1024
	s_mov_b32 s96, 0
	v_lshl_add_u64 v[248:249], v[184:185], 0, s[96:97]
	v_lshl_add_u64 v[250:251], v[186:187], 0, s[96:97]
	global_load_dwordx4 v[128:131], v[248:249], off
	global_load_dwordx4 v[132:135], v[248:249], off offset:256
	global_load_dwordx4 v[136:139], v[250:251], off
	global_load_dwordx4 v[140:143], v[250:251], off offset:256
	s_movk_i32 s96, 0x2000
	s_add_i32 m0, vcc_lo, 8192
	v_lshl_add_u64 v[160:161], v[188:189], 0, s[96:97]
	global_load_lds_dwordx4 v[160:161], off
	global_load_lds_dwordx4 v[160:161], off offset:1024
	s_movk_i32 s96, 0x800
	v_lshl_add_u64 v[248:249], v[184:185], 0, s[96:97]
	v_lshl_add_u64 v[250:251], v[186:187], 0, s[96:97]
	global_load_dwordx4 v[144:147], v[248:249], off
	global_load_dwordx4 v[148:151], v[248:249], off offset:256
	global_load_dwordx4 v[152:155], v[250:251], off
	global_load_dwordx4 v[156:159], v[250:251], off offset:256
	v_mov_b32_e32 v0, 0
	v_mov_b32_e32 v1, 0
	v_mov_b32_e32 v2, 0
	v_mov_b32_e32 v3, 0
	v_mov_b32_e32 v4, 0
	v_mov_b32_e32 v5, 0
	v_mov_b32_e32 v6, 0
	v_mov_b32_e32 v7, 0
	v_mov_b32_e32 v8, 0
	v_mov_b32_e32 v9, 0
	v_mov_b32_e32 v10, 0
	v_mov_b32_e32 v11, 0
	v_mov_b32_e32 v12, 0
	v_mov_b32_e32 v13, 0
	v_mov_b32_e32 v14, 0
	v_mov_b32_e32 v15, 0
	v_mov_b32_e32 v16, 0
	v_mov_b32_e32 v17, 0
	v_mov_b32_e32 v18, 0
	v_mov_b32_e32 v19, 0
	v_mov_b32_e32 v20, 0
	v_mov_b32_e32 v21, 0
	v_mov_b32_e32 v22, 0
	v_mov_b32_e32 v23, 0
	v_mov_b32_e32 v24, 0
	v_mov_b32_e32 v25, 0
	v_mov_b32_e32 v26, 0
	v_mov_b32_e32 v27, 0
	v_mov_b32_e32 v28, 0
	v_mov_b32_e32 v29, 0
	v_mov_b32_e32 v30, 0
	v_mov_b32_e32 v31, 0
	v_mov_b32_e32 v32, 0
	v_mov_b32_e32 v33, 0
	v_mov_b32_e32 v34, 0
	v_mov_b32_e32 v35, 0
	v_mov_b32_e32 v36, 0
	v_mov_b32_e32 v37, 0
	v_mov_b32_e32 v38, 0
	v_mov_b32_e32 v39, 0
	v_mov_b32_e32 v40, 0
	v_mov_b32_e32 v41, 0
	v_mov_b32_e32 v42, 0
	v_mov_b32_e32 v43, 0
	v_mov_b32_e32 v44, 0
	v_mov_b32_e32 v45, 0
	v_mov_b32_e32 v46, 0
	v_mov_b32_e32 v47, 0
	v_mov_b32_e32 v48, 0
	v_mov_b32_e32 v49, 0
	v_mov_b32_e32 v50, 0
	v_mov_b32_e32 v51, 0
	v_mov_b32_e32 v52, 0
	v_mov_b32_e32 v53, 0
	v_mov_b32_e32 v54, 0
	v_mov_b32_e32 v55, 0
	v_mov_b32_e32 v56, 0
	v_mov_b32_e32 v57, 0
	v_mov_b32_e32 v58, 0
	v_mov_b32_e32 v59, 0
	v_mov_b32_e32 v60, 0
	v_mov_b32_e32 v61, 0
	v_mov_b32_e32 v62, 0
	v_mov_b32_e32 v63, 0
	v_mov_b32_e32 v64, 0
	v_mov_b32_e32 v65, 0
	v_mov_b32_e32 v66, 0
	v_mov_b32_e32 v67, 0
	v_mov_b32_e32 v68, 0
	v_mov_b32_e32 v69, 0
	v_mov_b32_e32 v70, 0
	v_mov_b32_e32 v71, 0
	v_mov_b32_e32 v72, 0
	v_mov_b32_e32 v73, 0
	v_mov_b32_e32 v74, 0
	v_mov_b32_e32 v75, 0
	v_mov_b32_e32 v76, 0
	v_mov_b32_e32 v77, 0
	v_mov_b32_e32 v78, 0
	v_mov_b32_e32 v79, 0
	v_mov_b32_e32 v80, 0
	v_mov_b32_e32 v81, 0
	v_mov_b32_e32 v82, 0
	v_mov_b32_e32 v83, 0
	v_mov_b32_e32 v84, 0
	v_mov_b32_e32 v85, 0
	v_mov_b32_e32 v86, 0
	v_mov_b32_e32 v87, 0
	v_mov_b32_e32 v88, 0
	v_mov_b32_e32 v89, 0
	v_mov_b32_e32 v90, 0
	v_mov_b32_e32 v91, 0
	v_mov_b32_e32 v92, 0
	v_mov_b32_e32 v93, 0
	v_mov_b32_e32 v94, 0
	v_mov_b32_e32 v95, 0
	v_mov_b32_e32 v96, 0
	v_mov_b32_e32 v97, 0
	v_mov_b32_e32 v98, 0
	v_mov_b32_e32 v99, 0
	v_mov_b32_e32 v100, 0
	v_mov_b32_e32 v101, 0
	v_mov_b32_e32 v102, 0
	v_mov_b32_e32 v103, 0
	v_mov_b32_e32 v104, 0
	v_mov_b32_e32 v105, 0
	v_mov_b32_e32 v106, 0
	v_mov_b32_e32 v107, 0
	v_mov_b32_e32 v108, 0
	v_mov_b32_e32 v109, 0
	v_mov_b32_e32 v110, 0
	v_mov_b32_e32 v111, 0
	v_mov_b32_e32 v112, 0
	v_mov_b32_e32 v113, 0
	v_mov_b32_e32 v114, 0
	v_mov_b32_e32 v115, 0
	v_mov_b32_e32 v116, 0
	v_mov_b32_e32 v117, 0
	v_mov_b32_e32 v118, 0
	v_mov_b32_e32 v119, 0
	v_mov_b32_e32 v120, 0
	v_mov_b32_e32 v121, 0
	v_mov_b32_e32 v122, 0
	v_mov_b32_e32 v123, 0
	v_mov_b32_e32 v124, 0
	v_mov_b32_e32 v125, 0
	v_mov_b32_e32 v126, 0
	v_mov_b32_e32 v127, 0
	s_mov_b32 s3, 0
	s_waitcnt vmcnt(4)
	s_barrier
.Lg16_out_k:
	s_add_i32 s9, s3, 2
	s_lshl_b32 s96, s9, 13
	s_add_i32 m0, vcc_lo, 16384
	v_lshl_add_u64 v[160:161], v[188:189], 0, s[96:97]
	global_load_lds_dwordx4 v[160:161], off
	global_load_lds_dwordx4 v[160:161], off offset:1024
	ds_read_b128 v[196:199], v246 offset:0
	ds_read_b128 v[200:203], v246 offset:1024
	ds_read_b128 v[204:207], v246 offset:2048
	ds_read_b128 v[242:245], v246 offset:3072
	s_add_i32 s9, s3, 2
	s_lshl_b32 s96, s9, 11
	v_lshl_add_u64 v[248:249], v[184:185], 0, s[96:97]
	v_lshl_add_u64 v[250:251], v[186:187], 0, s[96:97]
	s_waitcnt vmcnt(8) lgkmcnt(3)
	v_mfma_f32_16x16x32_bf16 v[112:115], v[128:131], v[196:199], v[112:115]
	v_mfma_f32_16x16x32_bf16 v[120:123], v[132:135], v[196:199], v[120:123]
	v_mfma_f32_16x16x32_bf16 v[48:51], v[136:139], v[196:199], v[48:51]
	v_mfma_f32_16x16x32_bf16 v[56:59], v[140:143], v[196:199], v[56:59]
	ds_read_b128 v[196:199], v246 offset:4096
	s_waitcnt lgkmcnt(3)
	v_mfma_f32_16x16x32_bf16 v[116:119], v[128:131], v[200:203], v[116:119]
	v_mfma_f32_16x16x32_bf16 v[124:127], v[132:135], v[200:203], v[124:127]
	v_mfma_f32_16x16x32_bf16 v[52:55], v[136:139], v[200:203], v[52:55]
	v_mfma_f32_16x16x32_bf16 v[60:63], v[140:143], v[200:203], v[60:63]
	ds_read_b128 v[200:203], v246 offset:5120
	s_waitcnt lgkmcnt(3)
	v_mfma_f32_16x16x32_bf16 v[96:99], v[128:131], v[204:207], v[96:99]
	v_mfma_f32_16x16x32_bf16 v[104:107], v[132:135], v[204:207], v[104:107]
	v_mfma_f32_16x16x32_bf16 v[32:35], v[136:139], v[204:207], v[32:35]
	v_mfma_f32_16x16x32_bf16 v[40:43], v[140:143], v[204:207], v[40:43]
	ds_read_b128 v[204:207], v246 offset:6144
	s_waitcnt lgkmcnt(3)
	v_mfma_f32_16x16x32_bf16 v[100:103], v[128:131], v[242:245], v[100:103]
	v_mfma_f32_16x16x32_bf16 v[108:111], v[132:135], v[242:245], v[108:111]
	v_mfma_f32_16x16x32_bf16 v[36:39], v[136:139], v[242:245], v[36:39]
	v_mfma_f32_16x16x32_bf16 v[44:47], v[140:143], v[242:245], v[44:47]
	ds_read_b128 v[242:245], v246 offset:7168
	s_waitcnt lgkmcnt(3)
	v_mfma_f32_16x16x32_bf16 v[80:83], v[128:131], v[196:199], v[80:83]
	v_mfma_f32_16x16x32_bf16 v[88:91], v[132:135], v[196:199], v[88:91]
	v_mfma_f32_16x16x32_bf16 v[16:19], v[136:139], v[196:199], v[16:19]
	v_mfma_f32_16x16x32_bf16 v[24:27], v[140:143], v[196:199], v[24:27]
	s_waitcnt lgkmcnt(2)
	v_mfma_f32_16x16x32_bf16 v[84:87], v[128:131], v[200:203], v[84:87]
	v_mfma_f32_16x16x32_bf16 v[92:95], v[132:135], v[200:203], v[92:95]
	v_mfma_f32_16x16x32_bf16 v[20:23], v[136:139], v[200:203], v[20:23]
	v_mfma_f32_16x16x32_bf16 v[28:31], v[140:143], v[200:203], v[28:31]
	s_waitcnt lgkmcnt(1)
	v_mfma_f32_16x16x32_bf16 v[64:67], v[128:131], v[204:207], v[64:67]
	v_mfma_f32_16x16x32_bf16 v[72:75], v[132:135], v[204:207], v[72:75]
	v_mfma_f32_16x16x32_bf16 v[0:3], v[136:139], v[204:207], v[0:3]
	v_mfma_f32_16x16x32_bf16 v[8:11], v[140:143], v[204:207], v[8:11]
	s_waitcnt lgkmcnt(0)
	v_mfma_f32_16x16x32_bf16 v[68:71], v[128:131], v[242:245], v[68:71]
	v_mfma_f32_16x16x32_bf16 v[76:79], v[132:135], v[242:245], v[76:79]
	v_mfma_f32_16x16x32_bf16 v[4:7], v[136:139], v[242:245], v[4:7]
	v_mfma_f32_16x16x32_bf16 v[12:15], v[140:143], v[242:245], v[12:15]
	global_load_dwordx4 v[128:131], v[248:249], off
	global_load_dwordx4 v[132:135], v[248:249], off offset:256
	global_load_dwordx4 v[136:139], v[250:251], off
	global_load_dwordx4 v[140:143], v[250:251], off offset:256
	s_waitcnt vmcnt(10)
	s_barrier
	s_add_i32 s9, s3, 3
	s_lshl_b32 s96, s9, 13
	s_mov_b32 m0, vcc_lo
	v_lshl_add_u64 v[160:161], v[188:189], 0, s[96:97]
	global_load_lds_dwordx4 v[160:161], off
	global_load_lds_dwordx4 v[160:161], off offset:1024
	ds_read_b128 v[196:199], v246 offset:8192
	ds_read_b128 v[200:203], v246 offset:9216
	ds_read_b128 v[204:207], v246 offset:10240
	ds_read_b128 v[242:245], v246 offset:11264
	s_add_i32 s9, s3, 3
	s_lshl_b32 s96, s9, 11
	v_lshl_add_u64 v[248:249], v[184:185], 0, s[96:97]
	v_lshl_add_u64 v[250:251], v[186:187], 0, s[96:97]
	s_waitcnt vmcnt(8) lgkmcnt(3)
	v_mfma_f32_16x16x32_bf16 v[112:115], v[144:147], v[196:199], v[112:115]
	v_mfma_f32_16x16x32_bf16 v[120:123], v[148:151], v[196:199], v[120:123]
	v_mfma_f32_16x16x32_bf16 v[48:51], v[152:155], v[196:199], v[48:51]
	v_mfma_f32_16x16x32_bf16 v[56:59], v[156:159], v[196:199], v[56:59]
	ds_read_b128 v[196:199], v246 offset:12288
	s_waitcnt lgkmcnt(3)
	v_mfma_f32_16x16x32_bf16 v[116:119], v[144:147], v[200:203], v[116:119]
	v_mfma_f32_16x16x32_bf16 v[124:127], v[148:151], v[200:203], v[124:127]
	v_mfma_f32_16x16x32_bf16 v[52:55], v[152:155], v[200:203], v[52:55]
	v_mfma_f32_16x16x32_bf16 v[60:63], v[156:159], v[200:203], v[60:63]
	ds_read_b128 v[200:203], v246 offset:13312
	s_waitcnt lgkmcnt(3)
	v_mfma_f32_16x16x32_bf16 v[96:99], v[144:147], v[204:207], v[96:99]
	v_mfma_f32_16x16x32_bf16 v[104:107], v[148:151], v[204:207], v[104:107]
	v_mfma_f32_16x16x32_bf16 v[32:35], v[152:155], v[204:207], v[32:35]
	v_mfma_f32_16x16x32_bf16 v[40:43], v[156:159], v[204:207], v[40:43]
	ds_read_b128 v[204:207], v246 offset:14336
	s_waitcnt lgkmcnt(3)
	v_mfma_f32_16x16x32_bf16 v[100:103], v[144:147], v[242:245], v[100:103]
	v_mfma_f32_16x16x32_bf16 v[108:111], v[148:151], v[242:245], v[108:111]
	v_mfma_f32_16x16x32_bf16 v[36:39], v[152:155], v[242:245], v[36:39]
	v_mfma_f32_16x16x32_bf16 v[44:47], v[156:159], v[242:245], v[44:47]
	ds_read_b128 v[242:245], v246 offset:15360
	s_waitcnt lgkmcnt(3)
	v_mfma_f32_16x16x32_bf16 v[80:83], v[144:147], v[196:199], v[80:83]
	v_mfma_f32_16x16x32_bf16 v[88:91], v[148:151], v[196:199], v[88:91]
	v_mfma_f32_16x16x32_bf16 v[16:19], v[152:155], v[196:199], v[16:19]
	v_mfma_f32_16x16x32_bf16 v[24:27], v[156:159], v[196:199], v[24:27]
	s_waitcnt lgkmcnt(2)
	v_mfma_f32_16x16x32_bf16 v[84:87], v[144:147], v[200:203], v[84:87]
	v_mfma_f32_16x16x32_bf16 v[92:95], v[148:151], v[200:203], v[92:95]
	v_mfma_f32_16x16x32_bf16 v[20:23], v[152:155], v[200:203], v[20:23]
	v_mfma_f32_16x16x32_bf16 v[28:31], v[156:159], v[200:203], v[28:31]
	s_waitcnt lgkmcnt(1)
	v_mfma_f32_16x16x32_bf16 v[64:67], v[144:147], v[204:207], v[64:67]
	v_mfma_f32_16x16x32_bf16 v[72:75], v[148:151], v[204:207], v[72:75]
	v_mfma_f32_16x16x32_bf16 v[0:3], v[152:155], v[204:207], v[0:3]
	v_mfma_f32_16x16x32_bf16 v[8:11], v[156:159], v[204:207], v[8:11]
	s_waitcnt lgkmcnt(0)
	v_mfma_f32_16x16x32_bf16 v[68:71], v[144:147], v[242:245], v[68:71]
	v_mfma_f32_16x16x32_bf16 v[76:79], v[148:151], v[242:245], v[76:79]
	v_mfma_f32_16x16x32_bf16 v[4:7], v[152:155], v[242:245], v[4:7]
	v_mfma_f32_16x16x32_bf16 v[12:15], v[156:159], v[242:245], v[12:15]
	global_load_dwordx4 v[144:147], v[248:249], off
	global_load_dwordx4 v[148:151], v[248:249], off offset:256
	global_load_dwordx4 v[152:155], v[250:251], off
	global_load_dwordx4 v[156:159], v[250:251], off offset:256
	s_waitcnt vmcnt(10)
	s_barrier
	s_add_i32 s9, s3, 4
	s_lshl_b32 s96, s9, 13
	s_add_i32 m0, vcc_lo, 8192
	v_lshl_add_u64 v[160:161], v[188:189], 0, s[96:97]
	global_load_lds_dwordx4 v[160:161], off
	global_load_lds_dwordx4 v[160:161], off offset:1024
	ds_read_b128 v[196:199], v246 offset:16384
	ds_read_b128 v[200:203], v246 offset:17408
	ds_read_b128 v[204:207], v246 offset:18432
	ds_read_b128 v[242:245], v246 offset:19456
	s_add_i32 s9, s3, 4
	s_lshl_b32 s96, s9, 11
	v_lshl_add_u64 v[248:249], v[184:185], 0, s[96:97]
	v_lshl_add_u64 v[250:251], v[186:187], 0, s[96:97]
	s_waitcnt vmcnt(8) lgkmcnt(3)
	v_mfma_f32_16x16x32_bf16 v[112:115], v[128:131], v[196:199], v[112:115]
	v_mfma_f32_16x16x32_bf16 v[120:123], v[132:135], v[196:199], v[120:123]
	v_mfma_f32_16x16x32_bf16 v[48:51], v[136:139], v[196:199], v[48:51]
	v_mfma_f32_16x16x32_bf16 v[56:59], v[140:143], v[196:199], v[56:59]
	ds_read_b128 v[196:199], v246 offset:20480
	s_waitcnt lgkmcnt(3)
	v_mfma_f32_16x16x32_bf16 v[116:119], v[128:131], v[200:203], v[116:119]
	v_mfma_f32_16x16x32_bf16 v[124:127], v[132:135], v[200:203], v[124:127]
	v_mfma_f32_16x16x32_bf16 v[52:55], v[136:139], v[200:203], v[52:55]
	v_mfma_f32_16x16x32_bf16 v[60:63], v[140:143], v[200:203], v[60:63]
	ds_read_b128 v[200:203], v246 offset:21504
	s_waitcnt lgkmcnt(3)
	v_mfma_f32_16x16x32_bf16 v[96:99], v[128:131], v[204:207], v[96:99]
	v_mfma_f32_16x16x32_bf16 v[104:107], v[132:135], v[204:207], v[104:107]
	v_mfma_f32_16x16x32_bf16 v[32:35], v[136:139], v[204:207], v[32:35]
	v_mfma_f32_16x16x32_bf16 v[40:43], v[140:143], v[204:207], v[40:43]
	ds_read_b128 v[204:207], v246 offset:22528
	s_waitcnt lgkmcnt(3)
	v_mfma_f32_16x16x32_bf16 v[100:103], v[128:131], v[242:245], v[100:103]
	v_mfma_f32_16x16x32_bf16 v[108:111], v[132:135], v[242:245], v[108:111]
	v_mfma_f32_16x16x32_bf16 v[36:39], v[136:139], v[242:245], v[36:39]
	v_mfma_f32_16x16x32_bf16 v[44:47], v[140:143], v[242:245], v[44:47]
	ds_read_b128 v[242:245], v246 offset:23552
	s_waitcnt lgkmcnt(3)
	v_mfma_f32_16x16x32_bf16 v[80:83], v[128:131], v[196:199], v[80:83]
	v_mfma_f32_16x16x32_bf16 v[88:91], v[132:135], v[196:199], v[88:91]
	v_mfma_f32_16x16x32_bf16 v[16:19], v[136:139], v[196:199], v[16:19]
	v_mfma_f32_16x16x32_bf16 v[24:27], v[140:143], v[196:199], v[24:27]
	s_waitcnt lgkmcnt(2)
	v_mfma_f32_16x16x32_bf16 v[84:87], v[128:131], v[200:203], v[84:87]
	v_mfma_f32_16x16x32_bf16 v[92:95], v[132:135], v[200:203], v[92:95]
	v_mfma_f32_16x16x32_bf16 v[20:23], v[136:139], v[200:203], v[20:23]
	v_mfma_f32_16x16x32_bf16 v[28:31], v[140:143], v[200:203], v[28:31]
	s_waitcnt lgkmcnt(1)
	v_mfma_f32_16x16x32_bf16 v[64:67], v[128:131], v[204:207], v[64:67]
	v_mfma_f32_16x16x32_bf16 v[72:75], v[132:135], v[204:207], v[72:75]
	v_mfma_f32_16x16x32_bf16 v[0:3], v[136:139], v[204:207], v[0:3]
	v_mfma_f32_16x16x32_bf16 v[8:11], v[140:143], v[204:207], v[8:11]
	s_waitcnt lgkmcnt(0)
	v_mfma_f32_16x16x32_bf16 v[68:71], v[128:131], v[242:245], v[68:71]
	v_mfma_f32_16x16x32_bf16 v[76:79], v[132:135], v[242:245], v[76:79]
	v_mfma_f32_16x16x32_bf16 v[4:7], v[136:139], v[242:245], v[4:7]
	v_mfma_f32_16x16x32_bf16 v[12:15], v[140:143], v[242:245], v[12:15]
	global_load_dwordx4 v[128:131], v[248:249], off
	global_load_dwordx4 v[132:135], v[248:249], off offset:256
	global_load_dwordx4 v[136:139], v[250:251], off
	global_load_dwordx4 v[140:143], v[250:251], off offset:256
	s_waitcnt vmcnt(10)
	s_barrier
	s_add_i32 s9, s3, 5
	s_lshl_b32 s96, s9, 13
	s_add_i32 m0, vcc_lo, 16384
	v_lshl_add_u64 v[160:161], v[188:189], 0, s[96:97]
	global_load_lds_dwordx4 v[160:161], off
	global_load_lds_dwordx4 v[160:161], off offset:1024
	ds_read_b128 v[196:199], v246 offset:0
	ds_read_b128 v[200:203], v246 offset:1024
	ds_read_b128 v[204:207], v246 offset:2048
	ds_read_b128 v[242:245], v246 offset:3072
	s_add_i32 s9, s3, 5
	s_lshl_b32 s96, s9, 11
	v_lshl_add_u64 v[248:249], v[184:185], 0, s[96:97]
	v_lshl_add_u64 v[250:251], v[186:187], 0, s[96:97]
	s_waitcnt vmcnt(8) lgkmcnt(3)
	v_mfma_f32_16x16x32_bf16 v[112:115], v[144:147], v[196:199], v[112:115]
	v_mfma_f32_16x16x32_bf16 v[120:123], v[148:151], v[196:199], v[120:123]
	v_mfma_f32_16x16x32_bf16 v[48:51], v[152:155], v[196:199], v[48:51]
	v_mfma_f32_16x16x32_bf16 v[56:59], v[156:159], v[196:199], v[56:59]
	ds_read_b128 v[196:199], v246 offset:4096
	s_waitcnt lgkmcnt(3)
	v_mfma_f32_16x16x32_bf16 v[116:119], v[144:147], v[200:203], v[116:119]
	v_mfma_f32_16x16x32_bf16 v[124:127], v[148:151], v[200:203], v[124:127]
	v_mfma_f32_16x16x32_bf16 v[52:55], v[152:155], v[200:203], v[52:55]
	v_mfma_f32_16x16x32_bf16 v[60:63], v[156:159], v[200:203], v[60:63]
	ds_read_b128 v[200:203], v246 offset:5120
	s_waitcnt lgkmcnt(3)
	v_mfma_f32_16x16x32_bf16 v[96:99], v[144:147], v[204:207], v[96:99]
	v_mfma_f32_16x16x32_bf16 v[104:107], v[148:151], v[204:207], v[104:107]
	v_mfma_f32_16x16x32_bf16 v[32:35], v[152:155], v[204:207], v[32:35]
	v_mfma_f32_16x16x32_bf16 v[40:43], v[156:159], v[204:207], v[40:43]
	ds_read_b128 v[204:207], v246 offset:6144
	s_waitcnt lgkmcnt(3)
	v_mfma_f32_16x16x32_bf16 v[100:103], v[144:147], v[242:245], v[100:103]
	v_mfma_f32_16x16x32_bf16 v[108:111], v[148:151], v[242:245], v[108:111]
	v_mfma_f32_16x16x32_bf16 v[36:39], v[152:155], v[242:245], v[36:39]
	v_mfma_f32_16x16x32_bf16 v[44:47], v[156:159], v[242:245], v[44:47]
	ds_read_b128 v[242:245], v246 offset:7168
	s_waitcnt lgkmcnt(3)
	v_mfma_f32_16x16x32_bf16 v[80:83], v[144:147], v[196:199], v[80:83]
	v_mfma_f32_16x16x32_bf16 v[88:91], v[148:151], v[196:199], v[88:91]
	v_mfma_f32_16x16x32_bf16 v[16:19], v[152:155], v[196:199], v[16:19]
	v_mfma_f32_16x16x32_bf16 v[24:27], v[156:159], v[196:199], v[24:27]
	s_waitcnt lgkmcnt(2)
	v_mfma_f32_16x16x32_bf16 v[84:87], v[144:147], v[200:203], v[84:87]
	v_mfma_f32_16x16x32_bf16 v[92:95], v[148:151], v[200:203], v[92:95]
	v_mfma_f32_16x16x32_bf16 v[20:23], v[152:155], v[200:203], v[20:23]
	v_mfma_f32_16x16x32_bf16 v[28:31], v[156:159], v[200:203], v[28:31]
	s_waitcnt lgkmcnt(1)
	v_mfma_f32_16x16x32_bf16 v[64:67], v[144:147], v[204:207], v[64:67]
	v_mfma_f32_16x16x32_bf16 v[72:75], v[148:151], v[204:207], v[72:75]
	v_mfma_f32_16x16x32_bf16 v[0:3], v[152:155], v[204:207], v[0:3]
	v_mfma_f32_16x16x32_bf16 v[8:11], v[156:159], v[204:207], v[8:11]
	s_waitcnt lgkmcnt(0)
	v_mfma_f32_16x16x32_bf16 v[68:71], v[144:147], v[242:245], v[68:71]
	v_mfma_f32_16x16x32_bf16 v[76:79], v[148:151], v[242:245], v[76:79]
	v_mfma_f32_16x16x32_bf16 v[4:7], v[152:155], v[242:245], v[4:7]
	v_mfma_f32_16x16x32_bf16 v[12:15], v[156:159], v[242:245], v[12:15]
	global_load_dwordx4 v[144:147], v[248:249], off
	global_load_dwordx4 v[148:151], v[248:249], off offset:256
	global_load_dwordx4 v[152:155], v[250:251], off
	global_load_dwordx4 v[156:159], v[250:251], off offset:256
	s_waitcnt vmcnt(10)
	s_barrier
	s_add_i32 s9, s3, 6
	s_lshl_b32 s96, s9, 13
	s_mov_b32 m0, vcc_lo
	v_lshl_add_u64 v[160:161], v[188:189], 0, s[96:97]
	global_load_lds_dwordx4 v[160:161], off
	global_load_lds_dwordx4 v[160:161], off offset:1024
	ds_read_b128 v[196:199], v246 offset:8192
	ds_read_b128 v[200:203], v246 offset:9216
	ds_read_b128 v[204:207], v246 offset:10240
	ds_read_b128 v[242:245], v246 offset:11264
	s_add_i32 s9, s3, 6
	s_lshl_b32 s96, s9, 11
	v_lshl_add_u64 v[248:249], v[184:185], 0, s[96:97]
	v_lshl_add_u64 v[250:251], v[186:187], 0, s[96:97]
	s_waitcnt vmcnt(8) lgkmcnt(3)
	v_mfma_f32_16x16x32_bf16 v[112:115], v[128:131], v[196:199], v[112:115]
	v_mfma_f32_16x16x32_bf16 v[120:123], v[132:135], v[196:199], v[120:123]
	v_mfma_f32_16x16x32_bf16 v[48:51], v[136:139], v[196:199], v[48:51]
	v_mfma_f32_16x16x32_bf16 v[56:59], v[140:143], v[196:199], v[56:59]
	ds_read_b128 v[196:199], v246 offset:12288
	s_waitcnt lgkmcnt(3)
	v_mfma_f32_16x16x32_bf16 v[116:119], v[128:131], v[200:203], v[116:119]
	v_mfma_f32_16x16x32_bf16 v[124:127], v[132:135], v[200:203], v[124:127]
	v_mfma_f32_16x16x32_bf16 v[52:55], v[136:139], v[200:203], v[52:55]
	v_mfma_f32_16x16x32_bf16 v[60:63], v[140:143], v[200:203], v[60:63]
	ds_read_b128 v[200:203], v246 offset:13312
	s_waitcnt lgkmcnt(3)
	v_mfma_f32_16x16x32_bf16 v[96:99], v[128:131], v[204:207], v[96:99]
	v_mfma_f32_16x16x32_bf16 v[104:107], v[132:135], v[204:207], v[104:107]
	v_mfma_f32_16x16x32_bf16 v[32:35], v[136:139], v[204:207], v[32:35]
	v_mfma_f32_16x16x32_bf16 v[40:43], v[140:143], v[204:207], v[40:43]
	ds_read_b128 v[204:207], v246 offset:14336
	s_waitcnt lgkmcnt(3)
	v_mfma_f32_16x16x32_bf16 v[100:103], v[128:131], v[242:245], v[100:103]
	v_mfma_f32_16x16x32_bf16 v[108:111], v[132:135], v[242:245], v[108:111]
	v_mfma_f32_16x16x32_bf16 v[36:39], v[136:139], v[242:245], v[36:39]
	v_mfma_f32_16x16x32_bf16 v[44:47], v[140:143], v[242:245], v[44:47]
	ds_read_b128 v[242:245], v246 offset:15360
	s_waitcnt lgkmcnt(3)
	v_mfma_f32_16x16x32_bf16 v[80:83], v[128:131], v[196:199], v[80:83]
	v_mfma_f32_16x16x32_bf16 v[88:91], v[132:135], v[196:199], v[88:91]
	v_mfma_f32_16x16x32_bf16 v[16:19], v[136:139], v[196:199], v[16:19]
	v_mfma_f32_16x16x32_bf16 v[24:27], v[140:143], v[196:199], v[24:27]
	s_waitcnt lgkmcnt(2)
	v_mfma_f32_16x16x32_bf16 v[84:87], v[128:131], v[200:203], v[84:87]
	v_mfma_f32_16x16x32_bf16 v[92:95], v[132:135], v[200:203], v[92:95]
	v_mfma_f32_16x16x32_bf16 v[20:23], v[136:139], v[200:203], v[20:23]
	v_mfma_f32_16x16x32_bf16 v[28:31], v[140:143], v[200:203], v[28:31]
	s_waitcnt lgkmcnt(1)
	v_mfma_f32_16x16x32_bf16 v[64:67], v[128:131], v[204:207], v[64:67]
	v_mfma_f32_16x16x32_bf16 v[72:75], v[132:135], v[204:207], v[72:75]
	v_mfma_f32_16x16x32_bf16 v[0:3], v[136:139], v[204:207], v[0:3]
	v_mfma_f32_16x16x32_bf16 v[8:11], v[140:143], v[204:207], v[8:11]
	s_waitcnt lgkmcnt(0)
	v_mfma_f32_16x16x32_bf16 v[68:71], v[128:131], v[242:245], v[68:71]
	v_mfma_f32_16x16x32_bf16 v[76:79], v[132:135], v[242:245], v[76:79]
	v_mfma_f32_16x16x32_bf16 v[4:7], v[136:139], v[242:245], v[4:7]
	v_mfma_f32_16x16x32_bf16 v[12:15], v[140:143], v[242:245], v[12:15]
	global_load_dwordx4 v[128:131], v[248:249], off
	global_load_dwordx4 v[132:135], v[248:249], off offset:256
	global_load_dwordx4 v[136:139], v[250:251], off
	global_load_dwordx4 v[140:143], v[250:251], off offset:256
	s_waitcnt vmcnt(10)
	s_barrier
	s_add_i32 s9, s3, 7
	s_lshl_b32 s96, s9, 13
	s_add_i32 m0, vcc_lo, 8192
	v_lshl_add_u64 v[160:161], v[188:189], 0, s[96:97]
	global_load_lds_dwordx4 v[160:161], off
	global_load_lds_dwordx4 v[160:161], off offset:1024
	ds_read_b128 v[196:199], v246 offset:16384
	ds_read_b128 v[200:203], v246 offset:17408
	ds_read_b128 v[204:207], v246 offset:18432
	ds_read_b128 v[242:245], v246 offset:19456
	s_add_i32 s9, s3, 7
	s_lshl_b32 s96, s9, 11
	v_lshl_add_u64 v[248:249], v[184:185], 0, s[96:97]
	v_lshl_add_u64 v[250:251], v[186:187], 0, s[96:97]
	s_waitcnt vmcnt(8) lgkmcnt(3)
	v_mfma_f32_16x16x32_bf16 v[112:115], v[144:147], v[196:199], v[112:115]
	v_mfma_f32_16x16x32_bf16 v[120:123], v[148:151], v[196:199], v[120:123]
	v_mfma_f32_16x16x32_bf16 v[48:51], v[152:155], v[196:199], v[48:51]
	v_mfma_f32_16x16x32_bf16 v[56:59], v[156:159], v[196:199], v[56:59]
	ds_read_b128 v[196:199], v246 offset:20480
	s_waitcnt lgkmcnt(3)
	v_mfma_f32_16x16x32_bf16 v[116:119], v[144:147], v[200:203], v[116:119]
	v_mfma_f32_16x16x32_bf16 v[124:127], v[148:151], v[200:203], v[124:127]
	v_mfma_f32_16x16x32_bf16 v[52:55], v[152:155], v[200:203], v[52:55]
	v_mfma_f32_16x16x32_bf16 v[60:63], v[156:159], v[200:203], v[60:63]
	ds_read_b128 v[200:203], v246 offset:21504
	s_waitcnt lgkmcnt(3)
	v_mfma_f32_16x16x32_bf16 v[96:99], v[144:147], v[204:207], v[96:99]
	v_mfma_f32_16x16x32_bf16 v[104:107], v[148:151], v[204:207], v[104:107]
	v_mfma_f32_16x16x32_bf16 v[32:35], v[152:155], v[204:207], v[32:35]
	v_mfma_f32_16x16x32_bf16 v[40:43], v[156:159], v[204:207], v[40:43]
	ds_read_b128 v[204:207], v246 offset:22528
	s_waitcnt lgkmcnt(3)
	v_mfma_f32_16x16x32_bf16 v[100:103], v[144:147], v[242:245], v[100:103]
	v_mfma_f32_16x16x32_bf16 v[108:111], v[148:151], v[242:245], v[108:111]
	v_mfma_f32_16x16x32_bf16 v[36:39], v[152:155], v[242:245], v[36:39]
	v_mfma_f32_16x16x32_bf16 v[44:47], v[156:159], v[242:245], v[44:47]
	ds_read_b128 v[242:245], v246 offset:23552
	s_waitcnt lgkmcnt(3)
	v_mfma_f32_16x16x32_bf16 v[80:83], v[144:147], v[196:199], v[80:83]
	v_mfma_f32_16x16x32_bf16 v[88:91], v[148:151], v[196:199], v[88:91]
	v_mfma_f32_16x16x32_bf16 v[16:19], v[152:155], v[196:199], v[16:19]
	v_mfma_f32_16x16x32_bf16 v[24:27], v[156:159], v[196:199], v[24:27]
	s_waitcnt lgkmcnt(2)
	v_mfma_f32_16x16x32_bf16 v[84:87], v[144:147], v[200:203], v[84:87]
	v_mfma_f32_16x16x32_bf16 v[92:95], v[148:151], v[200:203], v[92:95]
	v_mfma_f32_16x16x32_bf16 v[20:23], v[152:155], v[200:203], v[20:23]
	v_mfma_f32_16x16x32_bf16 v[28:31], v[156:159], v[200:203], v[28:31]
	s_waitcnt lgkmcnt(1)
	v_mfma_f32_16x16x32_bf16 v[64:67], v[144:147], v[204:207], v[64:67]
	v_mfma_f32_16x16x32_bf16 v[72:75], v[148:151], v[204:207], v[72:75]
	v_mfma_f32_16x16x32_bf16 v[0:3], v[152:155], v[204:207], v[0:3]
	v_mfma_f32_16x16x32_bf16 v[8:11], v[156:159], v[204:207], v[8:11]
	s_waitcnt lgkmcnt(0)
	v_mfma_f32_16x16x32_bf16 v[68:71], v[144:147], v[242:245], v[68:71]
	v_mfma_f32_16x16x32_bf16 v[76:79], v[148:151], v[242:245], v[76:79]
	v_mfma_f32_16x16x32_bf16 v[4:7], v[152:155], v[242:245], v[4:7]
	v_mfma_f32_16x16x32_bf16 v[12:15], v[156:159], v[242:245], v[12:15]
	global_load_dwordx4 v[144:147], v[248:249], off
	global_load_dwordx4 v[148:151], v[248:249], off offset:256
	global_load_dwordx4 v[152:155], v[250:251], off
	global_load_dwordx4 v[156:159], v[250:251], off offset:256
	s_waitcnt vmcnt(10)
	s_barrier
	s_add_i32 s3, s3, 6
	s_cmp_lt_u32 s3, 30
	s_cbranch_scc1 .Lg16_out_k
	ds_read_b128 v[196:199], v246 offset:0
	ds_read_b128 v[200:203], v246 offset:1024
	ds_read_b128 v[204:207], v246 offset:2048
	ds_read_b128 v[242:245], v246 offset:3072
	s_waitcnt vmcnt(6) lgkmcnt(3)
	v_mfma_f32_16x16x32_bf16 v[112:115], v[128:131], v[196:199], v[112:115]
	v_mfma_f32_16x16x32_bf16 v[120:123], v[132:135], v[196:199], v[120:123]
	v_mfma_f32_16x16x32_bf16 v[48:51], v[136:139], v[196:199], v[48:51]
	v_mfma_f32_16x16x32_bf16 v[56:59], v[140:143], v[196:199], v[56:59]
	ds_read_b128 v[196:199], v246 offset:4096
	s_waitcnt lgkmcnt(3)
	v_mfma_f32_16x16x32_bf16 v[116:119], v[128:131], v[200:203], v[116:119]
	v_mfma_f32_16x16x32_bf16 v[124:127], v[132:135], v[200:203], v[124:127]
	v_mfma_f32_16x16x32_bf16 v[52:55], v[136:139], v[200:203], v[52:55]
	v_mfma_f32_16x16x32_bf16 v[60:63], v[140:143], v[200:203], v[60:63]
	ds_read_b128 v[200:203], v246 offset:5120
	s_waitcnt lgkmcnt(3)
	v_mfma_f32_16x16x32_bf16 v[96:99], v[128:131], v[204:207], v[96:99]
	v_mfma_f32_16x16x32_bf16 v[104:107], v[132:135], v[204:207], v[104:107]
	v_mfma_f32_16x16x32_bf16 v[32:35], v[136:139], v[204:207], v[32:35]
	v_mfma_f32_16x16x32_bf16 v[40:43], v[140:143], v[204:207], v[40:43]
	ds_read_b128 v[204:207], v246 offset:6144
	s_waitcnt lgkmcnt(3)
	v_mfma_f32_16x16x32_bf16 v[100:103], v[128:131], v[242:245], v[100:103]
	v_mfma_f32_16x16x32_bf16 v[108:111], v[132:135], v[242:245], v[108:111]
	v_mfma_f32_16x16x32_bf16 v[36:39], v[136:139], v[242:245], v[36:39]
	v_mfma_f32_16x16x32_bf16 v[44:47], v[140:143], v[242:245], v[44:47]
	ds_read_b128 v[242:245], v246 offset:7168
	s_waitcnt lgkmcnt(3)
	v_mfma_f32_16x16x32_bf16 v[80:83], v[128:131], v[196:199], v[80:83]
	v_mfma_f32_16x16x32_bf16 v[88:91], v[132:135], v[196:199], v[88:91]
	v_mfma_f32_16x16x32_bf16 v[16:19], v[136:139], v[196:199], v[16:19]
	v_mfma_f32_16x16x32_bf16 v[24:27], v[140:143], v[196:199], v[24:27]
	s_waitcnt lgkmcnt(2)
	v_mfma_f32_16x16x32_bf16 v[84:87], v[128:131], v[200:203], v[84:87]
	v_mfma_f32_16x16x32_bf16 v[92:95], v[132:135], v[200:203], v[92:95]
	v_mfma_f32_16x16x32_bf16 v[20:23], v[136:139], v[200:203], v[20:23]
	v_mfma_f32_16x16x32_bf16 v[28:31], v[140:143], v[200:203], v[28:31]
	s_waitcnt lgkmcnt(1)
	v_mfma_f32_16x16x32_bf16 v[64:67], v[128:131], v[204:207], v[64:67]
	v_mfma_f32_16x16x32_bf16 v[72:75], v[132:135], v[204:207], v[72:75]
	v_mfma_f32_16x16x32_bf16 v[0:3], v[136:139], v[204:207], v[0:3]
	v_mfma_f32_16x16x32_bf16 v[8:11], v[140:143], v[204:207], v[8:11]
	s_waitcnt lgkmcnt(0)
	v_mfma_f32_16x16x32_bf16 v[68:71], v[128:131], v[242:245], v[68:71]
	v_mfma_f32_16x16x32_bf16 v[76:79], v[132:135], v[242:245], v[76:79]
	v_mfma_f32_16x16x32_bf16 v[4:7], v[136:139], v[242:245], v[4:7]
	v_mfma_f32_16x16x32_bf16 v[12:15], v[140:143], v[242:245], v[12:15]
	s_waitcnt vmcnt(4)
	s_barrier
	ds_read_b128 v[196:199], v246 offset:8192
	ds_read_b128 v[200:203], v246 offset:9216
	ds_read_b128 v[204:207], v246 offset:10240
	ds_read_b128 v[242:245], v246 offset:11264
	s_waitcnt vmcnt(0) lgkmcnt(3)
	v_mfma_f32_16x16x32_bf16 v[112:115], v[144:147], v[196:199], v[112:115]
	v_mfma_f32_16x16x32_bf16 v[120:123], v[148:151], v[196:199], v[120:123]
	v_mfma_f32_16x16x32_bf16 v[48:51], v[152:155], v[196:199], v[48:51]
	v_mfma_f32_16x16x32_bf16 v[56:59], v[156:159], v[196:199], v[56:59]
	ds_read_b128 v[196:199], v246 offset:12288
	s_waitcnt lgkmcnt(3)
	v_mfma_f32_16x16x32_bf16 v[116:119], v[144:147], v[200:203], v[116:119]
	v_mfma_f32_16x16x32_bf16 v[124:127], v[148:151], v[200:203], v[124:127]
	v_mfma_f32_16x16x32_bf16 v[52:55], v[152:155], v[200:203], v[52:55]
	v_mfma_f32_16x16x32_bf16 v[60:63], v[156:159], v[200:203], v[60:63]
	ds_read_b128 v[200:203], v246 offset:13312
	s_waitcnt lgkmcnt(3)
	v_mfma_f32_16x16x32_bf16 v[96:99], v[144:147], v[204:207], v[96:99]
	v_mfma_f32_16x16x32_bf16 v[104:107], v[148:151], v[204:207], v[104:107]
	v_mfma_f32_16x16x32_bf16 v[32:35], v[152:155], v[204:207], v[32:35]
	v_mfma_f32_16x16x32_bf16 v[40:43], v[156:159], v[204:207], v[40:43]
	ds_read_b128 v[204:207], v246 offset:14336
	s_waitcnt lgkmcnt(3)
	v_mfma_f32_16x16x32_bf16 v[100:103], v[144:147], v[242:245], v[100:103]
	v_mfma_f32_16x16x32_bf16 v[108:111], v[148:151], v[242:245], v[108:111]
	v_mfma_f32_16x16x32_bf16 v[36:39], v[152:155], v[242:245], v[36:39]
	v_mfma_f32_16x16x32_bf16 v[44:47], v[156:159], v[242:245], v[44:47]
	ds_read_b128 v[242:245], v246 offset:15360
	s_waitcnt lgkmcnt(3)
	v_mfma_f32_16x16x32_bf16 v[80:83], v[144:147], v[196:199], v[80:83]
	v_mfma_f32_16x16x32_bf16 v[88:91], v[148:151], v[196:199], v[88:91]
	v_mfma_f32_16x16x32_bf16 v[16:19], v[152:155], v[196:199], v[16:19]
	v_mfma_f32_16x16x32_bf16 v[24:27], v[156:159], v[196:199], v[24:27]
	s_waitcnt lgkmcnt(2)
	v_mfma_f32_16x16x32_bf16 v[84:87], v[144:147], v[200:203], v[84:87]
	v_mfma_f32_16x16x32_bf16 v[92:95], v[148:151], v[200:203], v[92:95]
	v_mfma_f32_16x16x32_bf16 v[20:23], v[152:155], v[200:203], v[20:23]
	v_mfma_f32_16x16x32_bf16 v[28:31], v[156:159], v[200:203], v[28:31]
	s_waitcnt lgkmcnt(1)
	v_mfma_f32_16x16x32_bf16 v[64:67], v[144:147], v[204:207], v[64:67]
	v_mfma_f32_16x16x32_bf16 v[72:75], v[148:151], v[204:207], v[72:75]
	v_mfma_f32_16x16x32_bf16 v[0:3], v[152:155], v[204:207], v[0:3]
	v_mfma_f32_16x16x32_bf16 v[8:11], v[156:159], v[204:207], v[8:11]
	s_waitcnt lgkmcnt(0)
	v_mfma_f32_16x16x32_bf16 v[68:71], v[144:147], v[242:245], v[68:71]
	v_mfma_f32_16x16x32_bf16 v[76:79], v[148:151], v[242:245], v[76:79]
	v_mfma_f32_16x16x32_bf16 v[4:7], v[152:155], v[242:245], v[4:7]
	v_mfma_f32_16x16x32_bf16 v[12:15], v[156:159], v[242:245], v[12:15]
	s_barrier
	s_nop 7
	v_permlane16_swap_b32_e32 v112, v116
	v_permlane16_swap_b32_e32 v113, v117
	v_permlane16_swap_b32_e32 v114, v118
	v_permlane16_swap_b32_e32 v115, v119
	v_permlane16_swap_b32_e32 v120, v124
	v_permlane16_swap_b32_e32 v121, v125
	v_permlane16_swap_b32_e32 v122, v126
	v_permlane16_swap_b32_e32 v123, v127
	v_permlane16_swap_b32_e32 v96, v100
	v_permlane16_swap_b32_e32 v97, v101
	v_permlane16_swap_b32_e32 v98, v102
	v_permlane16_swap_b32_e32 v99, v103
	v_permlane16_swap_b32_e32 v104, v108
	v_permlane16_swap_b32_e32 v105, v109
	v_permlane16_swap_b32_e32 v106, v110
	v_permlane16_swap_b32_e32 v107, v111
	v_permlane16_swap_b32_e32 v80, v84
	v_permlane16_swap_b32_e32 v81, v85
	v_permlane16_swap_b32_e32 v82, v86
	v_permlane16_swap_b32_e32 v83, v87
	v_permlane16_swap_b32_e32 v88, v92
	v_permlane16_swap_b32_e32 v89, v93
	v_permlane16_swap_b32_e32 v90, v94
	v_permlane16_swap_b32_e32 v91, v95
	v_permlane16_swap_b32_e32 v64, v68
	v_permlane16_swap_b32_e32 v65, v69
	v_permlane16_swap_b32_e32 v66, v70
	v_permlane16_swap_b32_e32 v67, v71
	v_permlane16_swap_b32_e32 v72, v76
	v_permlane16_swap_b32_e32 v73, v77
	v_permlane16_swap_b32_e32 v74, v78
	v_permlane16_swap_b32_e32 v75, v79
	v_permlane16_swap_b32_e32 v48, v52
	v_permlane16_swap_b32_e32 v49, v53
	v_permlane16_swap_b32_e32 v50, v54
	v_permlane16_swap_b32_e32 v51, v55
	v_permlane16_swap_b32_e32 v56, v60
	v_permlane16_swap_b32_e32 v57, v61
	v_permlane16_swap_b32_e32 v58, v62
	v_permlane16_swap_b32_e32 v59, v63
	v_permlane16_swap_b32_e32 v32, v36
	v_permlane16_swap_b32_e32 v33, v37
	v_permlane16_swap_b32_e32 v34, v38
	v_permlane16_swap_b32_e32 v35, v39
	v_permlane16_swap_b32_e32 v40, v44
	v_permlane16_swap_b32_e32 v41, v45
	v_permlane16_swap_b32_e32 v42, v46
	v_permlane16_swap_b32_e32 v43, v47
	v_permlane16_swap_b32_e32 v16, v20
	v_permlane16_swap_b32_e32 v17, v21
	v_permlane16_swap_b32_e32 v18, v22
	v_permlane16_swap_b32_e32 v19, v23
	v_permlane16_swap_b32_e32 v24, v28
	v_permlane16_swap_b32_e32 v25, v29
	v_permlane16_swap_b32_e32 v26, v30
	v_permlane16_swap_b32_e32 v27, v31
	v_permlane16_swap_b32_e32 v0, v4
	v_permlane16_swap_b32_e32 v1, v5
	v_permlane16_swap_b32_e32 v2, v6
	v_permlane16_swap_b32_e32 v3, v7
	v_permlane16_swap_b32_e32 v8, v12
	v_permlane16_swap_b32_e32 v9, v13
	v_permlane16_swap_b32_e32 v10, v14
	v_permlane16_swap_b32_e32 v11, v15
	v_permlane32_swap_b32_e32 v112, v116
	v_permlane32_swap_b32_e32 v113, v117
	v_permlane32_swap_b32_e32 v114, v118
	v_permlane32_swap_b32_e32 v115, v119
	v_permlane32_swap_b32_e32 v120, v124
	v_permlane32_swap_b32_e32 v121, v125
	v_permlane32_swap_b32_e32 v122, v126
	v_permlane32_swap_b32_e32 v123, v127
	v_permlane32_swap_b32_e32 v96, v100
	v_permlane32_swap_b32_e32 v97, v101
	v_permlane32_swap_b32_e32 v98, v102
	v_permlane32_swap_b32_e32 v99, v103
	v_permlane32_swap_b32_e32 v104, v108
	v_permlane32_swap_b32_e32 v105, v109
	v_permlane32_swap_b32_e32 v106, v110
	v_permlane32_swap_b32_e32 v107, v111
	v_permlane32_swap_b32_e32 v80, v84
	v_permlane32_swap_b32_e32 v81, v85
	v_permlane32_swap_b32_e32 v82, v86
	v_permlane32_swap_b32_e32 v83, v87
	v_permlane32_swap_b32_e32 v88, v92
	v_permlane32_swap_b32_e32 v89, v93
	v_permlane32_swap_b32_e32 v90, v94
	v_permlane32_swap_b32_e32 v91, v95
	v_permlane32_swap_b32_e32 v64, v68
	v_permlane32_swap_b32_e32 v65, v69
	v_permlane32_swap_b32_e32 v66, v70
	v_permlane32_swap_b32_e32 v67, v71
	v_permlane32_swap_b32_e32 v72, v76
	v_permlane32_swap_b32_e32 v73, v77
	v_permlane32_swap_b32_e32 v74, v78
	v_permlane32_swap_b32_e32 v75, v79
	v_permlane32_swap_b32_e32 v48, v52
	v_permlane32_swap_b32_e32 v49, v53
	v_permlane32_swap_b32_e32 v50, v54
	v_permlane32_swap_b32_e32 v51, v55
	v_permlane32_swap_b32_e32 v56, v60
	v_permlane32_swap_b32_e32 v57, v61
	v_permlane32_swap_b32_e32 v58, v62
	v_permlane32_swap_b32_e32 v59, v63
	v_permlane32_swap_b32_e32 v32, v36
	v_permlane32_swap_b32_e32 v33, v37
	v_permlane32_swap_b32_e32 v34, v38
	v_permlane32_swap_b32_e32 v35, v39
	v_permlane32_swap_b32_e32 v40, v44
	v_permlane32_swap_b32_e32 v41, v45
	v_permlane32_swap_b32_e32 v42, v46
	v_permlane32_swap_b32_e32 v43, v47
	v_permlane32_swap_b32_e32 v16, v20
	v_permlane32_swap_b32_e32 v17, v21
	v_permlane32_swap_b32_e32 v18, v22
	v_permlane32_swap_b32_e32 v19, v23
	v_permlane32_swap_b32_e32 v24, v28
	v_permlane32_swap_b32_e32 v25, v29
	v_permlane32_swap_b32_e32 v26, v30
	v_permlane32_swap_b32_e32 v27, v31
	v_permlane32_swap_b32_e32 v0, v4
	v_permlane32_swap_b32_e32 v1, v5
	v_permlane32_swap_b32_e32 v2, v6
	v_permlane32_swap_b32_e32 v3, v7
	v_permlane32_swap_b32_e32 v8, v12
	v_permlane32_swap_b32_e32 v9, v13
	v_permlane32_swap_b32_e32 v10, v14
	v_permlane32_swap_b32_e32 v11, v15
	s_waitcnt vmcnt(0)
	s_movk_i32 s3, 0x2400
	s_waitcnt vmcnt(6)
	v_lshlrev_b32_e32 v128, 2, v181
	s_waitcnt vmcnt(0)
	v_and_b32_e32 v133, 0xffffffc0, v181
	v_mul_lo_u32 v129, v237, s3
	v_lshlrev_b32_e32 v130, 2, v238
	v_and_b32_e32 v128, 60, v128
	v_lshl_add_u32 v176, s8, 8, v133
	v_mul_u32_u24_e32 v133, 0x110, v183
	v_or_b32_e32 v131, v129, v130
	v_lshl_or_b32 v132, v128, 2, v129
	v_lshl_or_b32 v128, s2, 7, v128
	v_lshlrev_b32_e32 v133, 2, v133
	v_lshrrev_b32_e32 v175, 4, v239
	s_movk_i32 s2, 0x110
	v_add_u32_e32 v147, v131, v133
	v_add3_u32 v148, v129, v133, v130
	v_mad_u32_u24 v146, v175, s2, v132
	v_readlane_b32 s2, v254, 39
	v_readlane_b32 s8, v253, 36
	v_add_u32_e32 v149, 0x800, v147
	v_add_u32_e32 v150, 0x800, v148
	v_add_u32_e32 v151, 0xa00, v148
	v_mov_b32_e32 v160, s2
	v_readlane_b32 s2, v254, 37
	v_readlane_b32 s9, v253, 37
	v_readlane_b32 s10, v253, 38
	v_readlane_b32 s11, v253, 39
	v_readlane_b32 s12, v253, 40
	v_readlane_b32 s13, v253, 41
	v_readlane_b32 s14, v253, 42
	v_readlane_b32 s15, v253, 43
	v_readlane_b32 s16, v253, 44
	v_readlane_b32 s17, v253, 45
	ds_write2_b32 v147, v112, v113 offset1:68
	ds_write2_b32 v148, v96, v97 offset0:32 offset1:100
	ds_write2_b32 v147, v114, v115 offset0:136 offset1:204
	ds_write2_b32 v148, v98, v99 offset0:168 offset1:236
	ds_write2_b32 v149, v116, v117 offset0:32 offset1:100
	ds_write2_b32 v150, v100, v101 offset0:64 offset1:132
	ds_write2_b32 v149, v118, v119 offset0:168 offset1:236
	ds_write2_b32 v151, v102, v103 offset0:72 offset1:140
	v_or_b32_e32 v102, v176, v175
	v_mov_b32_e32 v161, s2
	v_readlane_b32 s2, v254, 40
	v_readlane_b32 s18, v253, 46
	v_readlane_b32 s19, v253, 47
	v_readlane_b32 s20, v253, 48
	v_readlane_b32 s21, v253, 49
	v_readlane_b32 s22, v253, 50
	v_readlane_b32 s23, v253, 51
	s_mov_b64 s[8:9], s[16:17]
	v_cmp_gt_i32_e32 vcc, s39, v102
	v_add_u32_e32 v96, 0xffff8000, v102
	v_ashrrev_i32_e32 v97, 31, v102
	v_mov_b32_e32 v162, s2
	v_readlane_b32 s2, v254, 38
	s_mov_b64 s[10:11], s[18:19]
	v_cndmask_b32_e32 v97, 0, v97, vcc
	v_cndmask_b32_e32 v96, v96, v102, vcc
	v_mov_b32_e32 v163, s2
	v_mov_b32_e32 v164, s63
	v_mov_b32_e32 v165, s11
	v_mov_b32_e32 v166, s62
	v_mov_b32_e32 v167, s10
	v_min_i32_e32 v102, 0x8000, v102
	v_add_u32_e32 v152, 0x1000, v147
	v_add_u32_e32 v153, 0x1000, v148
	v_add_u32_e32 v154, 0x1200, v147
	v_add_u32_e32 v155, 0x1200, v148
	v_add_u32_e32 v156, 0x1800, v147
	v_add_u32_e32 v157, 0x1800, v148
	v_add_u32_e32 v158, 0x1a00, v147
	v_add_u32_e32 v159, 0x1c00, v148
	v_ashrrev_i32_e32 v129, 31, v128
	v_cndmask_b32_e32 v99, v160, v161, vcc
	v_cndmask_b32_e32 v98, v162, v163, vcc
	v_lshlrev_b64 v[96:97], 12, v[96:97]
	v_cndmask_b32_e32 v101, v164, v165, vcc
	v_cndmask_b32_e32 v100, v166, v167, vcc
	v_ashrrev_i32_e32 v102, 12, v102
	ds_write2_b32 v152, v120, v121 offset0:64 offset1:132
	ds_write2_b32 v153, v104, v105 offset0:96 offset1:164
	ds_write2_b32 v154, v122, v123 offset0:72 offset1:140
	ds_write2_b32 v155, v106, v107 offset0:104 offset1:172
	ds_write2_b32 v156, v124, v125 offset0:96 offset1:164
	ds_write2_b32 v157, v108, v109 offset0:128 offset1:196
	ds_write2_b32 v158, v126, v127 offset0:104 offset1:172
	ds_write2_b32 v159, v110, v111 offset0:8 offset1:76
	v_lshl_add_u64 v[98:99], v[98:99], 0, v[96:97]
	v_lshl_add_u64 v[100:101], v[100:101], 0, v[96:97]
	v_lshlrev_b64 v[96:97], 2, v[128:129]
	v_mul_hi_i32_i24_e32 v103, 0x6000, v102
	v_mul_i32_i24_e32 v102, 0x6000, v102
	s_waitcnt lgkmcnt(0)
	v_lshl_add_u64 v[98:99], v[98:99], 0, v[96:97]
	v_lshl_add_u64 v[102:103], s[0:1], 0, v[102:103]
	v_lshl_add_u64 v[102:103], v[102:103], 0, v[96:97]
	ds_read_b128 v[104:107], v146
	global_load_dwordx4 v[108:111], v[98:99], off
	global_load_dwordx4 v[112:115], v[102:103], off
	v_or_b32_e32 v168, 4, v175
	v_lshl_add_u64 v[100:101], v[100:101], 0, v[96:97]
	v_or_b32_e32 v169, 8, v175
	v_or_b32_e32 v170, 12, v175
	v_or_b32_e32 v171, 16, v175
	v_or_b32_e32 v172, 20, v175
	v_or_b32_e32 v173, 24, v175
	v_or_b32_e32 v174, 28, v175
	v_or_b32_e32 v181, v176, v174
	v_readlane_b32 s2, v254, 11
	s_add_i32 s4, s4, s2
	s_cmp_lt_i32 s4, s26
	s_mov_b64 s[12:13], s[20:21]
	s_mov_b64 s[14:15], s[22:23]
	s_waitcnt vmcnt(0) lgkmcnt(0)
	v_pk_fma_f32 v[104:105], v[104:105], v[112:113], v[108:109]
	v_pk_fma_f32 v[106:107], v[106:107], v[114:115], v[110:111]
	v_or_b32_e32 v110, v176, v168
	global_store_dwordx4 v[100:101], v[104:107], off
	v_cmp_gt_i32_e32 vcc, s39, v110
	s_nop 0
	v_ashrrev_i32_e32 v104, 31, v110
	v_add_u32_e32 v106, 0xffff8000, v110
	v_cndmask_b32_e32 v105, 0, v104, vcc
	v_cndmask_b32_e32 v104, v106, v110, vcc
	v_cndmask_b32_e32 v107, v160, v161, vcc
	v_cndmask_b32_e32 v106, v162, v163, vcc
	v_lshlrev_b64 v[104:105], 12, v[104:105]
	v_cndmask_b32_e32 v109, v164, v165, vcc
	v_cndmask_b32_e32 v108, v166, v167, vcc
	v_lshl_add_u64 v[106:107], v[106:107], 0, v[104:105]
	v_lshl_add_u64 v[104:105], v[108:109], 0, v[104:105]
	v_min_i32_e32 v108, 0x8000, v110
	v_ashrrev_i32_e32 v108, 12, v108
	v_mul_hi_i32_i24_e32 v109, 0x6000, v108
	v_mul_i32_i24_e32 v108, 0x6000, v108
	v_lshl_add_u64 v[106:107], v[106:107], 0, v[96:97]
	v_lshl_add_u64 v[108:109], s[0:1], 0, v[108:109]
	v_lshl_add_u64 v[108:109], v[108:109], 0, v[96:97]
	ds_read_b128 v[110:113], v146 offset:1088
	global_load_dwordx4 v[114:117], v[106:107], off
	global_load_dwordx4 v[118:121], v[108:109], off
	v_lshl_add_u64 v[104:105], v[104:105], 0, v[96:97]
	s_waitcnt vmcnt(0) lgkmcnt(0)
	v_pk_fma_f32 v[110:111], v[110:111], v[118:119], v[114:115]
	v_pk_fma_f32 v[112:113], v[112:113], v[120:121], v[116:117]
	v_or_b32_e32 v118, v176, v169
	global_store_dwordx4 v[104:105], v[110:113], off
	v_cmp_gt_i32_e32 vcc, s39, v118
	s_nop 0
	v_ashrrev_i32_e32 v110, 31, v118
	v_add_u32_e32 v112, 0xffff8000, v118
	v_cndmask_b32_e32 v111, 0, v110, vcc
	v_cndmask_b32_e32 v110, v112, v118, vcc
	v_cndmask_b32_e32 v113, v160, v161, vcc
	v_cndmask_b32_e32 v112, v162, v163, vcc
	v_lshlrev_b64 v[110:111], 12, v[110:111]
	v_lshl_add_u64 v[112:113], v[112:113], 0, v[110:111]
	v_cndmask_b32_e32 v115, v164, v165, vcc
	v_cndmask_b32_e32 v114, v166, v167, vcc
	v_lshl_add_u64 v[116:117], v[114:115], 0, v[110:111]
	v_lshl_add_u64 v[110:111], v[112:113], 0, v[96:97]
	v_min_i32_e32 v112, 0x8000, v118
	v_ashrrev_i32_e32 v112, 12, v112
	v_mul_hi_i32_i24_e32 v113, 0x6000, v112
	v_mul_i32_i24_e32 v112, 0x6000, v112
	v_lshl_add_u64 v[112:113], s[0:1], 0, v[112:113]
	v_lshl_add_u64 v[114:115], v[112:113], 0, v[96:97]
	v_lshl_add_u64 v[112:113], v[116:117], 0, v[96:97]
	ds_read_b128 v[116:119], v146 offset:2176
	global_load_dwordx4 v[120:123], v[110:111], off
	global_load_dwordx4 v[124:127], v[114:115], off
	s_waitcnt vmcnt(0) lgkmcnt(0)
	v_pk_fma_f32 v[116:117], v[116:117], v[124:125], v[120:121]
	v_pk_fma_f32 v[118:119], v[118:119], v[126:127], v[122:123]
	v_or_b32_e32 v124, v176, v170
	global_store_dwordx4 v[112:113], v[116:119], off
	v_cmp_gt_i32_e32 vcc, s39, v124
	s_nop 0
	v_ashrrev_i32_e32 v116, 31, v124
	v_add_u32_e32 v118, 0xffff8000, v124
	v_cndmask_b32_e32 v117, 0, v116, vcc
	v_cndmask_b32_e32 v116, v118, v124, vcc
	v_cndmask_b32_e32 v119, v160, v161, vcc
	v_cndmask_b32_e32 v118, v162, v163, vcc
	v_lshlrev_b64 v[116:117], 12, v[116:117]
	v_lshl_add_u64 v[118:119], v[118:119], 0, v[116:117]
	v_cndmask_b32_e32 v121, v164, v165, vcc
	v_cndmask_b32_e32 v120, v166, v167, vcc
	v_lshl_add_u64 v[122:123], v[120:121], 0, v[116:117]
	v_lshl_add_u64 v[116:117], v[118:119], 0, v[96:97]
	v_min_i32_e32 v118, 0x8000, v124
	v_ashrrev_i32_e32 v118, 12, v118
	v_mul_hi_i32_i24_e32 v119, 0x6000, v118
	v_mul_i32_i24_e32 v118, 0x6000, v118
	v_lshl_add_u64 v[118:119], s[0:1], 0, v[118:119]
	v_lshl_add_u64 v[120:121], v[118:119], 0, v[96:97]
	v_lshl_add_u64 v[118:119], v[122:123], 0, v[96:97]
	ds_read_b128 v[122:125], v146 offset:3264
	global_load_dwordx4 v[126:129], v[116:117], off
	global_load_dwordx4 v[130:133], v[120:121], off
	s_waitcnt vmcnt(0) lgkmcnt(0)
	v_pk_fma_f32 v[122:123], v[122:123], v[130:131], v[126:127]
	v_pk_fma_f32 v[124:125], v[124:125], v[132:133], v[128:129]
	v_or_b32_e32 v130, v176, v171
	global_store_dwordx4 v[118:119], v[122:125], off
	v_cmp_gt_i32_e32 vcc, s39, v130
	s_nop 0
	v_ashrrev_i32_e32 v122, 31, v130
	v_add_u32_e32 v124, 0xffff8000, v130
	v_cndmask_b32_e32 v123, 0, v122, vcc
	v_cndmask_b32_e32 v122, v124, v130, vcc
	v_cndmask_b32_e32 v125, v160, v161, vcc
	v_cndmask_b32_e32 v124, v162, v163, vcc
	v_lshlrev_b64 v[122:123], 12, v[122:123]
	v_lshl_add_u64 v[124:125], v[124:125], 0, v[122:123]
	v_cndmask_b32_e32 v127, v164, v165, vcc
	v_cndmask_b32_e32 v126, v166, v167, vcc
	v_lshl_add_u64 v[128:129], v[126:127], 0, v[122:123]
	v_lshl_add_u64 v[122:123], v[124:125], 0, v[96:97]
	v_min_i32_e32 v124, 0x8000, v130
	v_ashrrev_i32_e32 v124, 12, v124
	v_mul_hi_i32_i24_e32 v125, 0x6000, v124
	v_mul_i32_i24_e32 v124, 0x6000, v124
	v_lshl_add_u64 v[124:125], s[0:1], 0, v[124:125]
	v_lshl_add_u64 v[126:127], v[124:125], 0, v[96:97]
	v_lshl_add_u64 v[124:125], v[128:129], 0, v[96:97]
	ds_read_b128 v[128:131], v146 offset:4352
	global_load_dwordx4 v[132:135], v[122:123], off
	global_load_dwordx4 v[136:139], v[126:127], off
	s_waitcnt vmcnt(0) lgkmcnt(0)
	v_pk_fma_f32 v[128:129], v[128:129], v[136:137], v[132:133]
	v_pk_fma_f32 v[130:131], v[130:131], v[138:139], v[134:135]
	v_or_b32_e32 v136, v176, v172
	global_store_dwordx4 v[124:125], v[128:131], off
	v_cmp_gt_i32_e32 vcc, s39, v136
	s_nop 0
	v_ashrrev_i32_e32 v128, 31, v136
	v_add_u32_e32 v130, 0xffff8000, v136
	v_cndmask_b32_e32 v129, 0, v128, vcc
	v_cndmask_b32_e32 v128, v130, v136, vcc
	v_cndmask_b32_e32 v131, v160, v161, vcc
	v_cndmask_b32_e32 v130, v162, v163, vcc
	v_lshlrev_b64 v[128:129], 12, v[128:129]
	v_lshl_add_u64 v[130:131], v[130:131], 0, v[128:129]
	v_cndmask_b32_e32 v133, v164, v165, vcc
	v_cndmask_b32_e32 v132, v166, v167, vcc
	v_lshl_add_u64 v[134:135], v[132:133], 0, v[128:129]
	v_lshl_add_u64 v[128:129], v[130:131], 0, v[96:97]
	v_min_i32_e32 v130, 0x8000, v136
	v_ashrrev_i32_e32 v130, 12, v130
	v_mul_hi_i32_i24_e32 v131, 0x6000, v130
	v_mul_i32_i24_e32 v130, 0x6000, v130
	v_lshl_add_u64 v[130:131], s[0:1], 0, v[130:131]
	v_lshl_add_u64 v[132:133], v[130:131], 0, v[96:97]
	v_lshl_add_u64 v[130:131], v[134:135], 0, v[96:97]
	ds_read_b128 v[134:137], v146 offset:5440
	global_load_dwordx4 v[138:141], v[128:129], off
	global_load_dwordx4 v[142:145], v[132:133], off
	s_waitcnt vmcnt(0) lgkmcnt(0)
	v_pk_fma_f32 v[134:135], v[134:135], v[142:143], v[138:139]
	v_pk_fma_f32 v[136:137], v[136:137], v[144:145], v[140:141]
	v_or_b32_e32 v142, v176, v173
	global_store_dwordx4 v[130:131], v[134:137], off
	v_cmp_gt_i32_e32 vcc, s39, v142
	s_nop 0
	v_ashrrev_i32_e32 v134, 31, v142
	v_add_u32_e32 v136, 0xffff8000, v142
	v_cndmask_b32_e32 v135, 0, v134, vcc
	v_cndmask_b32_e32 v134, v136, v142, vcc
	v_cndmask_b32_e32 v137, v160, v161, vcc
	v_cndmask_b32_e32 v136, v162, v163, vcc
	v_lshlrev_b64 v[134:135], 12, v[134:135]
	v_lshl_add_u64 v[136:137], v[136:137], 0, v[134:135]
	v_cndmask_b32_e32 v139, v164, v165, vcc
	v_cndmask_b32_e32 v138, v166, v167, vcc
	v_lshl_add_u64 v[140:141], v[138:139], 0, v[134:135]
	v_lshl_add_u64 v[134:135], v[136:137], 0, v[96:97]
	v_min_i32_e32 v136, 0x8000, v142
	v_ashrrev_i32_e32 v136, 12, v136
	v_mul_hi_i32_i24_e32 v137, 0x6000, v136
	v_mul_i32_i24_e32 v136, 0x6000, v136
	v_lshl_add_u64 v[136:137], s[0:1], 0, v[136:137]
	v_lshl_add_u64 v[138:139], v[136:137], 0, v[96:97]
	v_lshl_add_u64 v[136:137], v[140:141], 0, v[96:97]
	ds_read_b128 v[140:143], v146 offset:6528
	global_load_dwordx4 v[184:187], v[134:135], off
	global_load_dwordx4 v[196:199], v[138:139], off
	v_cmp_gt_i32_e32 vcc, s39, v181
	s_waitcnt vmcnt(0) lgkmcnt(0)
	v_pk_fma_f32 v[140:141], v[140:141], v[196:197], v[184:185]
	v_pk_fma_f32 v[142:143], v[142:143], v[198:199], v[186:187]
	global_store_dwordx4 v[136:137], v[140:143], off
	v_cndmask_b32_e32 v145, v164, v165, vcc
	v_cndmask_b32_e32 v144, v166, v167, vcc
	v_ashrrev_i32_e32 v140, 31, v181
	v_add_u32_e32 v142, 0xffff8000, v181
	v_cndmask_b32_e32 v141, 0, v140, vcc
	v_cndmask_b32_e32 v140, v142, v181, vcc
	v_cndmask_b32_e32 v143, v160, v161, vcc
	v_cndmask_b32_e32 v142, v162, v163, vcc
	v_lshlrev_b64 v[140:141], 12, v[140:141]
	v_lshl_add_u64 v[142:143], v[142:143], 0, v[140:141]
	v_lshl_add_u64 v[184:185], v[144:145], 0, v[140:141]
	v_lshl_add_u64 v[140:141], v[142:143], 0, v[96:97]
	v_min_i32_e32 v142, 0x8000, v181
	v_ashrrev_i32_e32 v142, 12, v142
	v_mul_hi_i32_i24_e32 v143, 0x6000, v142
	v_mul_i32_i24_e32 v142, 0x6000, v142
	v_lshl_add_u64 v[142:143], s[0:1], 0, v[142:143]
	v_lshl_add_u64 v[144:145], v[142:143], 0, v[96:97]
	v_lshl_add_u64 v[142:143], v[184:185], 0, v[96:97]
	ds_read_b128 v[184:187], v146 offset:7616
	global_load_dwordx4 v[196:199], v[140:141], off
	global_load_dwordx4 v[200:203], v[144:145], off
	s_waitcnt vmcnt(0) lgkmcnt(0)
	v_pk_fma_f32 v[184:185], v[184:185], v[200:201], v[196:197]
	v_pk_fma_f32 v[186:187], v[186:187], v[202:203], v[198:199]
	global_store_dwordx4 v[142:143], v[184:187], off
	s_waitcnt lgkmcnt(0)
	ds_write2_b32 v147, v80, v81 offset1:68
	ds_write2_b32 v148, v64, v65 offset0:32 offset1:100
	ds_write2_b32 v147, v82, v83 offset0:136 offset1:204
	ds_write2_b32 v148, v66, v67 offset0:168 offset1:236
	ds_write2_b32 v149, v84, v85 offset0:32 offset1:100
	ds_write2_b32 v150, v68, v69 offset0:64 offset1:132
	ds_write2_b32 v149, v86, v87 offset0:168 offset1:236
	ds_write2_b32 v151, v70, v71 offset0:72 offset1:140
	ds_write2_b32 v152, v88, v89 offset0:64 offset1:132
	ds_write2_b32 v153, v72, v73 offset0:96 offset1:164
	ds_write2_b32 v154, v90, v91 offset0:72 offset1:140
	ds_write2_b32 v155, v74, v75 offset0:104 offset1:172
	ds_write2_b32 v156, v92, v93 offset0:96 offset1:164
	ds_write2_b32 v157, v76, v77 offset0:128 offset1:196
	ds_write2_b32 v158, v94, v95 offset0:104 offset1:172
	ds_write2_b32 v159, v78, v79 offset0:8 offset1:76
	s_waitcnt lgkmcnt(0)
	ds_read_b128 v[64:67], v146
	global_load_dwordx4 v[68:71], v[98:99], off offset:256
	global_load_dwordx4 v[72:75], v[102:103], off offset:256
	s_waitcnt vmcnt(0) lgkmcnt(0)
	v_pk_fma_f32 v[64:65], v[64:65], v[72:73], v[68:69]
	v_pk_fma_f32 v[66:67], v[66:67], v[74:75], v[70:71]
	global_store_dwordx4 v[100:101], v[64:67], off offset:256
	ds_read_b128 v[64:67], v146 offset:1088
	global_load_dwordx4 v[68:71], v[106:107], off offset:256
	global_load_dwordx4 v[72:75], v[108:109], off offset:256
	s_waitcnt vmcnt(0) lgkmcnt(0)
	v_pk_fma_f32 v[64:65], v[64:65], v[72:73], v[68:69]
	v_pk_fma_f32 v[66:67], v[66:67], v[74:75], v[70:71]
	global_store_dwordx4 v[104:105], v[64:67], off offset:256
	ds_read_b128 v[64:67], v146 offset:2176
	global_load_dwordx4 v[68:71], v[110:111], off offset:256
	global_load_dwordx4 v[72:75], v[114:115], off offset:256
	s_waitcnt vmcnt(0) lgkmcnt(0)
	v_pk_fma_f32 v[64:65], v[64:65], v[72:73], v[68:69]
	v_pk_fma_f32 v[66:67], v[66:67], v[74:75], v[70:71]
	global_store_dwordx4 v[112:113], v[64:67], off offset:256
	ds_read_b128 v[64:67], v146 offset:3264
	global_load_dwordx4 v[68:71], v[116:117], off offset:256
	global_load_dwordx4 v[72:75], v[120:121], off offset:256
	s_waitcnt vmcnt(0) lgkmcnt(0)
	v_pk_fma_f32 v[64:65], v[64:65], v[72:73], v[68:69]
	v_pk_fma_f32 v[66:67], v[66:67], v[74:75], v[70:71]
	global_store_dwordx4 v[118:119], v[64:67], off offset:256
	ds_read_b128 v[64:67], v146 offset:4352
	global_load_dwordx4 v[68:71], v[122:123], off offset:256
	global_load_dwordx4 v[72:75], v[126:127], off offset:256
	s_waitcnt vmcnt(0) lgkmcnt(0)
	v_pk_fma_f32 v[64:65], v[64:65], v[72:73], v[68:69]
	v_pk_fma_f32 v[66:67], v[66:67], v[74:75], v[70:71]
	global_store_dwordx4 v[124:125], v[64:67], off offset:256
	ds_read_b128 v[64:67], v146 offset:5440
	global_load_dwordx4 v[68:71], v[128:129], off offset:256
	global_load_dwordx4 v[72:75], v[132:133], off offset:256
	s_waitcnt vmcnt(0) lgkmcnt(0)
	v_pk_fma_f32 v[64:65], v[64:65], v[72:73], v[68:69]
	v_pk_fma_f32 v[66:67], v[66:67], v[74:75], v[70:71]
	global_store_dwordx4 v[130:131], v[64:67], off offset:256
	ds_read_b128 v[64:67], v146 offset:6528
	global_load_dwordx4 v[68:71], v[134:135], off offset:256
	global_load_dwordx4 v[72:75], v[138:139], off offset:256
	s_waitcnt vmcnt(0) lgkmcnt(0)
	v_pk_fma_f32 v[64:65], v[64:65], v[72:73], v[68:69]
	v_pk_fma_f32 v[66:67], v[66:67], v[74:75], v[70:71]
	global_store_dwordx4 v[136:137], v[64:67], off offset:256
	ds_read_b128 v[64:67], v146 offset:7616
	global_load_dwordx4 v[68:71], v[140:141], off offset:256
	global_load_dwordx4 v[72:75], v[144:145], off offset:256
	s_waitcnt vmcnt(0) lgkmcnt(0)
	v_pk_fma_f32 v[64:65], v[64:65], v[72:73], v[68:69]
	v_pk_fma_f32 v[66:67], v[66:67], v[74:75], v[70:71]
	global_store_dwordx4 v[142:143], v[64:67], off offset:256
	v_or_b32_e32 v74, 32, v176
	s_waitcnt lgkmcnt(0)
	ds_write2_b32 v147, v48, v49 offset1:68
	ds_write2_b32 v148, v32, v33 offset0:32 offset1:100
	ds_write2_b32 v147, v50, v51 offset0:136 offset1:204
	ds_write2_b32 v148, v34, v35 offset0:168 offset1:236
	ds_write2_b32 v149, v52, v53 offset0:32 offset1:100
	ds_write2_b32 v150, v36, v37 offset0:64 offset1:132
	ds_write2_b32 v149, v54, v55 offset0:168 offset1:236
	ds_write2_b32 v151, v38, v39 offset0:72 offset1:140
	ds_write2_b32 v152, v56, v57 offset0:64 offset1:132
	ds_write2_b32 v153, v40, v41 offset0:96 offset1:164
	ds_write2_b32 v154, v58, v59 offset0:72 offset1:140
	ds_write2_b32 v155, v42, v43 offset0:104 offset1:172
	ds_write2_b32 v156, v60, v61 offset0:96 offset1:164
	ds_write2_b32 v157, v44, v45 offset0:128 offset1:196
	ds_write2_b32 v158, v62, v63 offset0:104 offset1:172
	ds_write2_b32 v159, v46, v47 offset0:8 offset1:76
	v_or_b32_e32 v40, v74, v175
	v_cmp_gt_i32_e32 vcc, s39, v40
	v_ashrrev_i32_e32 v32, 31, v40
	v_add_u32_e32 v34, 0xffff8000, v40
	v_cndmask_b32_e32 v33, 0, v32, vcc
	v_cndmask_b32_e32 v32, v34, v40, vcc
	v_cndmask_b32_e32 v35, v160, v161, vcc
	v_cndmask_b32_e32 v34, v162, v163, vcc
	v_lshlrev_b64 v[32:33], 12, v[32:33]
	v_lshl_add_u64 v[34:35], v[34:35], 0, v[32:33]
	v_cndmask_b32_e32 v37, v164, v165, vcc
	v_cndmask_b32_e32 v36, v166, v167, vcc
	v_lshl_add_u64 v[38:39], v[36:37], 0, v[32:33]
	v_lshl_add_u64 v[32:33], v[34:35], 0, v[96:97]
	v_min_i32_e32 v34, 0x8000, v40
	v_ashrrev_i32_e32 v34, 12, v34
	v_mul_hi_i32_i24_e32 v35, 0x6000, v34
	v_mul_i32_i24_e32 v34, 0x6000, v34
	s_waitcnt lgkmcnt(0)
	v_lshl_add_u64 v[34:35], s[0:1], 0, v[34:35]
	v_lshl_add_u64 v[36:37], v[34:35], 0, v[96:97]
	v_lshl_add_u64 v[34:35], v[38:39], 0, v[96:97]
	ds_read_b128 v[38:41], v146
	global_load_dwordx4 v[42:45], v[32:33], off
	global_load_dwordx4 v[46:49], v[36:37], off
	v_or_b32_e32 v75, v74, v173
	s_waitcnt vmcnt(0) lgkmcnt(0)
	v_pk_fma_f32 v[38:39], v[38:39], v[46:47], v[42:43]
	v_pk_fma_f32 v[40:41], v[40:41], v[48:49], v[44:45]
	v_or_b32_e32 v46, v74, v168
	global_store_dwordx4 v[34:35], v[38:41], off
	v_cmp_gt_i32_e32 vcc, s39, v46
	s_nop 0
	v_ashrrev_i32_e32 v38, 31, v46
	v_add_u32_e32 v40, 0xffff8000, v46
	v_cndmask_b32_e32 v39, 0, v38, vcc
	v_cndmask_b32_e32 v38, v40, v46, vcc
	v_cndmask_b32_e32 v41, v160, v161, vcc
	v_cndmask_b32_e32 v40, v162, v163, vcc
	v_lshlrev_b64 v[38:39], 12, v[38:39]
	v_lshl_add_u64 v[40:41], v[40:41], 0, v[38:39]
	v_cndmask_b32_e32 v43, v164, v165, vcc
	v_cndmask_b32_e32 v42, v166, v167, vcc
	v_lshl_add_u64 v[44:45], v[42:43], 0, v[38:39]
	v_lshl_add_u64 v[38:39], v[40:41], 0, v[96:97]
	v_min_i32_e32 v40, 0x8000, v46
	v_ashrrev_i32_e32 v40, 12, v40
	v_mul_hi_i32_i24_e32 v41, 0x6000, v40
	v_mul_i32_i24_e32 v40, 0x6000, v40
	v_lshl_add_u64 v[40:41], s[0:1], 0, v[40:41]
	v_lshl_add_u64 v[42:43], v[40:41], 0, v[96:97]
	v_lshl_add_u64 v[40:41], v[44:45], 0, v[96:97]
	ds_read_b128 v[44:47], v146 offset:1088
	global_load_dwordx4 v[48:51], v[38:39], off
	global_load_dwordx4 v[52:55], v[42:43], off
	s_waitcnt vmcnt(0) lgkmcnt(0)
	v_pk_fma_f32 v[44:45], v[44:45], v[52:53], v[48:49]
	v_pk_fma_f32 v[46:47], v[46:47], v[54:55], v[50:51]
	v_or_b32_e32 v52, v74, v169
	global_store_dwordx4 v[40:41], v[44:47], off
	v_cmp_gt_i32_e32 vcc, s39, v52
	s_nop 0
	v_ashrrev_i32_e32 v44, 31, v52
	v_add_u32_e32 v46, 0xffff8000, v52
	v_cndmask_b32_e32 v45, 0, v44, vcc
	v_cndmask_b32_e32 v44, v46, v52, vcc
	v_cndmask_b32_e32 v47, v160, v161, vcc
	v_cndmask_b32_e32 v46, v162, v163, vcc
	v_lshlrev_b64 v[44:45], 12, v[44:45]
	v_lshl_add_u64 v[46:47], v[46:47], 0, v[44:45]
	v_cndmask_b32_e32 v49, v164, v165, vcc
	v_cndmask_b32_e32 v48, v166, v167, vcc
	v_lshl_add_u64 v[50:51], v[48:49], 0, v[44:45]
	v_lshl_add_u64 v[44:45], v[46:47], 0, v[96:97]
	v_min_i32_e32 v46, 0x8000, v52
	v_ashrrev_i32_e32 v46, 12, v46
	v_mul_hi_i32_i24_e32 v47, 0x6000, v46
	v_mul_i32_i24_e32 v46, 0x6000, v46
	v_lshl_add_u64 v[46:47], s[0:1], 0, v[46:47]
	v_lshl_add_u64 v[48:49], v[46:47], 0, v[96:97]
	v_lshl_add_u64 v[46:47], v[50:51], 0, v[96:97]
	ds_read_b128 v[50:53], v146 offset:2176
	global_load_dwordx4 v[54:57], v[44:45], off
	global_load_dwordx4 v[58:61], v[48:49], off
	s_waitcnt vmcnt(0) lgkmcnt(0)
	v_pk_fma_f32 v[50:51], v[50:51], v[58:59], v[54:55]
	v_pk_fma_f32 v[52:53], v[52:53], v[60:61], v[56:57]
	v_or_b32_e32 v58, v74, v170
	global_store_dwordx4 v[46:47], v[50:53], off
	v_cmp_gt_i32_e32 vcc, s39, v58
	s_nop 0
	v_ashrrev_i32_e32 v50, 31, v58
	v_add_u32_e32 v52, 0xffff8000, v58
	v_cndmask_b32_e32 v51, 0, v50, vcc
	v_cndmask_b32_e32 v50, v52, v58, vcc
	v_cndmask_b32_e32 v53, v160, v161, vcc
	v_cndmask_b32_e32 v52, v162, v163, vcc
	v_lshlrev_b64 v[50:51], 12, v[50:51]
	v_lshl_add_u64 v[52:53], v[52:53], 0, v[50:51]
	v_cndmask_b32_e32 v55, v164, v165, vcc
	v_cndmask_b32_e32 v54, v166, v167, vcc
	v_lshl_add_u64 v[56:57], v[54:55], 0, v[50:51]
	v_lshl_add_u64 v[50:51], v[52:53], 0, v[96:97]
	v_min_i32_e32 v52, 0x8000, v58
	v_ashrrev_i32_e32 v52, 12, v52
	v_mul_hi_i32_i24_e32 v53, 0x6000, v52
	v_mul_i32_i24_e32 v52, 0x6000, v52
	v_lshl_add_u64 v[52:53], s[0:1], 0, v[52:53]
	v_lshl_add_u64 v[54:55], v[52:53], 0, v[96:97]
	v_lshl_add_u64 v[52:53], v[56:57], 0, v[96:97]
	ds_read_b128 v[56:59], v146 offset:3264
	global_load_dwordx4 v[60:63], v[50:51], off
	global_load_dwordx4 v[64:67], v[54:55], off
	s_waitcnt vmcnt(0) lgkmcnt(0)
	v_pk_fma_f32 v[56:57], v[56:57], v[64:65], v[60:61]
	v_pk_fma_f32 v[58:59], v[58:59], v[66:67], v[62:63]
	v_or_b32_e32 v64, v74, v171
	global_store_dwordx4 v[52:53], v[56:59], off
	v_cmp_gt_i32_e32 vcc, s39, v64
	s_nop 0
	v_ashrrev_i32_e32 v56, 31, v64
	v_add_u32_e32 v58, 0xffff8000, v64
	v_cndmask_b32_e32 v57, 0, v56, vcc
	v_cndmask_b32_e32 v56, v58, v64, vcc
	v_cndmask_b32_e32 v59, v160, v161, vcc
	v_cndmask_b32_e32 v58, v162, v163, vcc
	v_lshlrev_b64 v[56:57], 12, v[56:57]
	v_lshl_add_u64 v[58:59], v[58:59], 0, v[56:57]
	v_cndmask_b32_e32 v61, v164, v165, vcc
	v_cndmask_b32_e32 v60, v166, v167, vcc
	v_lshl_add_u64 v[62:63], v[60:61], 0, v[56:57]
	v_lshl_add_u64 v[56:57], v[58:59], 0, v[96:97]
	v_min_i32_e32 v58, 0x8000, v64
	v_ashrrev_i32_e32 v58, 12, v58
	v_mul_hi_i32_i24_e32 v59, 0x6000, v58
	v_mul_i32_i24_e32 v58, 0x6000, v58
	v_lshl_add_u64 v[58:59], s[0:1], 0, v[58:59]
	v_lshl_add_u64 v[60:61], v[58:59], 0, v[96:97]
	v_lshl_add_u64 v[58:59], v[62:63], 0, v[96:97]
	ds_read_b128 v[62:65], v146 offset:4352
	global_load_dwordx4 v[66:69], v[56:57], off
	global_load_dwordx4 v[70:73], v[60:61], off
	s_waitcnt vmcnt(0) lgkmcnt(0)
	v_pk_fma_f32 v[62:63], v[62:63], v[70:71], v[66:67]
	v_pk_fma_f32 v[64:65], v[64:65], v[72:73], v[68:69]
	v_or_b32_e32 v70, v74, v172
	global_store_dwordx4 v[58:59], v[62:65], off
	v_cmp_gt_i32_e32 vcc, s39, v70
	s_nop 0
	v_ashrrev_i32_e32 v62, 31, v70
	v_add_u32_e32 v64, 0xffff8000, v70
	v_cndmask_b32_e32 v63, 0, v62, vcc
	v_cndmask_b32_e32 v62, v64, v70, vcc
	v_cndmask_b32_e32 v65, v160, v161, vcc
	v_cndmask_b32_e32 v64, v162, v163, vcc
	v_lshlrev_b64 v[62:63], 12, v[62:63]
	v_lshl_add_u64 v[64:65], v[64:65], 0, v[62:63]
	v_cndmask_b32_e32 v67, v164, v165, vcc
	v_cndmask_b32_e32 v66, v166, v167, vcc
	v_lshl_add_u64 v[68:69], v[66:67], 0, v[62:63]
	v_lshl_add_u64 v[62:63], v[64:65], 0, v[96:97]
	v_min_i32_e32 v64, 0x8000, v70
	v_ashrrev_i32_e32 v64, 12, v64
	v_mul_hi_i32_i24_e32 v65, 0x6000, v64
	v_mul_i32_i24_e32 v64, 0x6000, v64
	v_lshl_add_u64 v[64:65], s[0:1], 0, v[64:65]
	v_lshl_add_u64 v[66:67], v[64:65], 0, v[96:97]
	v_lshl_add_u64 v[64:65], v[68:69], 0, v[96:97]
	ds_read_b128 v[68:71], v146 offset:5440
	global_load_dwordx4 v[76:79], v[62:63], off
	global_load_dwordx4 v[80:83], v[66:67], off
	v_cmp_gt_i32_e32 vcc, s39, v75
	s_waitcnt vmcnt(0) lgkmcnt(0)
	v_pk_fma_f32 v[68:69], v[68:69], v[80:81], v[76:77]
	v_pk_fma_f32 v[70:71], v[70:71], v[82:83], v[78:79]
	global_store_dwordx4 v[64:65], v[68:71], off
	v_cndmask_b32_e32 v73, v164, v165, vcc
	v_cndmask_b32_e32 v72, v166, v167, vcc
	v_ashrrev_i32_e32 v68, 31, v75
	v_add_u32_e32 v70, 0xffff8000, v75
	v_cndmask_b32_e32 v69, 0, v68, vcc
	v_cndmask_b32_e32 v68, v70, v75, vcc
	v_cndmask_b32_e32 v71, v160, v161, vcc
	v_cndmask_b32_e32 v70, v162, v163, vcc
	v_lshlrev_b64 v[68:69], 12, v[68:69]
	v_lshl_add_u64 v[70:71], v[70:71], 0, v[68:69]
	v_lshl_add_u64 v[76:77], v[72:73], 0, v[68:69]
	v_lshl_add_u64 v[68:69], v[70:71], 0, v[96:97]
	v_min_i32_e32 v70, 0x8000, v75
	v_ashrrev_i32_e32 v70, 12, v70
	v_mul_hi_i32_i24_e32 v71, 0x6000, v70
	v_mul_i32_i24_e32 v70, 0x6000, v70
	v_lshl_add_u64 v[70:71], s[0:1], 0, v[70:71]
	v_lshl_add_u64 v[72:73], v[70:71], 0, v[96:97]
	v_lshl_add_u64 v[70:71], v[76:77], 0, v[96:97]
	ds_read_b128 v[76:79], v146 offset:6528
	global_load_dwordx4 v[80:83], v[68:69], off
	global_load_dwordx4 v[84:87], v[72:73], off
	s_waitcnt vmcnt(0) lgkmcnt(0)
	v_pk_fma_f32 v[76:77], v[76:77], v[84:85], v[80:81]
	v_pk_fma_f32 v[78:79], v[78:79], v[86:87], v[82:83]
	v_or_b32_e32 v82, v74, v174
	global_store_dwordx4 v[70:71], v[76:79], off
	v_cmp_gt_i32_e32 vcc, s39, v82
	v_ashrrev_i32_e32 v74, 31, v82
	v_add_u32_e32 v76, 0xffff8000, v82
	v_cndmask_b32_e32 v75, 0, v74, vcc
	v_cndmask_b32_e32 v74, v76, v82, vcc
	v_cndmask_b32_e32 v77, v160, v161, vcc
	v_cndmask_b32_e32 v76, v162, v163, vcc
	v_lshlrev_b64 v[74:75], 12, v[74:75]
	v_lshl_add_u64 v[76:77], v[76:77], 0, v[74:75]
	v_cndmask_b32_e32 v79, v164, v165, vcc
	v_cndmask_b32_e32 v78, v166, v167, vcc
	v_lshl_add_u64 v[80:81], v[78:79], 0, v[74:75]
	v_lshl_add_u64 v[74:75], v[76:77], 0, v[96:97]
	v_min_i32_e32 v76, 0x8000, v82
	v_ashrrev_i32_e32 v76, 12, v76
	v_mul_hi_i32_i24_e32 v77, 0x6000, v76
	v_mul_i32_i24_e32 v76, 0x6000, v76
	v_lshl_add_u64 v[76:77], s[0:1], 0, v[76:77]
	v_lshl_add_u64 v[78:79], v[76:77], 0, v[96:97]
	v_lshl_add_u64 v[76:77], v[80:81], 0, v[96:97]
	ds_read_b128 v[80:83], v146 offset:7616
	global_load_dwordx4 v[84:87], v[74:75], off
	global_load_dwordx4 v[88:91], v[78:79], off
	s_waitcnt vmcnt(0) lgkmcnt(0)
	v_pk_fma_f32 v[80:81], v[80:81], v[88:89], v[84:85]
	v_pk_fma_f32 v[82:83], v[82:83], v[90:91], v[86:87]
	global_store_dwordx4 v[76:77], v[80:83], off
	s_waitcnt lgkmcnt(0)
	ds_write2_b32 v147, v16, v17 offset1:68
	ds_write2_b32 v148, v0, v1 offset0:32 offset1:100
	ds_write2_b32 v147, v18, v19 offset0:136 offset1:204
	ds_write2_b32 v148, v2, v3 offset0:168 offset1:236
	ds_write2_b32 v149, v20, v21 offset0:32 offset1:100
	ds_write2_b32 v150, v4, v5 offset0:64 offset1:132
	ds_write2_b32 v149, v22, v23 offset0:168 offset1:236
	ds_write2_b32 v151, v6, v7 offset0:72 offset1:140
	ds_write2_b32 v152, v24, v25 offset0:64 offset1:132
	ds_write2_b32 v153, v8, v9 offset0:96 offset1:164
	ds_write2_b32 v154, v26, v27 offset0:72 offset1:140
	ds_write2_b32 v155, v10, v11 offset0:104 offset1:172
	ds_write2_b32 v156, v28, v29 offset0:96 offset1:164
	ds_write2_b32 v157, v12, v13 offset0:128 offset1:196
	ds_write2_b32 v158, v30, v31 offset0:104 offset1:172
	ds_write2_b32 v159, v14, v15 offset0:8 offset1:76
	s_waitcnt lgkmcnt(0)
	ds_read_b128 v[0:3], v146
	global_load_dwordx4 v[4:7], v[32:33], off offset:256
	global_load_dwordx4 v[8:11], v[36:37], off offset:256
	s_waitcnt vmcnt(0) lgkmcnt(0)
	v_pk_fma_f32 v[0:1], v[0:1], v[8:9], v[4:5]
	v_pk_fma_f32 v[2:3], v[2:3], v[10:11], v[6:7]
	global_store_dwordx4 v[34:35], v[0:3], off offset:256
	ds_read_b128 v[0:3], v146 offset:1088
	global_load_dwordx4 v[4:7], v[38:39], off offset:256
	global_load_dwordx4 v[8:11], v[42:43], off offset:256
	s_waitcnt vmcnt(0) lgkmcnt(0)
	v_pk_fma_f32 v[0:1], v[0:1], v[8:9], v[4:5]
	v_pk_fma_f32 v[2:3], v[2:3], v[10:11], v[6:7]
	global_store_dwordx4 v[40:41], v[0:3], off offset:256
	ds_read_b128 v[0:3], v146 offset:2176
	global_load_dwordx4 v[4:7], v[44:45], off offset:256
	global_load_dwordx4 v[8:11], v[48:49], off offset:256
	s_waitcnt vmcnt(0) lgkmcnt(0)
	v_pk_fma_f32 v[0:1], v[0:1], v[8:9], v[4:5]
	v_pk_fma_f32 v[2:3], v[2:3], v[10:11], v[6:7]
	global_store_dwordx4 v[46:47], v[0:3], off offset:256
	ds_read_b128 v[0:3], v146 offset:3264
	global_load_dwordx4 v[4:7], v[50:51], off offset:256
	global_load_dwordx4 v[8:11], v[54:55], off offset:256
	s_waitcnt vmcnt(0) lgkmcnt(0)
	v_pk_fma_f32 v[0:1], v[0:1], v[8:9], v[4:5]
	v_pk_fma_f32 v[2:3], v[2:3], v[10:11], v[6:7]
	global_store_dwordx4 v[52:53], v[0:3], off offset:256
	ds_read_b128 v[0:3], v146 offset:4352
	global_load_dwordx4 v[4:7], v[56:57], off offset:256
	global_load_dwordx4 v[8:11], v[60:61], off offset:256
	s_waitcnt vmcnt(0) lgkmcnt(0)
	v_pk_fma_f32 v[0:1], v[0:1], v[8:9], v[4:5]
	v_pk_fma_f32 v[2:3], v[2:3], v[10:11], v[6:7]
	global_store_dwordx4 v[58:59], v[0:3], off offset:256
	ds_read_b128 v[0:3], v146 offset:5440
	global_load_dwordx4 v[4:7], v[62:63], off offset:256
	global_load_dwordx4 v[8:11], v[66:67], off offset:256
	s_waitcnt vmcnt(0) lgkmcnt(0)
	v_pk_fma_f32 v[0:1], v[0:1], v[8:9], v[4:5]
	v_pk_fma_f32 v[2:3], v[2:3], v[10:11], v[6:7]
	global_store_dwordx4 v[64:65], v[0:3], off offset:256
	ds_read_b128 v[0:3], v146 offset:6528
	global_load_dwordx4 v[4:7], v[68:69], off offset:256
	global_load_dwordx4 v[8:11], v[72:73], off offset:256
	s_waitcnt vmcnt(0) lgkmcnt(0)
	v_pk_fma_f32 v[0:1], v[0:1], v[8:9], v[4:5]
	v_pk_fma_f32 v[2:3], v[2:3], v[10:11], v[6:7]
	global_store_dwordx4 v[70:71], v[0:3], off offset:256
	ds_read_b128 v[0:3], v146 offset:7616
	global_load_dwordx4 v[4:7], v[74:75], off offset:256
	global_load_dwordx4 v[8:11], v[78:79], off offset:256
	s_waitcnt vmcnt(0) lgkmcnt(0)
	v_pk_fma_f32 v[0:1], v[0:1], v[8:9], v[4:5]
	v_pk_fma_f32 v[2:3], v[2:3], v[10:11], v[6:7]
	global_store_dwordx4 v[76:77], v[0:3], off offset:256
	s_waitcnt lgkmcnt(0)
	s_barrier
	s_cbranch_scc1 .LBB0_923

.LBB0_1031:
	s_mul_hi_i32 s0, s2, 0x2e8ba2e9
	s_lshr_b32 s1, s0, 31
	s_ashr_i32 s0, s0, 6
	s_add_i32 s0, s0, s1
	s_lshl_b32 s1, s0, 3
	s_sub_i32 s7, s25, s1
	s_min_i32 s7, s7, 8
	s_abs_i32 s8, s7
	v_cvt_f32_u32_e32 v0, s8
	s_sub_i32 s11, 0, s8
	s_mulk_i32 s0, 0xfea0
	s_add_i32 s9, s0, s2
	v_rcp_iflag_f32_e32 v0, v0
	s_abs_i32 s0, s9
	s_xor_b32 s10, s9, s7
	s_ashr_i32 s10, s10, 31
	v_mul_f32_e32 v0, 0x4f7ffffe, v0
	v_cvt_u32_f32_e32 v0, v0
	v_mov_b32_e32 v237, v179
	v_readfirstlane_b32 s12, v0
	s_mul_i32 s11, s11, s12
	s_mul_hi_u32 s11, s12, s11
	s_add_i32 s12, s12, s11
	s_mul_hi_u32 s11, s0, s12
	s_mul_i32 s12, s11, s8
	s_sub_i32 s0, s0, s12
	s_add_i32 s13, s11, 1
	s_sub_i32 s12, s0, s8
	s_cmp_ge_u32 s0, s8
	s_cselect_b32 s11, s13, s11
	s_cselect_b32 s0, s12, s0
	s_add_i32 s12, s11, 1
	s_cmp_ge_u32 s0, s8
	s_cselect_b32 s0, s12, s11
	s_xor_b32 s0, s0, s10
	s_sub_i32 s0, s0, s10
	s_mul_i32 s7, s7, s0
	s_sub_i32 s7, s9, s7
	s_add_i32 s1, s1, s6
	v_ashrrev_i32_e32 v238, 6, v237
	s_add_i32 s7, s1, s7
	v_lshlrev_b32_e32 v0, 1, v238
	v_lshl_add_u32 v0, s7, 3, v0
	v_ashrrev_i32_e32 v1, 31, v0
	v_bfe_u32 v183, v237, 5, 1
	v_lshlrev_b64 v[0:1], 16, v[0:1]
	v_and_b32_e32 v239, 31, v237
	v_lshl_add_u64 v[0:1], s[64:65], 0, v[0:1]
	v_lshlrev_b32_e32 v176, 9, v183
	s_ashr_i32 s1, s0, 31
	v_lshl_add_u64 v[0:1], v[0:1], 0, v[176:177]
	v_lshlrev_b32_e32 v176, 4, v239
	v_ashrrev_i32_e32 v38, 2, v237
	s_lshl_b64 s[8:9], s[0:1], 18
	v_lshl_add_u64 v[184:185], v[0:1], 0, v[176:177]
	s_add_u32 s8, s4, s8
	v_lshlrev_b32_e32 v0, 5, v38
	v_lshlrev_b32_e32 v2, 3, v237
	s_addc_u32 s9, s5, s9
	v_ashrrev_i32_e32 v1, 31, v0
	v_and_b32_e32 v181, 24, v2
	v_lshl_add_u64 v[0:1], v[0:1], 1, s[8:9]
	v_lshlrev_b32_e32 v176, 1, v181
	v_lshl_add_u64 v[186:187], v[0:1], 0, v[176:177]
	s_movk_i32 s1, 0x2000
	v_add_co_u32_e32 v34, vcc, s1, v186
	v_mul_u32_u24_e32 v36, 40, v239
	s_nop 0
	v_addc_co_u32_e32 v35, vcc, 0, v187, vcc
	v_lshlrev_b32_e32 v37, 4, v183
	v_lshl_add_u32 v241, v36, 1, v37
	v_add_co_u32_e32 v36, vcc, s41, v184
	s_movk_i32 s8, 0x50
	s_nop 0
	v_addc_co_u32_e32 v37, vcc, 0, v185, vcc
	v_mad_u64_u32 v[188:189], s[8:9], v38, s8, v[176:177]
	v_and_b32_e32 v240, 63, v237
	v_bfe_u32 v247, v237, 4, 2
	v_lshlrev_b32_e32 v247, 1, v247
	v_mov_b32_e32 v176, 0x78
	v_lshrrev_b32_e32 v247, v247, v176
	v_and_b32_e32 v247, 3, v247
	v_and_b32_e32 v246, 3, v237
	v_xor_b32_e32 v247, v247, v246
	v_lshlrev_b32_e32 v247, 4, v247
	v_and_b32_e32 v188, 0xffffffcf, v186
	v_or_b32_e32 v188, v188, v247
	v_mov_b32_e32 v189, v187
	v_lshrrev_b32_e32 v176, 6, v237
	v_lshlrev_b32_e32 v247, 11, v176
	v_lshlrev_b32_e32 v176, 10, v176
	v_lshl_add_u64 v[188:189], v[188:189], 0, v[176:177]
	v_readfirstlane_b32 vcc_lo, v247
	v_bfe_u32 v247, v237, 4, 1
	v_lshlrev_b32_e32 v176, 9, v183
	v_lshl_add_u32 v176, v247, 8, v176
	v_lshl_add_u64 v[184:185], v[184:185], 0, v[176:177]
	v_mov_b32_e32 v176, s41
	v_lshl_add_u64 v[186:187], v[184:185], 0, v[176:177]
	v_mov_b32_e32 v176, 0x78
	v_bfe_u32 v247, v237, 2, 2
	v_lshlrev_b32_e32 v247, 1, v247
	v_lshrrev_b32_e32 v247, v247, v176
	v_and_b32_e32 v247, 3, v247
	v_bfe_u32 v246, v237, 4, 2
	v_xor_b32_e32 v247, v247, v246
	v_lshlrev_b32_e32 v247, 4, v247
	v_and_b32_e32 v246, 15, v237
	v_lshl_add_u32 v246, v246, 6, v247
	s_mov_b32 s96, 0
	s_mov_b32 m0, vcc_lo
	v_lshl_add_u64 v[160:161], v[188:189], 0, s[96:97]
	global_load_lds_dwordx4 v[160:161], off
	global_load_lds_dwordx4 v[160:161], off offset:1024
	s_mov_b32 s96, 0
	v_lshl_add_u64 v[248:249], v[184:185], 0, s[96:97]
	v_lshl_add_u64 v[250:251], v[186:187], 0, s[96:97]
	global_load_dwordx4 v[128:131], v[248:249], off
	global_load_dwordx4 v[132:135], v[248:249], off offset:256
	global_load_dwordx4 v[136:139], v[250:251], off
	global_load_dwordx4 v[140:143], v[250:251], off offset:256
	s_movk_i32 s96, 0x2000
	s_add_i32 m0, vcc_lo, 8192
	v_lshl_add_u64 v[160:161], v[188:189], 0, s[96:97]
	global_load_lds_dwordx4 v[160:161], off
	global_load_lds_dwordx4 v[160:161], off offset:1024
	s_movk_i32 s96, 0x800
	v_lshl_add_u64 v[248:249], v[184:185], 0, s[96:97]
	v_lshl_add_u64 v[250:251], v[186:187], 0, s[96:97]
	global_load_dwordx4 v[144:147], v[248:249], off
	global_load_dwordx4 v[148:151], v[248:249], off offset:256
	global_load_dwordx4 v[152:155], v[250:251], off
	global_load_dwordx4 v[156:159], v[250:251], off offset:256
	v_mov_b32_e32 v0, 0
	v_mov_b32_e32 v1, 0
	v_mov_b32_e32 v2, 0
	v_mov_b32_e32 v3, 0
	v_mov_b32_e32 v4, 0
	v_mov_b32_e32 v5, 0
	v_mov_b32_e32 v6, 0
	v_mov_b32_e32 v7, 0
	v_mov_b32_e32 v8, 0
	v_mov_b32_e32 v9, 0
	v_mov_b32_e32 v10, 0
	v_mov_b32_e32 v11, 0
	v_mov_b32_e32 v12, 0
	v_mov_b32_e32 v13, 0
	v_mov_b32_e32 v14, 0
	v_mov_b32_e32 v15, 0
	v_mov_b32_e32 v16, 0
	v_mov_b32_e32 v17, 0
	v_mov_b32_e32 v18, 0
	v_mov_b32_e32 v19, 0
	v_mov_b32_e32 v20, 0
	v_mov_b32_e32 v21, 0
	v_mov_b32_e32 v22, 0
	v_mov_b32_e32 v23, 0
	v_mov_b32_e32 v24, 0
	v_mov_b32_e32 v25, 0
	v_mov_b32_e32 v26, 0
	v_mov_b32_e32 v27, 0
	v_mov_b32_e32 v28, 0
	v_mov_b32_e32 v29, 0
	v_mov_b32_e32 v30, 0
	v_mov_b32_e32 v31, 0
	v_mov_b32_e32 v32, 0
	v_mov_b32_e32 v33, 0
	v_mov_b32_e32 v34, 0
	v_mov_b32_e32 v35, 0
	v_mov_b32_e32 v36, 0
	v_mov_b32_e32 v37, 0
	v_mov_b32_e32 v38, 0
	v_mov_b32_e32 v39, 0
	v_mov_b32_e32 v40, 0
	v_mov_b32_e32 v41, 0
	v_mov_b32_e32 v42, 0
	v_mov_b32_e32 v43, 0
	v_mov_b32_e32 v44, 0
	v_mov_b32_e32 v45, 0
	v_mov_b32_e32 v46, 0
	v_mov_b32_e32 v47, 0
	v_mov_b32_e32 v48, 0
	v_mov_b32_e32 v49, 0
	v_mov_b32_e32 v50, 0
	v_mov_b32_e32 v51, 0
	v_mov_b32_e32 v52, 0
	v_mov_b32_e32 v53, 0
	v_mov_b32_e32 v54, 0
	v_mov_b32_e32 v55, 0
	v_mov_b32_e32 v56, 0
	v_mov_b32_e32 v57, 0
	v_mov_b32_e32 v58, 0
	v_mov_b32_e32 v59, 0
	v_mov_b32_e32 v60, 0
	v_mov_b32_e32 v61, 0
	v_mov_b32_e32 v62, 0
	v_mov_b32_e32 v63, 0
	v_mov_b32_e32 v64, 0
	v_mov_b32_e32 v65, 0
	v_mov_b32_e32 v66, 0
	v_mov_b32_e32 v67, 0
	v_mov_b32_e32 v68, 0
	v_mov_b32_e32 v69, 0
	v_mov_b32_e32 v70, 0
	v_mov_b32_e32 v71, 0
	v_mov_b32_e32 v72, 0
	v_mov_b32_e32 v73, 0
	v_mov_b32_e32 v74, 0
	v_mov_b32_e32 v75, 0
	v_mov_b32_e32 v76, 0
	v_mov_b32_e32 v77, 0
	v_mov_b32_e32 v78, 0
	v_mov_b32_e32 v79, 0
	v_mov_b32_e32 v80, 0
	v_mov_b32_e32 v81, 0
	v_mov_b32_e32 v82, 0
	v_mov_b32_e32 v83, 0
	v_mov_b32_e32 v84, 0
	v_mov_b32_e32 v85, 0
	v_mov_b32_e32 v86, 0
	v_mov_b32_e32 v87, 0
	v_mov_b32_e32 v88, 0
	v_mov_b32_e32 v89, 0
	v_mov_b32_e32 v90, 0
	v_mov_b32_e32 v91, 0
	v_mov_b32_e32 v92, 0
	v_mov_b32_e32 v93, 0
	v_mov_b32_e32 v94, 0
	v_mov_b32_e32 v95, 0
	v_mov_b32_e32 v96, 0
	v_mov_b32_e32 v97, 0
	v_mov_b32_e32 v98, 0
	v_mov_b32_e32 v99, 0
	v_mov_b32_e32 v100, 0
	v_mov_b32_e32 v101, 0
	v_mov_b32_e32 v102, 0
	v_mov_b32_e32 v103, 0
	v_mov_b32_e32 v104, 0
	v_mov_b32_e32 v105, 0
	v_mov_b32_e32 v106, 0
	v_mov_b32_e32 v107, 0
	v_mov_b32_e32 v108, 0
	v_mov_b32_e32 v109, 0
	v_mov_b32_e32 v110, 0
	v_mov_b32_e32 v111, 0
	v_mov_b32_e32 v112, 0
	v_mov_b32_e32 v113, 0
	v_mov_b32_e32 v114, 0
	v_mov_b32_e32 v115, 0
	v_mov_b32_e32 v116, 0
	v_mov_b32_e32 v117, 0
	v_mov_b32_e32 v118, 0
	v_mov_b32_e32 v119, 0
	v_mov_b32_e32 v120, 0
	v_mov_b32_e32 v121, 0
	v_mov_b32_e32 v122, 0
	v_mov_b32_e32 v123, 0
	v_mov_b32_e32 v124, 0
	v_mov_b32_e32 v125, 0
	v_mov_b32_e32 v126, 0
	v_mov_b32_e32 v127, 0
	s_mov_b32 s1, 0
	s_waitcnt vmcnt(4)
	s_barrier
.Lg16_gu_k:
	s_add_i32 s8, s1, 2
	s_lshl_b32 s96, s8, 13
	s_add_i32 m0, vcc_lo, 16384
	v_lshl_add_u64 v[160:161], v[188:189], 0, s[96:97]
	global_load_lds_dwordx4 v[160:161], off
	global_load_lds_dwordx4 v[160:161], off offset:1024
	ds_read_b128 v[196:199], v246 offset:0
	ds_read_b128 v[200:203], v246 offset:1024
	ds_read_b128 v[204:207], v246 offset:2048
	ds_read_b128 v[242:245], v246 offset:3072
	s_add_i32 s8, s1, 2
	s_lshl_b32 s96, s8, 11
	v_lshl_add_u64 v[248:249], v[184:185], 0, s[96:97]
	v_lshl_add_u64 v[250:251], v[186:187], 0, s[96:97]
	s_waitcnt vmcnt(8) lgkmcnt(3)
	v_mfma_f32_16x16x32_bf16 v[112:115], v[128:131], v[196:199], v[112:115]
	v_mfma_f32_16x16x32_bf16 v[120:123], v[132:135], v[196:199], v[120:123]
	v_mfma_f32_16x16x32_bf16 v[80:83], v[136:139], v[196:199], v[80:83]
	v_mfma_f32_16x16x32_bf16 v[88:91], v[140:143], v[196:199], v[88:91]
	ds_read_b128 v[196:199], v246 offset:4096
	s_waitcnt lgkmcnt(3)
	v_mfma_f32_16x16x32_bf16 v[116:119], v[128:131], v[200:203], v[116:119]
	v_mfma_f32_16x16x32_bf16 v[124:127], v[132:135], v[200:203], v[124:127]
	v_mfma_f32_16x16x32_bf16 v[84:87], v[136:139], v[200:203], v[84:87]
	v_mfma_f32_16x16x32_bf16 v[92:95], v[140:143], v[200:203], v[92:95]
	ds_read_b128 v[200:203], v246 offset:5120
	s_waitcnt lgkmcnt(3)
	v_mfma_f32_16x16x32_bf16 v[96:99], v[128:131], v[204:207], v[96:99]
	v_mfma_f32_16x16x32_bf16 v[104:107], v[132:135], v[204:207], v[104:107]
	v_mfma_f32_16x16x32_bf16 v[64:67], v[136:139], v[204:207], v[64:67]
	v_mfma_f32_16x16x32_bf16 v[72:75], v[140:143], v[204:207], v[72:75]
	ds_read_b128 v[204:207], v246 offset:6144
	s_waitcnt lgkmcnt(3)
	v_mfma_f32_16x16x32_bf16 v[100:103], v[128:131], v[242:245], v[100:103]
	v_mfma_f32_16x16x32_bf16 v[108:111], v[132:135], v[242:245], v[108:111]
	v_mfma_f32_16x16x32_bf16 v[68:71], v[136:139], v[242:245], v[68:71]
	v_mfma_f32_16x16x32_bf16 v[76:79], v[140:143], v[242:245], v[76:79]
	ds_read_b128 v[242:245], v246 offset:7168
	s_waitcnt lgkmcnt(3)
	v_mfma_f32_16x16x32_bf16 v[48:51], v[128:131], v[196:199], v[48:51]
	v_mfma_f32_16x16x32_bf16 v[56:59], v[132:135], v[196:199], v[56:59]
	v_mfma_f32_16x16x32_bf16 v[16:19], v[136:139], v[196:199], v[16:19]
	v_mfma_f32_16x16x32_bf16 v[24:27], v[140:143], v[196:199], v[24:27]
	s_waitcnt lgkmcnt(2)
	v_mfma_f32_16x16x32_bf16 v[52:55], v[128:131], v[200:203], v[52:55]
	v_mfma_f32_16x16x32_bf16 v[60:63], v[132:135], v[200:203], v[60:63]
	v_mfma_f32_16x16x32_bf16 v[20:23], v[136:139], v[200:203], v[20:23]
	v_mfma_f32_16x16x32_bf16 v[28:31], v[140:143], v[200:203], v[28:31]
	s_waitcnt lgkmcnt(1)
	v_mfma_f32_16x16x32_bf16 v[32:35], v[128:131], v[204:207], v[32:35]
	v_mfma_f32_16x16x32_bf16 v[40:43], v[132:135], v[204:207], v[40:43]
	v_mfma_f32_16x16x32_bf16 v[0:3], v[136:139], v[204:207], v[0:3]
	v_mfma_f32_16x16x32_bf16 v[8:11], v[140:143], v[204:207], v[8:11]
	s_waitcnt lgkmcnt(0)
	v_mfma_f32_16x16x32_bf16 v[36:39], v[128:131], v[242:245], v[36:39]
	v_mfma_f32_16x16x32_bf16 v[44:47], v[132:135], v[242:245], v[44:47]
	v_mfma_f32_16x16x32_bf16 v[4:7], v[136:139], v[242:245], v[4:7]
	v_mfma_f32_16x16x32_bf16 v[12:15], v[140:143], v[242:245], v[12:15]
	global_load_dwordx4 v[128:131], v[248:249], off
	global_load_dwordx4 v[132:135], v[248:249], off offset:256
	global_load_dwordx4 v[136:139], v[250:251], off
	global_load_dwordx4 v[140:143], v[250:251], off offset:256
	s_waitcnt vmcnt(10)
	s_barrier
	s_add_i32 s8, s1, 3
	s_lshl_b32 s96, s8, 13
	s_mov_b32 m0, vcc_lo
	v_lshl_add_u64 v[160:161], v[188:189], 0, s[96:97]
	global_load_lds_dwordx4 v[160:161], off
	global_load_lds_dwordx4 v[160:161], off offset:1024
	ds_read_b128 v[196:199], v246 offset:8192
	ds_read_b128 v[200:203], v246 offset:9216
	ds_read_b128 v[204:207], v246 offset:10240
	ds_read_b128 v[242:245], v246 offset:11264
	s_add_i32 s8, s1, 3
	s_lshl_b32 s96, s8, 11
	v_lshl_add_u64 v[248:249], v[184:185], 0, s[96:97]
	v_lshl_add_u64 v[250:251], v[186:187], 0, s[96:97]
	s_waitcnt vmcnt(8) lgkmcnt(3)
	v_mfma_f32_16x16x32_bf16 v[112:115], v[144:147], v[196:199], v[112:115]
	v_mfma_f32_16x16x32_bf16 v[120:123], v[148:151], v[196:199], v[120:123]
	v_mfma_f32_16x16x32_bf16 v[80:83], v[152:155], v[196:199], v[80:83]
	v_mfma_f32_16x16x32_bf16 v[88:91], v[156:159], v[196:199], v[88:91]
	ds_read_b128 v[196:199], v246 offset:12288
	s_waitcnt lgkmcnt(3)
	v_mfma_f32_16x16x32_bf16 v[116:119], v[144:147], v[200:203], v[116:119]
	v_mfma_f32_16x16x32_bf16 v[124:127], v[148:151], v[200:203], v[124:127]
	v_mfma_f32_16x16x32_bf16 v[84:87], v[152:155], v[200:203], v[84:87]
	v_mfma_f32_16x16x32_bf16 v[92:95], v[156:159], v[200:203], v[92:95]
	ds_read_b128 v[200:203], v246 offset:13312
	s_waitcnt lgkmcnt(3)
	v_mfma_f32_16x16x32_bf16 v[96:99], v[144:147], v[204:207], v[96:99]
	v_mfma_f32_16x16x32_bf16 v[104:107], v[148:151], v[204:207], v[104:107]
	v_mfma_f32_16x16x32_bf16 v[64:67], v[152:155], v[204:207], v[64:67]
	v_mfma_f32_16x16x32_bf16 v[72:75], v[156:159], v[204:207], v[72:75]
	ds_read_b128 v[204:207], v246 offset:14336
	s_waitcnt lgkmcnt(3)
	v_mfma_f32_16x16x32_bf16 v[100:103], v[144:147], v[242:245], v[100:103]
	v_mfma_f32_16x16x32_bf16 v[108:111], v[148:151], v[242:245], v[108:111]
	v_mfma_f32_16x16x32_bf16 v[68:71], v[152:155], v[242:245], v[68:71]
	v_mfma_f32_16x16x32_bf16 v[76:79], v[156:159], v[242:245], v[76:79]
	ds_read_b128 v[242:245], v246 offset:15360
	s_waitcnt lgkmcnt(3)
	v_mfma_f32_16x16x32_bf16 v[48:51], v[144:147], v[196:199], v[48:51]
	v_mfma_f32_16x16x32_bf16 v[56:59], v[148:151], v[196:199], v[56:59]
	v_mfma_f32_16x16x32_bf16 v[16:19], v[152:155], v[196:199], v[16:19]
	v_mfma_f32_16x16x32_bf16 v[24:27], v[156:159], v[196:199], v[24:27]
	s_waitcnt lgkmcnt(2)
	v_mfma_f32_16x16x32_bf16 v[52:55], v[144:147], v[200:203], v[52:55]
	v_mfma_f32_16x16x32_bf16 v[60:63], v[148:151], v[200:203], v[60:63]
	v_mfma_f32_16x16x32_bf16 v[20:23], v[152:155], v[200:203], v[20:23]
	v_mfma_f32_16x16x32_bf16 v[28:31], v[156:159], v[200:203], v[28:31]
	s_waitcnt lgkmcnt(1)
	v_mfma_f32_16x16x32_bf16 v[32:35], v[144:147], v[204:207], v[32:35]
	v_mfma_f32_16x16x32_bf16 v[40:43], v[148:151], v[204:207], v[40:43]
	v_mfma_f32_16x16x32_bf16 v[0:3], v[152:155], v[204:207], v[0:3]
	v_mfma_f32_16x16x32_bf16 v[8:11], v[156:159], v[204:207], v[8:11]
	s_waitcnt lgkmcnt(0)
	v_mfma_f32_16x16x32_bf16 v[36:39], v[144:147], v[242:245], v[36:39]
	v_mfma_f32_16x16x32_bf16 v[44:47], v[148:151], v[242:245], v[44:47]
	v_mfma_f32_16x16x32_bf16 v[4:7], v[152:155], v[242:245], v[4:7]
	v_mfma_f32_16x16x32_bf16 v[12:15], v[156:159], v[242:245], v[12:15]
	global_load_dwordx4 v[144:147], v[248:249], off
	global_load_dwordx4 v[148:151], v[248:249], off offset:256
	global_load_dwordx4 v[152:155], v[250:251], off
	global_load_dwordx4 v[156:159], v[250:251], off offset:256
	s_waitcnt vmcnt(10)
	s_barrier
	s_add_i32 s8, s1, 4
	s_lshl_b32 s96, s8, 13
	s_add_i32 m0, vcc_lo, 8192
	v_lshl_add_u64 v[160:161], v[188:189], 0, s[96:97]
	global_load_lds_dwordx4 v[160:161], off
	global_load_lds_dwordx4 v[160:161], off offset:1024
	ds_read_b128 v[196:199], v246 offset:16384
	ds_read_b128 v[200:203], v246 offset:17408
	ds_read_b128 v[204:207], v246 offset:18432
	ds_read_b128 v[242:245], v246 offset:19456
	s_add_i32 s8, s1, 4
	s_lshl_b32 s96, s8, 11
	v_lshl_add_u64 v[248:249], v[184:185], 0, s[96:97]
	v_lshl_add_u64 v[250:251], v[186:187], 0, s[96:97]
	s_waitcnt vmcnt(8) lgkmcnt(3)
	v_mfma_f32_16x16x32_bf16 v[112:115], v[128:131], v[196:199], v[112:115]
	v_mfma_f32_16x16x32_bf16 v[120:123], v[132:135], v[196:199], v[120:123]
	v_mfma_f32_16x16x32_bf16 v[80:83], v[136:139], v[196:199], v[80:83]
	v_mfma_f32_16x16x32_bf16 v[88:91], v[140:143], v[196:199], v[88:91]
	ds_read_b128 v[196:199], v246 offset:20480
	s_waitcnt lgkmcnt(3)
	v_mfma_f32_16x16x32_bf16 v[116:119], v[128:131], v[200:203], v[116:119]
	v_mfma_f32_16x16x32_bf16 v[124:127], v[132:135], v[200:203], v[124:127]
	v_mfma_f32_16x16x32_bf16 v[84:87], v[136:139], v[200:203], v[84:87]
	v_mfma_f32_16x16x32_bf16 v[92:95], v[140:143], v[200:203], v[92:95]
	ds_read_b128 v[200:203], v246 offset:21504
	s_waitcnt lgkmcnt(3)
	v_mfma_f32_16x16x32_bf16 v[96:99], v[128:131], v[204:207], v[96:99]
	v_mfma_f32_16x16x32_bf16 v[104:107], v[132:135], v[204:207], v[104:107]
	v_mfma_f32_16x16x32_bf16 v[64:67], v[136:139], v[204:207], v[64:67]
	v_mfma_f32_16x16x32_bf16 v[72:75], v[140:143], v[204:207], v[72:75]
	ds_read_b128 v[204:207], v246 offset:22528
	s_waitcnt lgkmcnt(3)
	v_mfma_f32_16x16x32_bf16 v[100:103], v[128:131], v[242:245], v[100:103]
	v_mfma_f32_16x16x32_bf16 v[108:111], v[132:135], v[242:245], v[108:111]
	v_mfma_f32_16x16x32_bf16 v[68:71], v[136:139], v[242:245], v[68:71]
	v_mfma_f32_16x16x32_bf16 v[76:79], v[140:143], v[242:245], v[76:79]
	ds_read_b128 v[242:245], v246 offset:23552
	s_waitcnt lgkmcnt(3)
	v_mfma_f32_16x16x32_bf16 v[48:51], v[128:131], v[196:199], v[48:51]
	v_mfma_f32_16x16x32_bf16 v[56:59], v[132:135], v[196:199], v[56:59]
	v_mfma_f32_16x16x32_bf16 v[16:19], v[136:139], v[196:199], v[16:19]
	v_mfma_f32_16x16x32_bf16 v[24:27], v[140:143], v[196:199], v[24:27]
	s_waitcnt lgkmcnt(2)
	v_mfma_f32_16x16x32_bf16 v[52:55], v[128:131], v[200:203], v[52:55]
	v_mfma_f32_16x16x32_bf16 v[60:63], v[132:135], v[200:203], v[60:63]
	v_mfma_f32_16x16x32_bf16 v[20:23], v[136:139], v[200:203], v[20:23]
	v_mfma_f32_16x16x32_bf16 v[28:31], v[140:143], v[200:203], v[28:31]
	s_waitcnt lgkmcnt(1)
	v_mfma_f32_16x16x32_bf16 v[32:35], v[128:131], v[204:207], v[32:35]
	v_mfma_f32_16x16x32_bf16 v[40:43], v[132:135], v[204:207], v[40:43]
	v_mfma_f32_16x16x32_bf16 v[0:3], v[136:139], v[204:207], v[0:3]
	v_mfma_f32_16x16x32_bf16 v[8:11], v[140:143], v[204:207], v[8:11]
	s_waitcnt lgkmcnt(0)
	v_mfma_f32_16x16x32_bf16 v[36:39], v[128:131], v[242:245], v[36:39]
	v_mfma_f32_16x16x32_bf16 v[44:47], v[132:135], v[242:245], v[44:47]
	v_mfma_f32_16x16x32_bf16 v[4:7], v[136:139], v[242:245], v[4:7]
	v_mfma_f32_16x16x32_bf16 v[12:15], v[140:143], v[242:245], v[12:15]
	global_load_dwordx4 v[128:131], v[248:249], off
	global_load_dwordx4 v[132:135], v[248:249], off offset:256
	global_load_dwordx4 v[136:139], v[250:251], off
	global_load_dwordx4 v[140:143], v[250:251], off offset:256
	s_waitcnt vmcnt(10)
	s_barrier
	s_add_i32 s8, s1, 5
	s_lshl_b32 s96, s8, 13
	s_add_i32 m0, vcc_lo, 16384
	v_lshl_add_u64 v[160:161], v[188:189], 0, s[96:97]
	global_load_lds_dwordx4 v[160:161], off
	global_load_lds_dwordx4 v[160:161], off offset:1024
	ds_read_b128 v[196:199], v246 offset:0
	ds_read_b128 v[200:203], v246 offset:1024
	ds_read_b128 v[204:207], v246 offset:2048
	ds_read_b128 v[242:245], v246 offset:3072
	s_add_i32 s8, s1, 5
	s_lshl_b32 s96, s8, 11
	v_lshl_add_u64 v[248:249], v[184:185], 0, s[96:97]
	v_lshl_add_u64 v[250:251], v[186:187], 0, s[96:97]
	s_waitcnt vmcnt(8) lgkmcnt(3)
	v_mfma_f32_16x16x32_bf16 v[112:115], v[144:147], v[196:199], v[112:115]
	v_mfma_f32_16x16x32_bf16 v[120:123], v[148:151], v[196:199], v[120:123]
	v_mfma_f32_16x16x32_bf16 v[80:83], v[152:155], v[196:199], v[80:83]
	v_mfma_f32_16x16x32_bf16 v[88:91], v[156:159], v[196:199], v[88:91]
	ds_read_b128 v[196:199], v246 offset:4096
	s_waitcnt lgkmcnt(3)
	v_mfma_f32_16x16x32_bf16 v[116:119], v[144:147], v[200:203], v[116:119]
	v_mfma_f32_16x16x32_bf16 v[124:127], v[148:151], v[200:203], v[124:127]
	v_mfma_f32_16x16x32_bf16 v[84:87], v[152:155], v[200:203], v[84:87]
	v_mfma_f32_16x16x32_bf16 v[92:95], v[156:159], v[200:203], v[92:95]
	ds_read_b128 v[200:203], v246 offset:5120
	s_waitcnt lgkmcnt(3)
	v_mfma_f32_16x16x32_bf16 v[96:99], v[144:147], v[204:207], v[96:99]
	v_mfma_f32_16x16x32_bf16 v[104:107], v[148:151], v[204:207], v[104:107]
	v_mfma_f32_16x16x32_bf16 v[64:67], v[152:155], v[204:207], v[64:67]
	v_mfma_f32_16x16x32_bf16 v[72:75], v[156:159], v[204:207], v[72:75]
	ds_read_b128 v[204:207], v246 offset:6144
	s_waitcnt lgkmcnt(3)
	v_mfma_f32_16x16x32_bf16 v[100:103], v[144:147], v[242:245], v[100:103]
	v_mfma_f32_16x16x32_bf16 v[108:111], v[148:151], v[242:245], v[108:111]
	v_mfma_f32_16x16x32_bf16 v[68:71], v[152:155], v[242:245], v[68:71]
	v_mfma_f32_16x16x32_bf16 v[76:79], v[156:159], v[242:245], v[76:79]
	ds_read_b128 v[242:245], v246 offset:7168
	s_waitcnt lgkmcnt(3)
	v_mfma_f32_16x16x32_bf16 v[48:51], v[144:147], v[196:199], v[48:51]
	v_mfma_f32_16x16x32_bf16 v[56:59], v[148:151], v[196:199], v[56:59]
	v_mfma_f32_16x16x32_bf16 v[16:19], v[152:155], v[196:199], v[16:19]
	v_mfma_f32_16x16x32_bf16 v[24:27], v[156:159], v[196:199], v[24:27]
	s_waitcnt lgkmcnt(2)
	v_mfma_f32_16x16x32_bf16 v[52:55], v[144:147], v[200:203], v[52:55]
	v_mfma_f32_16x16x32_bf16 v[60:63], v[148:151], v[200:203], v[60:63]
	v_mfma_f32_16x16x32_bf16 v[20:23], v[152:155], v[200:203], v[20:23]
	v_mfma_f32_16x16x32_bf16 v[28:31], v[156:159], v[200:203], v[28:31]
	s_waitcnt lgkmcnt(1)
	v_mfma_f32_16x16x32_bf16 v[32:35], v[144:147], v[204:207], v[32:35]
	v_mfma_f32_16x16x32_bf16 v[40:43], v[148:151], v[204:207], v[40:43]
	v_mfma_f32_16x16x32_bf16 v[0:3], v[152:155], v[204:207], v[0:3]
	v_mfma_f32_16x16x32_bf16 v[8:11], v[156:159], v[204:207], v[8:11]
	s_waitcnt lgkmcnt(0)
	v_mfma_f32_16x16x32_bf16 v[36:39], v[144:147], v[242:245], v[36:39]
	v_mfma_f32_16x16x32_bf16 v[44:47], v[148:151], v[242:245], v[44:47]
	v_mfma_f32_16x16x32_bf16 v[4:7], v[152:155], v[242:245], v[4:7]
	v_mfma_f32_16x16x32_bf16 v[12:15], v[156:159], v[242:245], v[12:15]
	global_load_dwordx4 v[144:147], v[248:249], off
	global_load_dwordx4 v[148:151], v[248:249], off offset:256
	global_load_dwordx4 v[152:155], v[250:251], off
	global_load_dwordx4 v[156:159], v[250:251], off offset:256
	s_waitcnt vmcnt(10)
	s_barrier
	s_add_i32 s8, s1, 6
	s_lshl_b32 s96, s8, 13
	s_mov_b32 m0, vcc_lo
	v_lshl_add_u64 v[160:161], v[188:189], 0, s[96:97]
	global_load_lds_dwordx4 v[160:161], off
	global_load_lds_dwordx4 v[160:161], off offset:1024
	ds_read_b128 v[196:199], v246 offset:8192
	ds_read_b128 v[200:203], v246 offset:9216
	ds_read_b128 v[204:207], v246 offset:10240
	ds_read_b128 v[242:245], v246 offset:11264
	s_add_i32 s8, s1, 6
	s_lshl_b32 s96, s8, 11
	v_lshl_add_u64 v[248:249], v[184:185], 0, s[96:97]
	v_lshl_add_u64 v[250:251], v[186:187], 0, s[96:97]
	s_waitcnt vmcnt(8) lgkmcnt(3)
	v_mfma_f32_16x16x32_bf16 v[112:115], v[128:131], v[196:199], v[112:115]
	v_mfma_f32_16x16x32_bf16 v[120:123], v[132:135], v[196:199], v[120:123]
	v_mfma_f32_16x16x32_bf16 v[80:83], v[136:139], v[196:199], v[80:83]
	v_mfma_f32_16x16x32_bf16 v[88:91], v[140:143], v[196:199], v[88:91]
	ds_read_b128 v[196:199], v246 offset:12288
	s_waitcnt lgkmcnt(3)
	v_mfma_f32_16x16x32_bf16 v[116:119], v[128:131], v[200:203], v[116:119]
	v_mfma_f32_16x16x32_bf16 v[124:127], v[132:135], v[200:203], v[124:127]
	v_mfma_f32_16x16x32_bf16 v[84:87], v[136:139], v[200:203], v[84:87]
	v_mfma_f32_16x16x32_bf16 v[92:95], v[140:143], v[200:203], v[92:95]
	ds_read_b128 v[200:203], v246 offset:13312
	s_waitcnt lgkmcnt(3)
	v_mfma_f32_16x16x32_bf16 v[96:99], v[128:131], v[204:207], v[96:99]
	v_mfma_f32_16x16x32_bf16 v[104:107], v[132:135], v[204:207], v[104:107]
	v_mfma_f32_16x16x32_bf16 v[64:67], v[136:139], v[204:207], v[64:67]
	v_mfma_f32_16x16x32_bf16 v[72:75], v[140:143], v[204:207], v[72:75]
	ds_read_b128 v[204:207], v246 offset:14336
	s_waitcnt lgkmcnt(3)
	v_mfma_f32_16x16x32_bf16 v[100:103], v[128:131], v[242:245], v[100:103]
	v_mfma_f32_16x16x32_bf16 v[108:111], v[132:135], v[242:245], v[108:111]
	v_mfma_f32_16x16x32_bf16 v[68:71], v[136:139], v[242:245], v[68:71]
	v_mfma_f32_16x16x32_bf16 v[76:79], v[140:143], v[242:245], v[76:79]
	ds_read_b128 v[242:245], v246 offset:15360
	s_waitcnt lgkmcnt(3)
	v_mfma_f32_16x16x32_bf16 v[48:51], v[128:131], v[196:199], v[48:51]
	v_mfma_f32_16x16x32_bf16 v[56:59], v[132:135], v[196:199], v[56:59]
	v_mfma_f32_16x16x32_bf16 v[16:19], v[136:139], v[196:199], v[16:19]
	v_mfma_f32_16x16x32_bf16 v[24:27], v[140:143], v[196:199], v[24:27]
	s_waitcnt lgkmcnt(2)
	v_mfma_f32_16x16x32_bf16 v[52:55], v[128:131], v[200:203], v[52:55]
	v_mfma_f32_16x16x32_bf16 v[60:63], v[132:135], v[200:203], v[60:63]
	v_mfma_f32_16x16x32_bf16 v[20:23], v[136:139], v[200:203], v[20:23]
	v_mfma_f32_16x16x32_bf16 v[28:31], v[140:143], v[200:203], v[28:31]
	s_waitcnt lgkmcnt(1)
	v_mfma_f32_16x16x32_bf16 v[32:35], v[128:131], v[204:207], v[32:35]
	v_mfma_f32_16x16x32_bf16 v[40:43], v[132:135], v[204:207], v[40:43]
	v_mfma_f32_16x16x32_bf16 v[0:3], v[136:139], v[204:207], v[0:3]
	v_mfma_f32_16x16x32_bf16 v[8:11], v[140:143], v[204:207], v[8:11]
	s_waitcnt lgkmcnt(0)
	v_mfma_f32_16x16x32_bf16 v[36:39], v[128:131], v[242:245], v[36:39]
	v_mfma_f32_16x16x32_bf16 v[44:47], v[132:135], v[242:245], v[44:47]
	v_mfma_f32_16x16x32_bf16 v[4:7], v[136:139], v[242:245], v[4:7]
	v_mfma_f32_16x16x32_bf16 v[12:15], v[140:143], v[242:245], v[12:15]
	global_load_dwordx4 v[128:131], v[248:249], off
	global_load_dwordx4 v[132:135], v[248:249], off offset:256
	global_load_dwordx4 v[136:139], v[250:251], off
	global_load_dwordx4 v[140:143], v[250:251], off offset:256
	s_waitcnt vmcnt(10)
	s_barrier
	s_add_i32 s8, s1, 7
	s_lshl_b32 s96, s8, 13
	s_add_i32 m0, vcc_lo, 8192
	v_lshl_add_u64 v[160:161], v[188:189], 0, s[96:97]
	global_load_lds_dwordx4 v[160:161], off
	global_load_lds_dwordx4 v[160:161], off offset:1024
	ds_read_b128 v[196:199], v246 offset:16384
	ds_read_b128 v[200:203], v246 offset:17408
	ds_read_b128 v[204:207], v246 offset:18432
	ds_read_b128 v[242:245], v246 offset:19456
	s_add_i32 s8, s1, 7
	s_lshl_b32 s96, s8, 11
	v_lshl_add_u64 v[248:249], v[184:185], 0, s[96:97]
	v_lshl_add_u64 v[250:251], v[186:187], 0, s[96:97]
	s_waitcnt vmcnt(8) lgkmcnt(3)
	v_mfma_f32_16x16x32_bf16 v[112:115], v[144:147], v[196:199], v[112:115]
	v_mfma_f32_16x16x32_bf16 v[120:123], v[148:151], v[196:199], v[120:123]
	v_mfma_f32_16x16x32_bf16 v[80:83], v[152:155], v[196:199], v[80:83]
	v_mfma_f32_16x16x32_bf16 v[88:91], v[156:159], v[196:199], v[88:91]
	ds_read_b128 v[196:199], v246 offset:20480
	s_waitcnt lgkmcnt(3)
	v_mfma_f32_16x16x32_bf16 v[116:119], v[144:147], v[200:203], v[116:119]
	v_mfma_f32_16x16x32_bf16 v[124:127], v[148:151], v[200:203], v[124:127]
	v_mfma_f32_16x16x32_bf16 v[84:87], v[152:155], v[200:203], v[84:87]
	v_mfma_f32_16x16x32_bf16 v[92:95], v[156:159], v[200:203], v[92:95]
	ds_read_b128 v[200:203], v246 offset:21504
	s_waitcnt lgkmcnt(3)
	v_mfma_f32_16x16x32_bf16 v[96:99], v[144:147], v[204:207], v[96:99]
	v_mfma_f32_16x16x32_bf16 v[104:107], v[148:151], v[204:207], v[104:107]
	v_mfma_f32_16x16x32_bf16 v[64:67], v[152:155], v[204:207], v[64:67]
	v_mfma_f32_16x16x32_bf16 v[72:75], v[156:159], v[204:207], v[72:75]
	ds_read_b128 v[204:207], v246 offset:22528
	s_waitcnt lgkmcnt(3)
	v_mfma_f32_16x16x32_bf16 v[100:103], v[144:147], v[242:245], v[100:103]
	v_mfma_f32_16x16x32_bf16 v[108:111], v[148:151], v[242:245], v[108:111]
	v_mfma_f32_16x16x32_bf16 v[68:71], v[152:155], v[242:245], v[68:71]
	v_mfma_f32_16x16x32_bf16 v[76:79], v[156:159], v[242:245], v[76:79]
	ds_read_b128 v[242:245], v246 offset:23552
	s_waitcnt lgkmcnt(3)
	v_mfma_f32_16x16x32_bf16 v[48:51], v[144:147], v[196:199], v[48:51]
	v_mfma_f32_16x16x32_bf16 v[56:59], v[148:151], v[196:199], v[56:59]
	v_mfma_f32_16x16x32_bf16 v[16:19], v[152:155], v[196:199], v[16:19]
	v_mfma_f32_16x16x32_bf16 v[24:27], v[156:159], v[196:199], v[24:27]
	s_waitcnt lgkmcnt(2)
	v_mfma_f32_16x16x32_bf16 v[52:55], v[144:147], v[200:203], v[52:55]
	v_mfma_f32_16x16x32_bf16 v[60:63], v[148:151], v[200:203], v[60:63]
	v_mfma_f32_16x16x32_bf16 v[20:23], v[152:155], v[200:203], v[20:23]
	v_mfma_f32_16x16x32_bf16 v[28:31], v[156:159], v[200:203], v[28:31]
	s_waitcnt lgkmcnt(1)
	v_mfma_f32_16x16x32_bf16 v[32:35], v[144:147], v[204:207], v[32:35]
	v_mfma_f32_16x16x32_bf16 v[40:43], v[148:151], v[204:207], v[40:43]
	v_mfma_f32_16x16x32_bf16 v[0:3], v[152:155], v[204:207], v[0:3]
	v_mfma_f32_16x16x32_bf16 v[8:11], v[156:159], v[204:207], v[8:11]
	s_waitcnt lgkmcnt(0)
	v_mfma_f32_16x16x32_bf16 v[36:39], v[144:147], v[242:245], v[36:39]
	v_mfma_f32_16x16x32_bf16 v[44:47], v[148:151], v[242:245], v[44:47]
	v_mfma_f32_16x16x32_bf16 v[4:7], v[152:155], v[242:245], v[4:7]
	v_mfma_f32_16x16x32_bf16 v[12:15], v[156:159], v[242:245], v[12:15]
	global_load_dwordx4 v[144:147], v[248:249], off
	global_load_dwordx4 v[148:151], v[248:249], off offset:256
	global_load_dwordx4 v[152:155], v[250:251], off
	global_load_dwordx4 v[156:159], v[250:251], off offset:256
	s_waitcnt vmcnt(10)
	s_barrier
	s_add_i32 s1, s1, 6
	s_cmp_lt_u32 s1, 30
	s_cbranch_scc1 .Lg16_gu_k
	ds_read_b128 v[196:199], v246 offset:0
	ds_read_b128 v[200:203], v246 offset:1024
	ds_read_b128 v[204:207], v246 offset:2048
	ds_read_b128 v[242:245], v246 offset:3072
	s_waitcnt vmcnt(6) lgkmcnt(3)
	v_mfma_f32_16x16x32_bf16 v[112:115], v[128:131], v[196:199], v[112:115]
	v_mfma_f32_16x16x32_bf16 v[120:123], v[132:135], v[196:199], v[120:123]
	v_mfma_f32_16x16x32_bf16 v[80:83], v[136:139], v[196:199], v[80:83]
	v_mfma_f32_16x16x32_bf16 v[88:91], v[140:143], v[196:199], v[88:91]
	ds_read_b128 v[196:199], v246 offset:4096
	s_waitcnt lgkmcnt(3)
	v_mfma_f32_16x16x32_bf16 v[116:119], v[128:131], v[200:203], v[116:119]
	v_mfma_f32_16x16x32_bf16 v[124:127], v[132:135], v[200:203], v[124:127]
	v_mfma_f32_16x16x32_bf16 v[84:87], v[136:139], v[200:203], v[84:87]
	v_mfma_f32_16x16x32_bf16 v[92:95], v[140:143], v[200:203], v[92:95]
	ds_read_b128 v[200:203], v246 offset:5120
	s_waitcnt lgkmcnt(3)
	v_mfma_f32_16x16x32_bf16 v[96:99], v[128:131], v[204:207], v[96:99]
	v_mfma_f32_16x16x32_bf16 v[104:107], v[132:135], v[204:207], v[104:107]
	v_mfma_f32_16x16x32_bf16 v[64:67], v[136:139], v[204:207], v[64:67]
	v_mfma_f32_16x16x32_bf16 v[72:75], v[140:143], v[204:207], v[72:75]
	ds_read_b128 v[204:207], v246 offset:6144
	s_waitcnt lgkmcnt(3)
	v_mfma_f32_16x16x32_bf16 v[100:103], v[128:131], v[242:245], v[100:103]
	v_mfma_f32_16x16x32_bf16 v[108:111], v[132:135], v[242:245], v[108:111]
	v_mfma_f32_16x16x32_bf16 v[68:71], v[136:139], v[242:245], v[68:71]
	v_mfma_f32_16x16x32_bf16 v[76:79], v[140:143], v[242:245], v[76:79]
	ds_read_b128 v[242:245], v246 offset:7168
	s_waitcnt lgkmcnt(3)
	v_mfma_f32_16x16x32_bf16 v[48:51], v[128:131], v[196:199], v[48:51]
	v_mfma_f32_16x16x32_bf16 v[56:59], v[132:135], v[196:199], v[56:59]
	v_mfma_f32_16x16x32_bf16 v[16:19], v[136:139], v[196:199], v[16:19]
	v_mfma_f32_16x16x32_bf16 v[24:27], v[140:143], v[196:199], v[24:27]
	s_waitcnt lgkmcnt(2)
	v_mfma_f32_16x16x32_bf16 v[52:55], v[128:131], v[200:203], v[52:55]
	v_mfma_f32_16x16x32_bf16 v[60:63], v[132:135], v[200:203], v[60:63]
	v_mfma_f32_16x16x32_bf16 v[20:23], v[136:139], v[200:203], v[20:23]
	v_mfma_f32_16x16x32_bf16 v[28:31], v[140:143], v[200:203], v[28:31]
	s_waitcnt lgkmcnt(1)
	v_mfma_f32_16x16x32_bf16 v[32:35], v[128:131], v[204:207], v[32:35]
	v_mfma_f32_16x16x32_bf16 v[40:43], v[132:135], v[204:207], v[40:43]
	v_mfma_f32_16x16x32_bf16 v[0:3], v[136:139], v[204:207], v[0:3]
	v_mfma_f32_16x16x32_bf16 v[8:11], v[140:143], v[204:207], v[8:11]
	s_waitcnt lgkmcnt(0)
	v_mfma_f32_16x16x32_bf16 v[36:39], v[128:131], v[242:245], v[36:39]
	v_mfma_f32_16x16x32_bf16 v[44:47], v[132:135], v[242:245], v[44:47]
	v_mfma_f32_16x16x32_bf16 v[4:7], v[136:139], v[242:245], v[4:7]
	v_mfma_f32_16x16x32_bf16 v[12:15], v[140:143], v[242:245], v[12:15]
	s_waitcnt vmcnt(4)
	s_barrier
	ds_read_b128 v[196:199], v246 offset:8192
	ds_read_b128 v[200:203], v246 offset:9216
	ds_read_b128 v[204:207], v246 offset:10240
	ds_read_b128 v[242:245], v246 offset:11264
	s_waitcnt vmcnt(0) lgkmcnt(3)
	v_mfma_f32_16x16x32_bf16 v[112:115], v[144:147], v[196:199], v[112:115]
	v_mfma_f32_16x16x32_bf16 v[120:123], v[148:151], v[196:199], v[120:123]
	v_mfma_f32_16x16x32_bf16 v[80:83], v[152:155], v[196:199], v[80:83]
	v_mfma_f32_16x16x32_bf16 v[88:91], v[156:159], v[196:199], v[88:91]
	ds_read_b128 v[196:199], v246 offset:12288
	s_waitcnt lgkmcnt(3)
	v_mfma_f32_16x16x32_bf16 v[116:119], v[144:147], v[200:203], v[116:119]
	v_mfma_f32_16x16x32_bf16 v[124:127], v[148:151], v[200:203], v[124:127]
	v_mfma_f32_16x16x32_bf16 v[84:87], v[152:155], v[200:203], v[84:87]
	v_mfma_f32_16x16x32_bf16 v[92:95], v[156:159], v[200:203], v[92:95]
	ds_read_b128 v[200:203], v246 offset:13312
	s_waitcnt lgkmcnt(3)
	v_mfma_f32_16x16x32_bf16 v[96:99], v[144:147], v[204:207], v[96:99]
	v_mfma_f32_16x16x32_bf16 v[104:107], v[148:151], v[204:207], v[104:107]
	v_mfma_f32_16x16x32_bf16 v[64:67], v[152:155], v[204:207], v[64:67]
	v_mfma_f32_16x16x32_bf16 v[72:75], v[156:159], v[204:207], v[72:75]
	ds_read_b128 v[204:207], v246 offset:14336
	s_waitcnt lgkmcnt(3)
	v_mfma_f32_16x16x32_bf16 v[100:103], v[144:147], v[242:245], v[100:103]
	v_mfma_f32_16x16x32_bf16 v[108:111], v[148:151], v[242:245], v[108:111]
	v_mfma_f32_16x16x32_bf16 v[68:71], v[152:155], v[242:245], v[68:71]
	v_mfma_f32_16x16x32_bf16 v[76:79], v[156:159], v[242:245], v[76:79]
	ds_read_b128 v[242:245], v246 offset:15360
	s_waitcnt lgkmcnt(3)
	v_mfma_f32_16x16x32_bf16 v[48:51], v[144:147], v[196:199], v[48:51]
	v_mfma_f32_16x16x32_bf16 v[56:59], v[148:151], v[196:199], v[56:59]
	v_mfma_f32_16x16x32_bf16 v[16:19], v[152:155], v[196:199], v[16:19]
	v_mfma_f32_16x16x32_bf16 v[24:27], v[156:159], v[196:199], v[24:27]
	s_waitcnt lgkmcnt(2)
	v_mfma_f32_16x16x32_bf16 v[52:55], v[144:147], v[200:203], v[52:55]
	v_mfma_f32_16x16x32_bf16 v[60:63], v[148:151], v[200:203], v[60:63]
	v_mfma_f32_16x16x32_bf16 v[20:23], v[152:155], v[200:203], v[20:23]
	v_mfma_f32_16x16x32_bf16 v[28:31], v[156:159], v[200:203], v[28:31]
	s_waitcnt lgkmcnt(1)
	v_mfma_f32_16x16x32_bf16 v[32:35], v[144:147], v[204:207], v[32:35]
	v_mfma_f32_16x16x32_bf16 v[40:43], v[148:151], v[204:207], v[40:43]
	v_mfma_f32_16x16x32_bf16 v[0:3], v[152:155], v[204:207], v[0:3]
	v_mfma_f32_16x16x32_bf16 v[8:11], v[156:159], v[204:207], v[8:11]
	s_waitcnt lgkmcnt(0)
	v_mfma_f32_16x16x32_bf16 v[36:39], v[144:147], v[242:245], v[36:39]
	v_mfma_f32_16x16x32_bf16 v[44:47], v[148:151], v[242:245], v[44:47]
	v_mfma_f32_16x16x32_bf16 v[4:7], v[152:155], v[242:245], v[4:7]
	v_mfma_f32_16x16x32_bf16 v[12:15], v[156:159], v[242:245], v[12:15]
	s_barrier
	s_nop 7
	v_permlane16_swap_b32_e32 v112, v116
	v_permlane16_swap_b32_e32 v113, v117
	v_permlane16_swap_b32_e32 v114, v118
	v_permlane16_swap_b32_e32 v115, v119
	v_permlane16_swap_b32_e32 v120, v124
	v_permlane16_swap_b32_e32 v121, v125
	v_permlane16_swap_b32_e32 v122, v126
	v_permlane16_swap_b32_e32 v123, v127
	v_permlane16_swap_b32_e32 v96, v100
	v_permlane16_swap_b32_e32 v97, v101
	v_permlane16_swap_b32_e32 v98, v102
	v_permlane16_swap_b32_e32 v99, v103
	v_permlane16_swap_b32_e32 v104, v108
	v_permlane16_swap_b32_e32 v105, v109
	v_permlane16_swap_b32_e32 v106, v110
	v_permlane16_swap_b32_e32 v107, v111
	v_permlane16_swap_b32_e32 v48, v52
	v_permlane16_swap_b32_e32 v49, v53
	v_permlane16_swap_b32_e32 v50, v54
	v_permlane16_swap_b32_e32 v51, v55
	v_permlane16_swap_b32_e32 v56, v60
	v_permlane16_swap_b32_e32 v57, v61
	v_permlane16_swap_b32_e32 v58, v62
	v_permlane16_swap_b32_e32 v59, v63
	v_permlane16_swap_b32_e32 v32, v36
	v_permlane16_swap_b32_e32 v33, v37
	v_permlane16_swap_b32_e32 v34, v38
	v_permlane16_swap_b32_e32 v35, v39
	v_permlane16_swap_b32_e32 v40, v44
	v_permlane16_swap_b32_e32 v41, v45
	v_permlane16_swap_b32_e32 v42, v46
	v_permlane16_swap_b32_e32 v43, v47
	v_permlane16_swap_b32_e32 v80, v84
	v_permlane16_swap_b32_e32 v81, v85
	v_permlane16_swap_b32_e32 v82, v86
	v_permlane16_swap_b32_e32 v83, v87
	v_permlane16_swap_b32_e32 v88, v92
	v_permlane16_swap_b32_e32 v89, v93
	v_permlane16_swap_b32_e32 v90, v94
	v_permlane16_swap_b32_e32 v91, v95
	v_permlane16_swap_b32_e32 v64, v68
	v_permlane16_swap_b32_e32 v65, v69
	v_permlane16_swap_b32_e32 v66, v70
	v_permlane16_swap_b32_e32 v67, v71
	v_permlane16_swap_b32_e32 v72, v76
	v_permlane16_swap_b32_e32 v73, v77
	v_permlane16_swap_b32_e32 v74, v78
	v_permlane16_swap_b32_e32 v75, v79
	v_permlane16_swap_b32_e32 v16, v20
	v_permlane16_swap_b32_e32 v17, v21
	v_permlane16_swap_b32_e32 v18, v22
	v_permlane16_swap_b32_e32 v19, v23
	v_permlane16_swap_b32_e32 v24, v28
	v_permlane16_swap_b32_e32 v25, v29
	v_permlane16_swap_b32_e32 v26, v30
	v_permlane16_swap_b32_e32 v27, v31
	v_permlane16_swap_b32_e32 v0, v4
	v_permlane16_swap_b32_e32 v1, v5
	v_permlane16_swap_b32_e32 v2, v6
	v_permlane16_swap_b32_e32 v3, v7
	v_permlane16_swap_b32_e32 v8, v12
	v_permlane16_swap_b32_e32 v9, v13
	v_permlane16_swap_b32_e32 v10, v14
	v_permlane16_swap_b32_e32 v11, v15
	v_permlane32_swap_b32_e32 v112, v116
	v_permlane32_swap_b32_e32 v113, v117
	v_permlane32_swap_b32_e32 v114, v118
	v_permlane32_swap_b32_e32 v115, v119
	v_permlane32_swap_b32_e32 v120, v124
	v_permlane32_swap_b32_e32 v121, v125
	v_permlane32_swap_b32_e32 v122, v126
	v_permlane32_swap_b32_e32 v123, v127
	v_permlane32_swap_b32_e32 v96, v100
	v_permlane32_swap_b32_e32 v97, v101
	v_permlane32_swap_b32_e32 v98, v102
	v_permlane32_swap_b32_e32 v99, v103
	v_permlane32_swap_b32_e32 v104, v108
	v_permlane32_swap_b32_e32 v105, v109
	v_permlane32_swap_b32_e32 v106, v110
	v_permlane32_swap_b32_e32 v107, v111
	v_permlane32_swap_b32_e32 v48, v52
	v_permlane32_swap_b32_e32 v49, v53
	v_permlane32_swap_b32_e32 v50, v54
	v_permlane32_swap_b32_e32 v51, v55
	v_permlane32_swap_b32_e32 v56, v60
	v_permlane32_swap_b32_e32 v57, v61
	v_permlane32_swap_b32_e32 v58, v62
	v_permlane32_swap_b32_e32 v59, v63
	v_permlane32_swap_b32_e32 v32, v36
	v_permlane32_swap_b32_e32 v33, v37
	v_permlane32_swap_b32_e32 v34, v38
	v_permlane32_swap_b32_e32 v35, v39
	v_permlane32_swap_b32_e32 v40, v44
	v_permlane32_swap_b32_e32 v41, v45
	v_permlane32_swap_b32_e32 v42, v46
	v_permlane32_swap_b32_e32 v43, v47
	v_permlane32_swap_b32_e32 v80, v84
	v_permlane32_swap_b32_e32 v81, v85
	v_permlane32_swap_b32_e32 v82, v86
	v_permlane32_swap_b32_e32 v83, v87
	v_permlane32_swap_b32_e32 v88, v92
	v_permlane32_swap_b32_e32 v89, v93
	v_permlane32_swap_b32_e32 v90, v94
	v_permlane32_swap_b32_e32 v91, v95
	v_permlane32_swap_b32_e32 v64, v68
	v_permlane32_swap_b32_e32 v65, v69
	v_permlane32_swap_b32_e32 v66, v70
	v_permlane32_swap_b32_e32 v67, v71
	v_permlane32_swap_b32_e32 v72, v76
	v_permlane32_swap_b32_e32 v73, v77
	v_permlane32_swap_b32_e32 v74, v78
	v_permlane32_swap_b32_e32 v75, v79
	v_permlane32_swap_b32_e32 v16, v20
	v_permlane32_swap_b32_e32 v17, v21
	v_permlane32_swap_b32_e32 v18, v22
	v_permlane32_swap_b32_e32 v19, v23
	v_permlane32_swap_b32_e32 v24, v28
	v_permlane32_swap_b32_e32 v25, v29
	v_permlane32_swap_b32_e32 v26, v30
	v_permlane32_swap_b32_e32 v27, v31
	v_permlane32_swap_b32_e32 v0, v4
	v_permlane32_swap_b32_e32 v1, v5
	v_permlane32_swap_b32_e32 v2, v6
	v_permlane32_swap_b32_e32 v3, v7
	v_permlane32_swap_b32_e32 v8, v12
	v_permlane32_swap_b32_e32 v9, v13
	v_permlane32_swap_b32_e32 v10, v14
	v_permlane32_swap_b32_e32 v11, v15
	s_waitcnt vmcnt(0)
	s_waitcnt vmcnt(0)
	v_mul_f32_e32 v133, 0xbfb8aa3b, v112
	v_exp_f32_e32 v133, v133
	s_movk_i32 s1, 0x2400
	v_mul_lo_u32 v128, v238, s1
	v_lshl_or_b32 v131, s0, 6, v181
	v_add_f32_e32 v133, 1.0, v133
	v_lshl_or_b32 v132, v239, 1, v128
	v_and_b32_e32 v129, 0xffffffc0, v237
	v_lshl_or_b32 v128, v181, 1, v128
	v_rcp_f32_e32 v135, v133
	s_nop 0
	v_mul_f32_e32 v112, v112, v135
	v_mul_f32_e32 v96, v96, v112
	v_cvt_pk_bf16_f32 v112, v96, s0
	s_movk_i32 s0, 0x240
	v_mad_u32_u24 v96, v183, s0, v132
	ds_write_b16 v96, v112
	v_mul_f32_e32 v112, 0xbfb8aa3b, v113
	v_exp_f32_e32 v112, v112
	v_lshl_add_u32 v130, s7, 8, v129
	v_lshrrev_b32_e32 v129, 2, v240
	v_mad_u32_u24 v128, v129, s42, v128
	v_add_f32_e32 v112, 1.0, v112
	v_rcp_f32_e32 v133, v112
	s_nop 0
	v_mul_f32_e32 v112, v113, v133
	v_mul_f32_e32 v97, v97, v112
	v_cvt_pk_bf16_f32 v97, v97, s0
	ds_write_b16 v96, v97 offset:144
	v_mul_f32_e32 v97, 0xbfb8aa3b, v114
	v_exp_f32_e32 v97, v97
	s_nop 0
	v_add_f32_e32 v97, 1.0, v97
	v_rcp_f32_e32 v113, v97
	s_nop 0
	v_mul_f32_e32 v97, v114, v113
	v_mul_f32_e32 v97, v98, v97
	v_cvt_pk_bf16_f32 v97, v97, s0
	ds_write_b16 v96, v97 offset:288
	v_mul_f32_e32 v97, 0xbfb8aa3b, v115
	v_exp_f32_e32 v97, v97
	s_nop 0
	v_add_f32_e32 v97, 1.0, v97
	v_rcp_f32_e32 v112, v97
	s_nop 0
	v_mul_f32_e32 v97, v115, v112
	v_mul_f32_e32 v97, v99, v97
	v_cvt_pk_bf16_f32 v97, v97, s0
	ds_write_b16 v96, v97 offset:432
	v_mul_f32_e32 v97, 0xbfb8aa3b, v116
	v_exp_f32_e32 v97, v97
	s_nop 0
	v_add_f32_e32 v97, 1.0, v97
	v_rcp_f32_e32 v99, v97
	s_nop 0
	v_mul_f32_e32 v97, v116, v99
	v_mul_f32_e32 v97, v100, v97
	v_cvt_pk_bf16_f32 v97, v97, s0
	ds_write_b16 v96, v97 offset:1152
	v_mul_f32_e32 v97, 0xbfb8aa3b, v117
	v_exp_f32_e32 v97, v97
	s_nop 0
	v_add_f32_e32 v97, 1.0, v97
	v_rcp_f32_e32 v99, v97
	s_nop 0
	v_mul_f32_e32 v97, v117, v99
	v_mul_f32_e32 v97, v101, v97
	v_cvt_pk_bf16_f32 v97, v97, s0
	ds_write_b16 v96, v97 offset:1296
	v_mul_f32_e32 v97, 0xbfb8aa3b, v118
	v_exp_f32_e32 v97, v97
	s_nop 0
	v_add_f32_e32 v97, 1.0, v97
	v_rcp_f32_e32 v99, v97
	s_nop 0
	v_mul_f32_e32 v97, v118, v99
	v_mul_f32_e32 v97, v102, v97
	v_cvt_pk_bf16_f32 v97, v97, s0
	ds_write_b16 v96, v97 offset:1440
	v_mul_f32_e32 v97, 0xbfb8aa3b, v119
	v_exp_f32_e32 v97, v97
	s_nop 0
	v_add_f32_e32 v97, 1.0, v97
	v_rcp_f32_e32 v99, v97
	s_nop 0
	v_mul_f32_e32 v97, v119, v99
	v_mul_f32_e32 v97, v103, v97
	v_cvt_pk_bf16_f32 v97, v97, s0
	ds_write_b16 v96, v97 offset:1584
	v_mul_f32_e32 v97, 0xbfb8aa3b, v120
	v_exp_f32_e32 v97, v97
	s_nop 0
	v_add_f32_e32 v97, 1.0, v97
	v_rcp_f32_e32 v99, v97
	s_nop 0
	v_mul_f32_e32 v97, v120, v99
	v_mul_f32_e32 v97, v104, v97
	v_cvt_pk_bf16_f32 v97, v97, s0
	ds_write_b16 v96, v97 offset:2304
	v_mul_f32_e32 v97, 0xbfb8aa3b, v121
	v_exp_f32_e32 v97, v97
	s_nop 0
	v_add_f32_e32 v97, 1.0, v97
	v_rcp_f32_e32 v99, v97
	s_nop 0
	v_mul_f32_e32 v97, v121, v99
	v_mul_f32_e32 v97, v105, v97
	v_cvt_pk_bf16_f32 v97, v97, s0
	ds_write_b16 v96, v97 offset:2448
	v_mul_f32_e32 v97, 0xbfb8aa3b, v122
	v_exp_f32_e32 v97, v97
	s_nop 0
	v_add_f32_e32 v97, 1.0, v97
	v_rcp_f32_e32 v99, v97
	s_nop 0
	v_mul_f32_e32 v97, v122, v99
	v_mul_f32_e32 v97, v106, v97
	v_cvt_pk_bf16_f32 v97, v97, s0
	ds_write_b16 v96, v97 offset:2592
	v_mul_f32_e32 v97, 0xbfb8aa3b, v123
	v_exp_f32_e32 v97, v97
	s_nop 0
	v_add_f32_e32 v97, 1.0, v97
	v_rcp_f32_e32 v99, v97
	s_nop 0
	v_mul_f32_e32 v97, v123, v99
	v_mul_f32_e32 v97, v107, v97
	v_cvt_pk_bf16_f32 v97, v97, s0
	ds_write_b16 v96, v97 offset:2736
	v_mul_f32_e32 v97, 0xbfb8aa3b, v124
	v_exp_f32_e32 v97, v97
	s_nop 0
	v_add_f32_e32 v97, 1.0, v97
	v_rcp_f32_e32 v99, v97
	s_nop 0
	v_mul_f32_e32 v97, v124, v99
	v_mul_f32_e32 v97, v108, v97
	v_cvt_pk_bf16_f32 v97, v97, s0
	ds_write_b16 v96, v97 offset:3456
	v_mul_f32_e32 v97, 0xbfb8aa3b, v125
	v_exp_f32_e32 v97, v97
	s_nop 0
	v_add_f32_e32 v97, 1.0, v97
	v_rcp_f32_e32 v99, v97
	s_nop 0
	v_mul_f32_e32 v97, v125, v99
	v_mul_f32_e32 v97, v109, v97
	v_cvt_pk_bf16_f32 v97, v97, s0
	ds_write_b16 v96, v97 offset:3600
	v_mul_f32_e32 v97, 0xbfb8aa3b, v126
	v_exp_f32_e32 v97, v97
	s_nop 0
	v_add_f32_e32 v97, 1.0, v97
	v_rcp_f32_e32 v99, v97
	s_nop 0
	v_mul_f32_e32 v97, v126, v99
	v_mul_f32_e32 v97, v110, v97
	v_cvt_pk_bf16_f32 v97, v97, s0
	ds_write_b16 v96, v97 offset:3744
	v_mul_f32_e32 v97, 0xbfb8aa3b, v127
	v_exp_f32_e32 v97, v97
	s_nop 0
	v_add_f32_e32 v97, 1.0, v97
	v_rcp_f32_e32 v99, v97
	s_nop 0
	v_mul_f32_e32 v97, v127, v99
	v_mul_f32_e32 v97, v111, v97
	v_cvt_pk_bf16_f32 v97, v97, s0
	ds_write_b16 v96, v97 offset:3888
	v_mul_f32_e32 v97, 0xbfb8aa3b, v80
	v_exp_f32_e32 v97, v97
	s_nop 0
	v_add_f32_e32 v97, 1.0, v97
	v_rcp_f32_e32 v99, v97
	s_nop 0
	v_mul_f32_e32 v80, v80, v99
	v_mul_f32_e32 v64, v64, v80
	v_cvt_pk_bf16_f32 v64, v64, s0
	ds_write_b16 v96, v64 offset:4608
	v_mul_f32_e32 v64, 0xbfb8aa3b, v81
	v_exp_f32_e32 v64, v64
	s_nop 0
	v_add_f32_e32 v64, 1.0, v64
	v_rcp_f32_e32 v97, v64
	s_nop 0
	v_mul_f32_e32 v64, v81, v97
	v_mul_f32_e32 v64, v65, v64
	v_cvt_pk_bf16_f32 v64, v64, s0
	ds_write_b16 v96, v64 offset:4752
	v_mul_f32_e32 v64, 0xbfb8aa3b, v82
	v_exp_f32_e32 v64, v64
	s_nop 0
	v_add_f32_e32 v64, 1.0, v64
	v_rcp_f32_e32 v80, v64
	s_nop 0
	v_mul_f32_e32 v64, v82, v80
	v_mul_f32_e32 v64, v66, v64
	v_cvt_pk_bf16_f32 v64, v64, s0
	ds_write_b16 v96, v64 offset:4896
	v_mul_f32_e32 v64, 0xbfb8aa3b, v83
	v_exp_f32_e32 v64, v64
	s_nop 0
	v_add_f32_e32 v64, 1.0, v64
	v_rcp_f32_e32 v66, v64
	s_nop 0
	v_mul_f32_e32 v64, v83, v66
	v_mul_f32_e32 v64, v67, v64
	v_cvt_pk_bf16_f32 v64, v64, s0
	ds_write_b16 v96, v64 offset:5040
	v_mul_f32_e32 v64, 0xbfb8aa3b, v84
	v_exp_f32_e32 v64, v64
	s_nop 0
	v_add_f32_e32 v64, 1.0, v64
	v_rcp_f32_e32 v66, v64
	s_nop 0
	v_mul_f32_e32 v64, v84, v66
	v_mul_f32_e32 v64, v68, v64
	v_cvt_pk_bf16_f32 v64, v64, s0
	ds_write_b16 v96, v64 offset:5760
	v_mul_f32_e32 v64, 0xbfb8aa3b, v85
	v_exp_f32_e32 v64, v64
	s_nop 0
	v_add_f32_e32 v64, 1.0, v64
	v_rcp_f32_e32 v66, v64
	s_nop 0
	v_mul_f32_e32 v64, v85, v66
	v_mul_f32_e32 v64, v69, v64
	v_cvt_pk_bf16_f32 v64, v64, s0
	ds_write_b16 v96, v64 offset:5904
	v_mul_f32_e32 v64, 0xbfb8aa3b, v86
	v_exp_f32_e32 v64, v64
	s_nop 0
	v_add_f32_e32 v64, 1.0, v64
	v_rcp_f32_e32 v66, v64
	s_nop 0
	v_mul_f32_e32 v64, v86, v66
	v_mul_f32_e32 v64, v70, v64
	v_cvt_pk_bf16_f32 v64, v64, s0
	ds_write_b16 v96, v64 offset:6048
	v_mul_f32_e32 v64, 0xbfb8aa3b, v87
	v_exp_f32_e32 v64, v64
	s_nop 0
	v_add_f32_e32 v64, 1.0, v64
	v_rcp_f32_e32 v66, v64
	s_nop 0
	v_mul_f32_e32 v64, v87, v66
	v_mul_f32_e32 v64, v71, v64
	v_cvt_pk_bf16_f32 v64, v64, s0
	ds_write_b16 v96, v64 offset:6192
	v_mul_f32_e32 v64, 0xbfb8aa3b, v88
	v_exp_f32_e32 v64, v64
	v_ashrrev_i32_e32 v71, 5, v130
	v_or_b32_e32 v70, 1, v71
	v_add_f32_e32 v64, 1.0, v64
	v_rcp_f32_e32 v66, v64
	s_nop 0
	v_mul_f32_e32 v64, v88, v66
	v_mul_f32_e32 v64, v72, v64
	v_cvt_pk_bf16_f32 v64, v64, s0
	ds_write_b16 v96, v64 offset:6912
	v_mul_f32_e32 v64, 0xbfb8aa3b, v89
	v_exp_f32_e32 v64, v64
	s_nop 0
	v_add_f32_e32 v64, 1.0, v64
	v_rcp_f32_e32 v66, v64
	s_nop 0
	v_mul_f32_e32 v64, v89, v66
	v_mul_f32_e32 v64, v73, v64
	v_cvt_pk_bf16_f32 v64, v64, s0
	ds_write_b16 v96, v64 offset:7056
	v_mul_f32_e32 v64, 0xbfb8aa3b, v90
	v_exp_f32_e32 v64, v64
	s_nop 0
	v_add_f32_e32 v64, 1.0, v64
	v_rcp_f32_e32 v66, v64
	s_nop 0
	v_mul_f32_e32 v64, v90, v66
	v_mul_f32_e32 v64, v74, v64
	v_cvt_pk_bf16_f32 v64, v64, s0
	ds_write_b16 v96, v64 offset:7200
	v_mul_f32_e32 v64, 0xbfb8aa3b, v91
	v_exp_f32_e32 v64, v64
	s_nop 0
	v_add_f32_e32 v64, 1.0, v64
	v_rcp_f32_e32 v66, v64
	s_nop 0
	v_mul_f32_e32 v64, v91, v66
	v_mul_f32_e32 v64, v75, v64
	v_cvt_pk_bf16_f32 v64, v64, s0
	ds_write_b16 v96, v64 offset:7344
	v_mul_f32_e32 v64, 0xbfb8aa3b, v92
	v_exp_f32_e32 v64, v64
	s_nop 0
	v_add_f32_e32 v64, 1.0, v64
	v_rcp_f32_e32 v66, v64
	s_nop 0
	v_mul_f32_e32 v64, v92, v66
	v_mul_f32_e32 v64, v76, v64
	v_cvt_pk_bf16_f32 v64, v64, s0
	ds_write_b16 v96, v64 offset:8064
	v_mul_f32_e32 v64, 0xbfb8aa3b, v93
	v_exp_f32_e32 v64, v64
	s_nop 0
	v_add_f32_e32 v64, 1.0, v64
	v_rcp_f32_e32 v66, v64
	s_nop 0
	v_mul_f32_e32 v64, v93, v66
	v_mul_f32_e32 v64, v77, v64
	v_cvt_pk_bf16_f32 v64, v64, s0
	ds_write_b16 v96, v64 offset:8208
	v_mul_f32_e32 v64, 0xbfb8aa3b, v94
	v_exp_f32_e32 v64, v64
	s_nop 0
	v_add_f32_e32 v64, 1.0, v64
	v_rcp_f32_e32 v66, v64
	s_nop 0
	v_mul_f32_e32 v64, v94, v66
	v_mul_f32_e32 v64, v78, v64
	v_cvt_pk_bf16_f32 v64, v64, s0
	ds_write_b16 v96, v64 offset:8352
	v_mul_f32_e32 v64, 0xbfb8aa3b, v95
	v_exp_f32_e32 v64, v64
	s_nop 0
	v_add_f32_e32 v64, 1.0, v64
	v_rcp_f32_e32 v66, v64
	s_nop 0
	v_mul_f32_e32 v64, v95, v66
	v_mul_f32_e32 v64, v79, v64
	v_cvt_pk_bf16_f32 v64, v64, s0
	ds_write_b16 v96, v64 offset:8496
	v_ashrrev_i32_e32 v68, 4, v131
	s_waitcnt lgkmcnt(0)
	v_ashrrev_i32_e32 v69, 31, v68
	ds_read_b128 v[72:75], v128
	v_mad_i64_i32 v[64:65], s[0:1], v71, s23, v[68:69]
	v_lshlrev_b64 v[64:65], 10, v[64:65]
	v_lshlrev_b32_e32 v66, 6, v181
	v_lshl_add_u64 v[64:65], s[66:67], 0, v[64:65]
	v_and_b32_e32 v176, 0x200, v66
	v_lshl_add_u64 v[76:77], v[64:65], 0, v[176:177]
	v_lshlrev_b32_e32 v66, 4, v129
	v_mov_b32_e32 v67, v177
	v_lshl_add_u64 v[64:65], v[76:77], 0, v[66:67]
	s_waitcnt lgkmcnt(0)
	global_store_dwordx4 v[64:65], v[72:75], off
	ds_read_b128 v[72:75], v128 offset:2304
	v_or_b32_e32 v64, 0x100, v66
	v_mov_b32_e32 v65, v177
	v_lshl_add_u64 v[76:77], v[76:77], 0, v[64:65]
	s_waitcnt lgkmcnt(0)
	global_store_dwordx4 v[76:77], v[72:75], off
	ds_read_b128 v[72:75], v128 offset:4608
	v_mad_i64_i32 v[76:77], s[0:1], v70, s23, v[68:69]
	v_lshlrev_b64 v[76:77], 10, v[76:77]
	v_lshl_add_u64 v[76:77], s[66:67], 0, v[76:77]
	v_lshl_add_u64 v[76:77], v[76:77], 0, v[176:177]
	v_lshl_add_u64 v[78:79], v[76:77], 0, v[66:67]
	v_mul_f32_e32 v69, 0xbfb8aa3b, v48
	s_waitcnt lgkmcnt(0)
	global_store_dwordx4 v[78:79], v[72:75], off
	ds_read_b128 v[72:75], v128 offset:6912
	v_exp_f32_e32 v69, v69
	v_lshl_add_u64 v[76:77], v[76:77], 0, v[64:65]
	v_add_f32_e32 v69, 1.0, v69
	s_waitcnt lgkmcnt(0)
	global_store_dwordx4 v[76:77], v[72:75], off
	s_waitcnt lgkmcnt(0)
	s_nop 1
	v_rcp_f32_e32 v73, v69
	s_nop 0
	v_mul_f32_e32 v48, v48, v73
	v_mul_f32_e32 v32, v32, v48
	v_cvt_pk_bf16_f32 v32, v32, s0
	ds_write_b16 v96, v32
	v_mul_f32_e32 v32, 0xbfb8aa3b, v49
	v_exp_f32_e32 v32, v32
	s_nop 0
	v_add_f32_e32 v32, 1.0, v32
	v_rcp_f32_e32 v69, v32
	s_nop 0
	v_mul_f32_e32 v32, v49, v69
	v_mul_f32_e32 v32, v33, v32
	v_cvt_pk_bf16_f32 v32, v32, s0
	ds_write_b16 v96, v32 offset:144
	v_mul_f32_e32 v32, 0xbfb8aa3b, v50
	v_exp_f32_e32 v32, v32
	s_nop 0
	v_add_f32_e32 v32, 1.0, v32
	v_rcp_f32_e32 v48, v32
	s_nop 0
	v_mul_f32_e32 v32, v50, v48
	v_mul_f32_e32 v32, v34, v32
	v_cvt_pk_bf16_f32 v32, v32, s0
	ds_write_b16 v96, v32 offset:288
	v_mul_f32_e32 v32, 0xbfb8aa3b, v51
	v_exp_f32_e32 v32, v32
	s_nop 0
	v_add_f32_e32 v32, 1.0, v32
	v_rcp_f32_e32 v34, v32
	s_nop 0
	v_mul_f32_e32 v32, v51, v34
	v_mul_f32_e32 v32, v35, v32
	v_cvt_pk_bf16_f32 v32, v32, s0
	ds_write_b16 v96, v32 offset:432
	v_mul_f32_e32 v32, 0xbfb8aa3b, v52
	v_exp_f32_e32 v32, v32
	s_nop 0
	v_add_f32_e32 v32, 1.0, v32
	v_rcp_f32_e32 v34, v32
	s_nop 0
	v_mul_f32_e32 v32, v52, v34
	v_mul_f32_e32 v32, v36, v32
	v_cvt_pk_bf16_f32 v32, v32, s0
	ds_write_b16 v96, v32 offset:1152
	v_mul_f32_e32 v32, 0xbfb8aa3b, v53
	v_exp_f32_e32 v32, v32
	s_nop 0
	v_add_f32_e32 v32, 1.0, v32
	v_rcp_f32_e32 v34, v32
	s_nop 0
	v_mul_f32_e32 v32, v53, v34
	v_mul_f32_e32 v32, v37, v32
	v_cvt_pk_bf16_f32 v32, v32, s0
	ds_write_b16 v96, v32 offset:1296
	v_mul_f32_e32 v32, 0xbfb8aa3b, v54
	v_exp_f32_e32 v32, v32
	s_nop 0
	v_add_f32_e32 v32, 1.0, v32
	v_rcp_f32_e32 v34, v32
	s_nop 0
	v_mul_f32_e32 v32, v54, v34
	v_mul_f32_e32 v32, v38, v32
	v_cvt_pk_bf16_f32 v32, v32, s0
	ds_write_b16 v96, v32 offset:1440
	v_mul_f32_e32 v32, 0xbfb8aa3b, v55
	v_exp_f32_e32 v32, v32
	s_nop 0
	v_add_f32_e32 v32, 1.0, v32
	v_rcp_f32_e32 v34, v32
	s_nop 0
	v_mul_f32_e32 v32, v55, v34
	v_mul_f32_e32 v32, v39, v32
	v_cvt_pk_bf16_f32 v32, v32, s0
	ds_write_b16 v96, v32 offset:1584
	v_mul_f32_e32 v32, 0xbfb8aa3b, v56
	v_exp_f32_e32 v32, v32
	s_nop 0
	v_add_f32_e32 v32, 1.0, v32
	v_rcp_f32_e32 v34, v32
	s_nop 0
	v_mul_f32_e32 v32, v56, v34
	v_mul_f32_e32 v32, v40, v32
	v_cvt_pk_bf16_f32 v32, v32, s0
	ds_write_b16 v96, v32 offset:2304
	v_mul_f32_e32 v32, 0xbfb8aa3b, v57
	v_exp_f32_e32 v32, v32
	s_nop 0
	v_add_f32_e32 v32, 1.0, v32
	v_rcp_f32_e32 v34, v32
	s_nop 0
	v_mul_f32_e32 v32, v57, v34
	v_mul_f32_e32 v32, v41, v32
	v_cvt_pk_bf16_f32 v32, v32, s0
	ds_write_b16 v96, v32 offset:2448
	v_mul_f32_e32 v32, 0xbfb8aa3b, v58
	v_exp_f32_e32 v32, v32
	s_nop 0
	v_add_f32_e32 v32, 1.0, v32
	v_rcp_f32_e32 v34, v32
	s_nop 0
	v_mul_f32_e32 v32, v58, v34
	v_mul_f32_e32 v32, v42, v32
	v_cvt_pk_bf16_f32 v32, v32, s0
	ds_write_b16 v96, v32 offset:2592
	v_mul_f32_e32 v32, 0xbfb8aa3b, v59
	v_exp_f32_e32 v32, v32
	s_nop 0
	v_add_f32_e32 v32, 1.0, v32
	v_rcp_f32_e32 v34, v32
	s_nop 0
	v_mul_f32_e32 v32, v59, v34
	v_mul_f32_e32 v32, v43, v32
	v_cvt_pk_bf16_f32 v32, v32, s0
	ds_write_b16 v96, v32 offset:2736
	v_mul_f32_e32 v32, 0xbfb8aa3b, v60
	v_exp_f32_e32 v32, v32
	s_nop 0
	v_add_f32_e32 v32, 1.0, v32
	v_rcp_f32_e32 v34, v32
	s_nop 0
	v_mul_f32_e32 v32, v60, v34
	v_mul_f32_e32 v32, v44, v32
	v_cvt_pk_bf16_f32 v32, v32, s0
	ds_write_b16 v96, v32 offset:3456
	v_mul_f32_e32 v32, 0xbfb8aa3b, v61
	v_exp_f32_e32 v32, v32
	s_nop 0
	v_add_f32_e32 v32, 1.0, v32
	v_rcp_f32_e32 v34, v32
	s_nop 0
	v_mul_f32_e32 v32, v61, v34
	v_mul_f32_e32 v32, v45, v32
	v_cvt_pk_bf16_f32 v32, v32, s0
	ds_write_b16 v96, v32 offset:3600
	v_mul_f32_e32 v32, 0xbfb8aa3b, v62
	v_exp_f32_e32 v32, v32
	s_nop 0
	v_add_f32_e32 v32, 1.0, v32
	v_rcp_f32_e32 v34, v32
	s_nop 0
	v_mul_f32_e32 v32, v62, v34
	v_mul_f32_e32 v32, v46, v32
	v_cvt_pk_bf16_f32 v32, v32, s0
	ds_write_b16 v96, v32 offset:3744
	v_mul_f32_e32 v32, 0xbfb8aa3b, v63
	v_exp_f32_e32 v32, v32
	s_nop 0
	v_add_f32_e32 v32, 1.0, v32
	v_rcp_f32_e32 v34, v32
	s_nop 0
	v_mul_f32_e32 v32, v63, v34
	v_mul_f32_e32 v32, v47, v32
	v_cvt_pk_bf16_f32 v32, v32, s0
	ds_write_b16 v96, v32 offset:3888
	v_mul_f32_e32 v32, 0xbfb8aa3b, v16
	v_exp_f32_e32 v32, v32
	s_nop 0
	v_add_f32_e32 v32, 1.0, v32
	v_rcp_f32_e32 v34, v32
	s_nop 0
	v_mul_f32_e32 v16, v16, v34
	v_mul_f32_e32 v0, v0, v16
	v_cvt_pk_bf16_f32 v0, v0, s0
	ds_write_b16 v96, v0 offset:4608
	v_mul_f32_e32 v0, 0xbfb8aa3b, v17
	v_exp_f32_e32 v0, v0
	s_nop 0
	v_add_f32_e32 v0, 1.0, v0
	v_rcp_f32_e32 v32, v0
	s_nop 0
	v_mul_f32_e32 v0, v17, v32
	v_mul_f32_e32 v0, v1, v0
	v_cvt_pk_bf16_f32 v0, v0, s0
	ds_write_b16 v96, v0 offset:4752
	v_mul_f32_e32 v0, 0xbfb8aa3b, v18
	v_exp_f32_e32 v0, v0
	s_nop 0
	v_add_f32_e32 v0, 1.0, v0
	v_rcp_f32_e32 v16, v0
	s_nop 0
	v_mul_f32_e32 v0, v18, v16
	v_mul_f32_e32 v0, v2, v0
	v_cvt_pk_bf16_f32 v0, v0, s0
	ds_write_b16 v96, v0 offset:4896
	v_mul_f32_e32 v0, 0xbfb8aa3b, v19
	v_exp_f32_e32 v0, v0
	s_nop 0
	v_add_f32_e32 v0, 1.0, v0
	v_rcp_f32_e32 v2, v0
	s_nop 0
	v_mul_f32_e32 v0, v19, v2
	v_mul_f32_e32 v0, v3, v0
	v_cvt_pk_bf16_f32 v0, v0, s0
	ds_write_b16 v96, v0 offset:5040
	v_mul_f32_e32 v0, 0xbfb8aa3b, v20
	v_exp_f32_e32 v0, v0
	s_nop 0
	v_add_f32_e32 v0, 1.0, v0
	v_rcp_f32_e32 v2, v0
	s_nop 0
	v_mul_f32_e32 v0, v20, v2
	v_mul_f32_e32 v0, v4, v0
	v_cvt_pk_bf16_f32 v0, v0, s0
	ds_write_b16 v96, v0 offset:5760
	v_mul_f32_e32 v0, 0xbfb8aa3b, v21
	v_exp_f32_e32 v0, v0
	s_nop 0
	v_add_f32_e32 v0, 1.0, v0
	v_rcp_f32_e32 v2, v0
	s_nop 0
	v_mul_f32_e32 v0, v21, v2
	v_mul_f32_e32 v0, v5, v0
	v_cvt_pk_bf16_f32 v0, v0, s0
	ds_write_b16 v96, v0 offset:5904
	v_mul_f32_e32 v0, 0xbfb8aa3b, v22
	v_exp_f32_e32 v0, v0
	s_nop 0
	v_add_f32_e32 v0, 1.0, v0
	v_rcp_f32_e32 v2, v0
	s_nop 0
	v_mul_f32_e32 v0, v22, v2
	v_mul_f32_e32 v0, v6, v0
	v_cvt_pk_bf16_f32 v0, v0, s0
	ds_write_b16 v96, v0 offset:6048
	v_mul_f32_e32 v0, 0xbfb8aa3b, v23
	v_exp_f32_e32 v0, v0
	s_nop 0
	v_add_f32_e32 v0, 1.0, v0
	v_rcp_f32_e32 v2, v0
	s_nop 0
	v_mul_f32_e32 v0, v23, v2
	v_mul_f32_e32 v0, v7, v0
	v_cvt_pk_bf16_f32 v0, v0, s0
	ds_write_b16 v96, v0 offset:6192
	v_mul_f32_e32 v0, 0xbfb8aa3b, v24
	v_exp_f32_e32 v0, v0
	s_nop 0
	v_add_f32_e32 v0, 1.0, v0
	v_rcp_f32_e32 v2, v0
	s_nop 0
	v_mul_f32_e32 v0, v24, v2
	v_mul_f32_e32 v0, v8, v0
	v_cvt_pk_bf16_f32 v0, v0, s0
	ds_write_b16 v96, v0 offset:6912
	v_mul_f32_e32 v0, 0xbfb8aa3b, v25
	v_exp_f32_e32 v0, v0
	s_nop 0
	v_add_f32_e32 v0, 1.0, v0
	v_rcp_f32_e32 v2, v0
	s_nop 0
	v_mul_f32_e32 v0, v25, v2
	v_mul_f32_e32 v0, v9, v0
	v_cvt_pk_bf16_f32 v0, v0, s0
	ds_write_b16 v96, v0 offset:7056
	v_mul_f32_e32 v0, 0xbfb8aa3b, v26
	v_exp_f32_e32 v0, v0
	s_nop 0
	v_add_f32_e32 v0, 1.0, v0
	v_rcp_f32_e32 v2, v0
	s_nop 0
	v_mul_f32_e32 v0, v26, v2
	v_mul_f32_e32 v0, v10, v0
	v_cvt_pk_bf16_f32 v0, v0, s0
	ds_write_b16 v96, v0 offset:7200
	v_mul_f32_e32 v0, 0xbfb8aa3b, v27
	v_exp_f32_e32 v0, v0
	s_nop 0
	v_add_f32_e32 v0, 1.0, v0
	v_rcp_f32_e32 v2, v0
	s_nop 0
	v_mul_f32_e32 v0, v27, v2
	v_mul_f32_e32 v0, v11, v0
	v_cvt_pk_bf16_f32 v0, v0, s0
	ds_write_b16 v96, v0 offset:7344
	v_mul_f32_e32 v0, 0xbfb8aa3b, v28
	v_exp_f32_e32 v0, v0
	s_nop 0
	v_add_f32_e32 v0, 1.0, v0
	v_rcp_f32_e32 v2, v0
	s_nop 0
	v_mul_f32_e32 v0, v28, v2
	v_mul_f32_e32 v0, v12, v0
	v_cvt_pk_bf16_f32 v0, v0, s0
	ds_write_b16 v96, v0 offset:8064
	v_mul_f32_e32 v0, 0xbfb8aa3b, v29
	v_exp_f32_e32 v0, v0
	s_nop 0
	v_add_f32_e32 v0, 1.0, v0
	v_rcp_f32_e32 v2, v0
	s_nop 0
	v_mul_f32_e32 v0, v29, v2
	v_mul_f32_e32 v0, v13, v0
	v_cvt_pk_bf16_f32 v0, v0, s0
	ds_write_b16 v96, v0 offset:8208
	v_mul_f32_e32 v0, 0xbfb8aa3b, v30
	v_exp_f32_e32 v0, v0
	s_nop 0
	v_add_f32_e32 v0, 1.0, v0
	v_rcp_f32_e32 v2, v0
	s_nop 0
	v_mul_f32_e32 v0, v30, v2
	v_mul_f32_e32 v0, v14, v0
	v_cvt_pk_bf16_f32 v0, v0, s0
	ds_write_b16 v96, v0 offset:8352
	v_mul_f32_e32 v0, 0xbfb8aa3b, v31
	v_exp_f32_e32 v0, v0
	s_nop 0
	v_add_f32_e32 v0, 1.0, v0
	v_rcp_f32_e32 v2, v0
	s_nop 0
	v_mul_f32_e32 v0, v31, v2
	v_mul_f32_e32 v0, v15, v0
	v_cvt_pk_bf16_f32 v0, v0, s0
	ds_write_b16 v96, v0 offset:8496
	v_or_b32_e32 v4, 2, v68
	s_waitcnt lgkmcnt(0)
	v_ashrrev_i32_e32 v5, 31, v4
	ds_read_b128 v[0:3], v128
	v_mad_i64_i32 v[6:7], s[0:1], v71, s23, v[4:5]
	v_lshlrev_b64 v[6:7], 10, v[6:7]
	v_lshl_add_u64 v[6:7], s[66:67], 0, v[6:7]
	v_lshl_add_u64 v[6:7], v[6:7], 0, v[176:177]
	v_lshl_add_u64 v[8:9], v[6:7], 0, v[66:67]
	s_waitcnt lgkmcnt(0)
	global_store_dwordx4 v[8:9], v[0:3], off
	ds_read_b128 v[0:3], v128 offset:2304
	v_lshl_add_u64 v[6:7], v[6:7], 0, v[64:65]
	v_mad_i64_i32 v[4:5], s[0:1], v70, s23, v[4:5]
	v_lshlrev_b64 v[4:5], 10, v[4:5]
	s_waitcnt lgkmcnt(0)
	global_store_dwordx4 v[6:7], v[0:3], off
	ds_read_b128 v[0:3], v128 offset:4608
	v_lshl_add_u64 v[4:5], s[66:67], 0, v[4:5]
	v_lshl_add_u64 v[4:5], v[4:5], 0, v[176:177]
	v_lshl_add_u64 v[6:7], v[4:5], 0, v[66:67]
	v_lshl_add_u64 v[4:5], v[4:5], 0, v[64:65]
	s_waitcnt lgkmcnt(0)
	global_store_dwordx4 v[6:7], v[0:3], off
	ds_read_b128 v[0:3], v128 offset:6912
	v_readlane_b32 s0, v254, 11
	s_add_i32 s2, s2, s0
	s_cmp_lt_i32 s2, s3
	s_waitcnt lgkmcnt(0)
	global_store_dwordx4 v[4:5], v[0:3], off
	s_waitcnt lgkmcnt(0)
	s_barrier
	s_cbranch_scc1 .LBB0_1031

.LBB0_1086:
	s_ashr_i32 s6, s2, 31
	s_lshr_b32 s6, s6, 26
	s_add_i32 s6, s2, s6
	s_ashr_i32 s7, s6, 6
	s_lshl_b32 s7, s7, 3
	s_sub_i32 s8, s25, s7
	s_min_i32 s8, s8, 8
	s_abs_i32 s9, s8
	v_cvt_f32_u32_e32 v0, s9
	s_sub_i32 s12, 0, s9
	s_andn2_b32 s6, s6, 63
	s_sub_i32 s10, s2, s6
	v_rcp_iflag_f32_e32 v0, v0
	s_abs_i32 s6, s10
	s_xor_b32 s11, s10, s8
	s_ashr_i32 s11, s11, 31
	v_mul_f32_e32 v0, 0x4f7ffffe, v0
	v_cvt_u32_f32_e32 v0, v0
	v_mov_b32_e32 v181, v179
	v_readfirstlane_b32 s13, v0
	s_mul_i32 s12, s12, s13
	s_mul_hi_u32 s12, s13, s12
	s_add_i32 s13, s13, s12
	s_mul_hi_u32 s12, s6, s13
	s_mul_i32 s13, s12, s9
	s_sub_i32 s6, s6, s13
	s_add_i32 s14, s12, 1
	s_sub_i32 s13, s6, s9
	s_cmp_ge_u32 s6, s9
	s_cselect_b32 s12, s14, s12
	s_cselect_b32 s6, s13, s6
	s_add_i32 s13, s12, 1
	s_cmp_ge_u32 s6, s9
	s_cselect_b32 s6, s13, s12
	s_xor_b32 s6, s6, s11
	s_sub_i32 s6, s6, s11
	s_mul_i32 s8, s8, s6
	s_add_i32 s7, s7, s5
	s_sub_i32 s8, s10, s8
	v_ashrrev_i32_e32 v237, 6, v181
	s_add_i32 s7, s7, s8
	v_lshlrev_b32_e32 v0, 1, v237
	v_bfe_u32 v183, v181, 5, 1
	v_lshl_add_u32 v2, s7, 3, v0
	v_mov_b64_e32 v[0:1], s[66:67]
	v_and_b32_e32 v238, 31, v181
	v_mad_i64_i32 v[0:1], s[8:9], v2, s24, v[0:1]
	v_lshlrev_b32_e32 v176, 9, v183
	v_lshl_add_u64 v[0:1], v[0:1], 0, v[176:177]
	v_lshlrev_b32_e32 v176, 4, v238
	v_ashrrev_i32_e32 v38, 2, v181
	s_mul_i32 s8, s6, 0xb0000
	v_lshl_add_u64 v[184:185], v[0:1], 0, v[176:177]
	s_mul_hi_i32 s9, s6, 0xb0000
	s_add_u32 s8, s3, s8
	v_lshlrev_b32_e32 v0, 5, v38
	s_addc_u32 s9, s4, s9
	v_ashrrev_i32_e32 v1, 31, v0
	v_lshlrev_b32_e32 v2, 4, v181
	v_lshl_add_u64 v[0:1], v[0:1], 1, s[8:9]
	v_and_b32_e32 v176, 48, v2
	v_lshl_add_u64 v[186:187], v[0:1], 0, v[176:177]
	s_movk_i32 s8, 0x2000
	v_add_co_u32_e32 v34, vcc, s8, v186
	v_mul_u32_u24_e32 v36, 40, v238
	s_nop 0
	v_addc_co_u32_e32 v35, vcc, 0, v187, vcc
	v_lshlrev_b32_e32 v37, 4, v183
	v_lshl_add_u32 v240, v36, 1, v37
	v_add_co_u32_e32 v36, vcc, s24, v184
	s_movk_i32 s9, 0x50
	s_nop 0
	v_addc_co_u32_e32 v37, vcc, 0, v185, vcc
	v_and_b32_e32 v239, 63, v181
	v_bfe_u32 v247, v181, 4, 2
	v_lshlrev_b32_e32 v247, 1, v247
	v_mov_b32_e32 v176, 0x78
	v_lshrrev_b32_e32 v247, v247, v176
	v_and_b32_e32 v247, 3, v247
	v_and_b32_e32 v246, 3, v181
	v_xor_b32_e32 v247, v247, v246
	v_lshlrev_b32_e32 v247, 4, v247
	v_and_b32_e32 v188, 0xffffffcf, v186
	v_or_b32_e32 v188, v188, v247
	v_mov_b32_e32 v189, v187
	v_lshrrev_b32_e32 v176, 6, v181
	v_lshlrev_b32_e32 v247, 11, v176
	v_lshlrev_b32_e32 v176, 10, v176
	v_lshl_add_u64 v[188:189], v[188:189], 0, v[176:177]
	v_readfirstlane_b32 vcc_lo, v247
	v_bfe_u32 v247, v181, 4, 1
	v_lshlrev_b32_e32 v176, 9, v183
	v_lshl_add_u32 v176, v247, 8, v176
	v_lshl_add_u64 v[184:185], v[184:185], 0, v[176:177]
	v_mov_b32_e32 v176, s24
	v_lshl_add_u64 v[186:187], v[184:185], 0, v[176:177]
	v_mov_b32_e32 v176, 0x78
	v_bfe_u32 v247, v181, 2, 2
	v_lshlrev_b32_e32 v247, 1, v247
	v_lshrrev_b32_e32 v247, v247, v176
	v_and_b32_e32 v247, 3, v247
	v_bfe_u32 v246, v181, 4, 2
	v_xor_b32_e32 v247, v247, v246
	v_lshlrev_b32_e32 v247, 4, v247
	v_and_b32_e32 v246, 15, v181
	v_lshl_add_u32 v246, v246, 6, v247
	s_mov_b32 s96, 0
	s_mov_b32 m0, vcc_lo
	v_lshl_add_u64 v[160:161], v[188:189], 0, s[96:97]
	global_load_lds_dwordx4 v[160:161], off
	global_load_lds_dwordx4 v[160:161], off offset:1024
	s_mov_b32 s96, 0
	v_lshl_add_u64 v[248:249], v[184:185], 0, s[96:97]
	v_lshl_add_u64 v[250:251], v[186:187], 0, s[96:97]
	global_load_dwordx4 v[128:131], v[248:249], off
	global_load_dwordx4 v[132:135], v[248:249], off offset:256
	global_load_dwordx4 v[136:139], v[250:251], off
	global_load_dwordx4 v[140:143], v[250:251], off offset:256
	s_movk_i32 s96, 0x2000
	s_add_i32 m0, vcc_lo, 8192
	v_lshl_add_u64 v[160:161], v[188:189], 0, s[96:97]
	global_load_lds_dwordx4 v[160:161], off
	global_load_lds_dwordx4 v[160:161], off offset:1024
	s_movk_i32 s96, 0x800
	v_lshl_add_u64 v[248:249], v[184:185], 0, s[96:97]
	v_lshl_add_u64 v[250:251], v[186:187], 0, s[96:97]
	global_load_dwordx4 v[144:147], v[248:249], off
	global_load_dwordx4 v[148:151], v[248:249], off offset:256
	global_load_dwordx4 v[152:155], v[250:251], off
	global_load_dwordx4 v[156:159], v[250:251], off offset:256
	v_mov_b32_e32 v0, 0
	v_mov_b32_e32 v1, 0
	v_mov_b32_e32 v2, 0
	v_mov_b32_e32 v3, 0
	v_mov_b32_e32 v4, 0
	v_mov_b32_e32 v5, 0
	v_mov_b32_e32 v6, 0
	v_mov_b32_e32 v7, 0
	v_mov_b32_e32 v8, 0
	v_mov_b32_e32 v9, 0
	v_mov_b32_e32 v10, 0
	v_mov_b32_e32 v11, 0
	v_mov_b32_e32 v12, 0
	v_mov_b32_e32 v13, 0
	v_mov_b32_e32 v14, 0
	v_mov_b32_e32 v15, 0
	v_mov_b32_e32 v16, 0
	v_mov_b32_e32 v17, 0
	v_mov_b32_e32 v18, 0
	v_mov_b32_e32 v19, 0
	v_mov_b32_e32 v20, 0
	v_mov_b32_e32 v21, 0
	v_mov_b32_e32 v22, 0
	v_mov_b32_e32 v23, 0
	v_mov_b32_e32 v24, 0
	v_mov_b32_e32 v25, 0
	v_mov_b32_e32 v26, 0
	v_mov_b32_e32 v27, 0
	v_mov_b32_e32 v28, 0
	v_mov_b32_e32 v29, 0
	v_mov_b32_e32 v30, 0
	v_mov_b32_e32 v31, 0
	v_mov_b32_e32 v32, 0
	v_mov_b32_e32 v33, 0
	v_mov_b32_e32 v34, 0
	v_mov_b32_e32 v35, 0
	v_mov_b32_e32 v36, 0
	v_mov_b32_e32 v37, 0
	v_mov_b32_e32 v38, 0
	v_mov_b32_e32 v39, 0
	v_mov_b32_e32 v40, 0
	v_mov_b32_e32 v41, 0
	v_mov_b32_e32 v42, 0
	v_mov_b32_e32 v43, 0
	v_mov_b32_e32 v44, 0
	v_mov_b32_e32 v45, 0
	v_mov_b32_e32 v46, 0
	v_mov_b32_e32 v47, 0
	v_mov_b32_e32 v48, 0
	v_mov_b32_e32 v49, 0
	v_mov_b32_e32 v50, 0
	v_mov_b32_e32 v51, 0
	v_mov_b32_e32 v52, 0
	v_mov_b32_e32 v53, 0
	v_mov_b32_e32 v54, 0
	v_mov_b32_e32 v55, 0
	v_mov_b32_e32 v56, 0
	v_mov_b32_e32 v57, 0
	v_mov_b32_e32 v58, 0
	v_mov_b32_e32 v59, 0
	v_mov_b32_e32 v60, 0
	v_mov_b32_e32 v61, 0
	v_mov_b32_e32 v62, 0
	v_mov_b32_e32 v63, 0
	v_mov_b32_e32 v64, 0
	v_mov_b32_e32 v65, 0
	v_mov_b32_e32 v66, 0
	v_mov_b32_e32 v67, 0
	v_mov_b32_e32 v68, 0
	v_mov_b32_e32 v69, 0
	v_mov_b32_e32 v70, 0
	v_mov_b32_e32 v71, 0
	v_mov_b32_e32 v72, 0
	v_mov_b32_e32 v73, 0
	v_mov_b32_e32 v74, 0
	v_mov_b32_e32 v75, 0
	v_mov_b32_e32 v76, 0
	v_mov_b32_e32 v77, 0
	v_mov_b32_e32 v78, 0
	v_mov_b32_e32 v79, 0
	v_mov_b32_e32 v80, 0
	v_mov_b32_e32 v81, 0
	v_mov_b32_e32 v82, 0
	v_mov_b32_e32 v83, 0
	v_mov_b32_e32 v84, 0
	v_mov_b32_e32 v85, 0
	v_mov_b32_e32 v86, 0
	v_mov_b32_e32 v87, 0
	v_mov_b32_e32 v88, 0
	v_mov_b32_e32 v89, 0
	v_mov_b32_e32 v90, 0
	v_mov_b32_e32 v91, 0
	v_mov_b32_e32 v92, 0
	v_mov_b32_e32 v93, 0
	v_mov_b32_e32 v94, 0
	v_mov_b32_e32 v95, 0
	v_mov_b32_e32 v96, 0
	v_mov_b32_e32 v97, 0
	v_mov_b32_e32 v98, 0
	v_mov_b32_e32 v99, 0
	v_mov_b32_e32 v100, 0
	v_mov_b32_e32 v101, 0
	v_mov_b32_e32 v102, 0
	v_mov_b32_e32 v103, 0
	v_mov_b32_e32 v104, 0
	v_mov_b32_e32 v105, 0
	v_mov_b32_e32 v106, 0
	v_mov_b32_e32 v107, 0
	v_mov_b32_e32 v108, 0
	v_mov_b32_e32 v109, 0
	v_mov_b32_e32 v110, 0
	v_mov_b32_e32 v111, 0
	v_mov_b32_e32 v112, 0
	v_mov_b32_e32 v113, 0
	v_mov_b32_e32 v114, 0
	v_mov_b32_e32 v115, 0
	v_mov_b32_e32 v116, 0
	v_mov_b32_e32 v117, 0
	v_mov_b32_e32 v118, 0
	v_mov_b32_e32 v119, 0
	v_mov_b32_e32 v120, 0
	v_mov_b32_e32 v121, 0
	v_mov_b32_e32 v122, 0
	v_mov_b32_e32 v123, 0
	v_mov_b32_e32 v124, 0
	v_mov_b32_e32 v125, 0
	v_mov_b32_e32 v126, 0
	v_mov_b32_e32 v127, 0
	s_mov_b32 s8, 0
	s_waitcnt vmcnt(4)
	s_barrier
.Lg16_down_k:
	s_add_i32 s9, s8, 2
	s_lshl_b32 s96, s9, 13
	s_add_i32 m0, vcc_lo, 16384
	v_lshl_add_u64 v[160:161], v[188:189], 0, s[96:97]
	global_load_lds_dwordx4 v[160:161], off
	global_load_lds_dwordx4 v[160:161], off offset:1024
	ds_read_b128 v[196:199], v246 offset:0
	ds_read_b128 v[200:203], v246 offset:1024
	ds_read_b128 v[204:207], v246 offset:2048
	ds_read_b128 v[242:245], v246 offset:3072
	s_add_i32 s9, s8, 2
	s_lshl_b32 s96, s9, 11
	v_lshl_add_u64 v[248:249], v[184:185], 0, s[96:97]
	v_lshl_add_u64 v[250:251], v[186:187], 0, s[96:97]
	s_waitcnt vmcnt(8) lgkmcnt(3)
	v_mfma_f32_16x16x32_bf16 v[112:115], v[128:131], v[196:199], v[112:115]
	v_mfma_f32_16x16x32_bf16 v[120:123], v[132:135], v[196:199], v[120:123]
	v_mfma_f32_16x16x32_bf16 v[48:51], v[136:139], v[196:199], v[48:51]
	v_mfma_f32_16x16x32_bf16 v[56:59], v[140:143], v[196:199], v[56:59]
	ds_read_b128 v[196:199], v246 offset:4096
	s_waitcnt lgkmcnt(3)
	v_mfma_f32_16x16x32_bf16 v[116:119], v[128:131], v[200:203], v[116:119]
	v_mfma_f32_16x16x32_bf16 v[124:127], v[132:135], v[200:203], v[124:127]
	v_mfma_f32_16x16x32_bf16 v[52:55], v[136:139], v[200:203], v[52:55]
	v_mfma_f32_16x16x32_bf16 v[60:63], v[140:143], v[200:203], v[60:63]
	ds_read_b128 v[200:203], v246 offset:5120
	s_waitcnt lgkmcnt(3)
	v_mfma_f32_16x16x32_bf16 v[96:99], v[128:131], v[204:207], v[96:99]
	v_mfma_f32_16x16x32_bf16 v[104:107], v[132:135], v[204:207], v[104:107]
	v_mfma_f32_16x16x32_bf16 v[32:35], v[136:139], v[204:207], v[32:35]
	v_mfma_f32_16x16x32_bf16 v[40:43], v[140:143], v[204:207], v[40:43]
	ds_read_b128 v[204:207], v246 offset:6144
	s_waitcnt lgkmcnt(3)
	v_mfma_f32_16x16x32_bf16 v[100:103], v[128:131], v[242:245], v[100:103]
	v_mfma_f32_16x16x32_bf16 v[108:111], v[132:135], v[242:245], v[108:111]
	v_mfma_f32_16x16x32_bf16 v[36:39], v[136:139], v[242:245], v[36:39]
	v_mfma_f32_16x16x32_bf16 v[44:47], v[140:143], v[242:245], v[44:47]
	ds_read_b128 v[242:245], v246 offset:7168
	s_waitcnt lgkmcnt(3)
	v_mfma_f32_16x16x32_bf16 v[80:83], v[128:131], v[196:199], v[80:83]
	v_mfma_f32_16x16x32_bf16 v[88:91], v[132:135], v[196:199], v[88:91]
	v_mfma_f32_16x16x32_bf16 v[16:19], v[136:139], v[196:199], v[16:19]
	v_mfma_f32_16x16x32_bf16 v[24:27], v[140:143], v[196:199], v[24:27]
	s_waitcnt lgkmcnt(2)
	v_mfma_f32_16x16x32_bf16 v[84:87], v[128:131], v[200:203], v[84:87]
	v_mfma_f32_16x16x32_bf16 v[92:95], v[132:135], v[200:203], v[92:95]
	v_mfma_f32_16x16x32_bf16 v[20:23], v[136:139], v[200:203], v[20:23]
	v_mfma_f32_16x16x32_bf16 v[28:31], v[140:143], v[200:203], v[28:31]
	s_waitcnt lgkmcnt(1)
	v_mfma_f32_16x16x32_bf16 v[64:67], v[128:131], v[204:207], v[64:67]
	v_mfma_f32_16x16x32_bf16 v[72:75], v[132:135], v[204:207], v[72:75]
	v_mfma_f32_16x16x32_bf16 v[0:3], v[136:139], v[204:207], v[0:3]
	v_mfma_f32_16x16x32_bf16 v[8:11], v[140:143], v[204:207], v[8:11]
	s_waitcnt lgkmcnt(0)
	v_mfma_f32_16x16x32_bf16 v[68:71], v[128:131], v[242:245], v[68:71]
	v_mfma_f32_16x16x32_bf16 v[76:79], v[132:135], v[242:245], v[76:79]
	v_mfma_f32_16x16x32_bf16 v[4:7], v[136:139], v[242:245], v[4:7]
	v_mfma_f32_16x16x32_bf16 v[12:15], v[140:143], v[242:245], v[12:15]
	global_load_dwordx4 v[128:131], v[248:249], off
	global_load_dwordx4 v[132:135], v[248:249], off offset:256
	global_load_dwordx4 v[136:139], v[250:251], off
	global_load_dwordx4 v[140:143], v[250:251], off offset:256
	s_waitcnt vmcnt(10)
	s_barrier
	s_add_i32 s9, s8, 3
	s_lshl_b32 s96, s9, 13
	s_mov_b32 m0, vcc_lo
	v_lshl_add_u64 v[160:161], v[188:189], 0, s[96:97]
	global_load_lds_dwordx4 v[160:161], off
	global_load_lds_dwordx4 v[160:161], off offset:1024
	ds_read_b128 v[196:199], v246 offset:8192
	ds_read_b128 v[200:203], v246 offset:9216
	ds_read_b128 v[204:207], v246 offset:10240
	ds_read_b128 v[242:245], v246 offset:11264
	s_add_i32 s9, s8, 3
	s_lshl_b32 s96, s9, 11
	v_lshl_add_u64 v[248:249], v[184:185], 0, s[96:97]
	v_lshl_add_u64 v[250:251], v[186:187], 0, s[96:97]
	s_waitcnt vmcnt(8) lgkmcnt(3)
	v_mfma_f32_16x16x32_bf16 v[112:115], v[144:147], v[196:199], v[112:115]
	v_mfma_f32_16x16x32_bf16 v[120:123], v[148:151], v[196:199], v[120:123]
	v_mfma_f32_16x16x32_bf16 v[48:51], v[152:155], v[196:199], v[48:51]
	v_mfma_f32_16x16x32_bf16 v[56:59], v[156:159], v[196:199], v[56:59]
	ds_read_b128 v[196:199], v246 offset:12288
	s_waitcnt lgkmcnt(3)
	v_mfma_f32_16x16x32_bf16 v[116:119], v[144:147], v[200:203], v[116:119]
	v_mfma_f32_16x16x32_bf16 v[124:127], v[148:151], v[200:203], v[124:127]
	v_mfma_f32_16x16x32_bf16 v[52:55], v[152:155], v[200:203], v[52:55]
	v_mfma_f32_16x16x32_bf16 v[60:63], v[156:159], v[200:203], v[60:63]
	ds_read_b128 v[200:203], v246 offset:13312
	s_waitcnt lgkmcnt(3)
	v_mfma_f32_16x16x32_bf16 v[96:99], v[144:147], v[204:207], v[96:99]
	v_mfma_f32_16x16x32_bf16 v[104:107], v[148:151], v[204:207], v[104:107]
	v_mfma_f32_16x16x32_bf16 v[32:35], v[152:155], v[204:207], v[32:35]
	v_mfma_f32_16x16x32_bf16 v[40:43], v[156:159], v[204:207], v[40:43]
	ds_read_b128 v[204:207], v246 offset:14336
	s_waitcnt lgkmcnt(3)
	v_mfma_f32_16x16x32_bf16 v[100:103], v[144:147], v[242:245], v[100:103]
	v_mfma_f32_16x16x32_bf16 v[108:111], v[148:151], v[242:245], v[108:111]
	v_mfma_f32_16x16x32_bf16 v[36:39], v[152:155], v[242:245], v[36:39]
	v_mfma_f32_16x16x32_bf16 v[44:47], v[156:159], v[242:245], v[44:47]
	ds_read_b128 v[242:245], v246 offset:15360
	s_waitcnt lgkmcnt(3)
	v_mfma_f32_16x16x32_bf16 v[80:83], v[144:147], v[196:199], v[80:83]
	v_mfma_f32_16x16x32_bf16 v[88:91], v[148:151], v[196:199], v[88:91]
	v_mfma_f32_16x16x32_bf16 v[16:19], v[152:155], v[196:199], v[16:19]
	v_mfma_f32_16x16x32_bf16 v[24:27], v[156:159], v[196:199], v[24:27]
	s_waitcnt lgkmcnt(2)
	v_mfma_f32_16x16x32_bf16 v[84:87], v[144:147], v[200:203], v[84:87]
	v_mfma_f32_16x16x32_bf16 v[92:95], v[148:151], v[200:203], v[92:95]
	v_mfma_f32_16x16x32_bf16 v[20:23], v[152:155], v[200:203], v[20:23]
	v_mfma_f32_16x16x32_bf16 v[28:31], v[156:159], v[200:203], v[28:31]
	s_waitcnt lgkmcnt(1)
	v_mfma_f32_16x16x32_bf16 v[64:67], v[144:147], v[204:207], v[64:67]
	v_mfma_f32_16x16x32_bf16 v[72:75], v[148:151], v[204:207], v[72:75]
	v_mfma_f32_16x16x32_bf16 v[0:3], v[152:155], v[204:207], v[0:3]
	v_mfma_f32_16x16x32_bf16 v[8:11], v[156:159], v[204:207], v[8:11]
	s_waitcnt lgkmcnt(0)
	v_mfma_f32_16x16x32_bf16 v[68:71], v[144:147], v[242:245], v[68:71]
	v_mfma_f32_16x16x32_bf16 v[76:79], v[148:151], v[242:245], v[76:79]
	v_mfma_f32_16x16x32_bf16 v[4:7], v[152:155], v[242:245], v[4:7]
	v_mfma_f32_16x16x32_bf16 v[12:15], v[156:159], v[242:245], v[12:15]
	global_load_dwordx4 v[144:147], v[248:249], off
	global_load_dwordx4 v[148:151], v[248:249], off offset:256
	global_load_dwordx4 v[152:155], v[250:251], off
	global_load_dwordx4 v[156:159], v[250:251], off offset:256
	s_waitcnt vmcnt(10)
	s_barrier
	s_add_i32 s9, s8, 4
	s_lshl_b32 s96, s9, 13
	s_add_i32 m0, vcc_lo, 8192
	v_lshl_add_u64 v[160:161], v[188:189], 0, s[96:97]
	global_load_lds_dwordx4 v[160:161], off
	global_load_lds_dwordx4 v[160:161], off offset:1024
	ds_read_b128 v[196:199], v246 offset:16384
	ds_read_b128 v[200:203], v246 offset:17408
	ds_read_b128 v[204:207], v246 offset:18432
	ds_read_b128 v[242:245], v246 offset:19456
	s_add_i32 s9, s8, 4
	s_lshl_b32 s96, s9, 11
	v_lshl_add_u64 v[248:249], v[184:185], 0, s[96:97]
	v_lshl_add_u64 v[250:251], v[186:187], 0, s[96:97]
	s_waitcnt vmcnt(8) lgkmcnt(3)
	v_mfma_f32_16x16x32_bf16 v[112:115], v[128:131], v[196:199], v[112:115]
	v_mfma_f32_16x16x32_bf16 v[120:123], v[132:135], v[196:199], v[120:123]
	v_mfma_f32_16x16x32_bf16 v[48:51], v[136:139], v[196:199], v[48:51]
	v_mfma_f32_16x16x32_bf16 v[56:59], v[140:143], v[196:199], v[56:59]
	ds_read_b128 v[196:199], v246 offset:20480
	s_waitcnt lgkmcnt(3)
	v_mfma_f32_16x16x32_bf16 v[116:119], v[128:131], v[200:203], v[116:119]
	v_mfma_f32_16x16x32_bf16 v[124:127], v[132:135], v[200:203], v[124:127]
	v_mfma_f32_16x16x32_bf16 v[52:55], v[136:139], v[200:203], v[52:55]
	v_mfma_f32_16x16x32_bf16 v[60:63], v[140:143], v[200:203], v[60:63]
	ds_read_b128 v[200:203], v246 offset:21504
	s_waitcnt lgkmcnt(3)
	v_mfma_f32_16x16x32_bf16 v[96:99], v[128:131], v[204:207], v[96:99]
	v_mfma_f32_16x16x32_bf16 v[104:107], v[132:135], v[204:207], v[104:107]
	v_mfma_f32_16x16x32_bf16 v[32:35], v[136:139], v[204:207], v[32:35]
	v_mfma_f32_16x16x32_bf16 v[40:43], v[140:143], v[204:207], v[40:43]
	ds_read_b128 v[204:207], v246 offset:22528
	s_waitcnt lgkmcnt(3)
	v_mfma_f32_16x16x32_bf16 v[100:103], v[128:131], v[242:245], v[100:103]
	v_mfma_f32_16x16x32_bf16 v[108:111], v[132:135], v[242:245], v[108:111]
	v_mfma_f32_16x16x32_bf16 v[36:39], v[136:139], v[242:245], v[36:39]
	v_mfma_f32_16x16x32_bf16 v[44:47], v[140:143], v[242:245], v[44:47]
	ds_read_b128 v[242:245], v246 offset:23552
	s_waitcnt lgkmcnt(3)
	v_mfma_f32_16x16x32_bf16 v[80:83], v[128:131], v[196:199], v[80:83]
	v_mfma_f32_16x16x32_bf16 v[88:91], v[132:135], v[196:199], v[88:91]
	v_mfma_f32_16x16x32_bf16 v[16:19], v[136:139], v[196:199], v[16:19]
	v_mfma_f32_16x16x32_bf16 v[24:27], v[140:143], v[196:199], v[24:27]
	s_waitcnt lgkmcnt(2)
	v_mfma_f32_16x16x32_bf16 v[84:87], v[128:131], v[200:203], v[84:87]
	v_mfma_f32_16x16x32_bf16 v[92:95], v[132:135], v[200:203], v[92:95]
	v_mfma_f32_16x16x32_bf16 v[20:23], v[136:139], v[200:203], v[20:23]
	v_mfma_f32_16x16x32_bf16 v[28:31], v[140:143], v[200:203], v[28:31]
	s_waitcnt lgkmcnt(1)
	v_mfma_f32_16x16x32_bf16 v[64:67], v[128:131], v[204:207], v[64:67]
	v_mfma_f32_16x16x32_bf16 v[72:75], v[132:135], v[204:207], v[72:75]
	v_mfma_f32_16x16x32_bf16 v[0:3], v[136:139], v[204:207], v[0:3]
	v_mfma_f32_16x16x32_bf16 v[8:11], v[140:143], v[204:207], v[8:11]
	s_waitcnt lgkmcnt(0)
	v_mfma_f32_16x16x32_bf16 v[68:71], v[128:131], v[242:245], v[68:71]
	v_mfma_f32_16x16x32_bf16 v[76:79], v[132:135], v[242:245], v[76:79]
	v_mfma_f32_16x16x32_bf16 v[4:7], v[136:139], v[242:245], v[4:7]
	v_mfma_f32_16x16x32_bf16 v[12:15], v[140:143], v[242:245], v[12:15]
	global_load_dwordx4 v[128:131], v[248:249], off
	global_load_dwordx4 v[132:135], v[248:249], off offset:256
	global_load_dwordx4 v[136:139], v[250:251], off
	global_load_dwordx4 v[140:143], v[250:251], off offset:256
	s_waitcnt vmcnt(10)
	s_barrier
	s_add_i32 s9, s8, 5
	s_lshl_b32 s96, s9, 13
	s_add_i32 m0, vcc_lo, 16384
	v_lshl_add_u64 v[160:161], v[188:189], 0, s[96:97]
	global_load_lds_dwordx4 v[160:161], off
	global_load_lds_dwordx4 v[160:161], off offset:1024
	ds_read_b128 v[196:199], v246 offset:0
	ds_read_b128 v[200:203], v246 offset:1024
	ds_read_b128 v[204:207], v246 offset:2048
	ds_read_b128 v[242:245], v246 offset:3072
	s_add_i32 s9, s8, 5
	s_lshl_b32 s96, s9, 11
	v_lshl_add_u64 v[248:249], v[184:185], 0, s[96:97]
	v_lshl_add_u64 v[250:251], v[186:187], 0, s[96:97]
	s_waitcnt vmcnt(8) lgkmcnt(3)
	v_mfma_f32_16x16x32_bf16 v[112:115], v[144:147], v[196:199], v[112:115]
	v_mfma_f32_16x16x32_bf16 v[120:123], v[148:151], v[196:199], v[120:123]
	v_mfma_f32_16x16x32_bf16 v[48:51], v[152:155], v[196:199], v[48:51]
	v_mfma_f32_16x16x32_bf16 v[56:59], v[156:159], v[196:199], v[56:59]
	ds_read_b128 v[196:199], v246 offset:4096
	s_waitcnt lgkmcnt(3)
	v_mfma_f32_16x16x32_bf16 v[116:119], v[144:147], v[200:203], v[116:119]
	v_mfma_f32_16x16x32_bf16 v[124:127], v[148:151], v[200:203], v[124:127]
	v_mfma_f32_16x16x32_bf16 v[52:55], v[152:155], v[200:203], v[52:55]
	v_mfma_f32_16x16x32_bf16 v[60:63], v[156:159], v[200:203], v[60:63]
	ds_read_b128 v[200:203], v246 offset:5120
	s_waitcnt lgkmcnt(3)
	v_mfma_f32_16x16x32_bf16 v[96:99], v[144:147], v[204:207], v[96:99]
	v_mfma_f32_16x16x32_bf16 v[104:107], v[148:151], v[204:207], v[104:107]
	v_mfma_f32_16x16x32_bf16 v[32:35], v[152:155], v[204:207], v[32:35]
	v_mfma_f32_16x16x32_bf16 v[40:43], v[156:159], v[204:207], v[40:43]
	ds_read_b128 v[204:207], v246 offset:6144
	s_waitcnt lgkmcnt(3)
	v_mfma_f32_16x16x32_bf16 v[100:103], v[144:147], v[242:245], v[100:103]
	v_mfma_f32_16x16x32_bf16 v[108:111], v[148:151], v[242:245], v[108:111]
	v_mfma_f32_16x16x32_bf16 v[36:39], v[152:155], v[242:245], v[36:39]
	v_mfma_f32_16x16x32_bf16 v[44:47], v[156:159], v[242:245], v[44:47]
	ds_read_b128 v[242:245], v246 offset:7168
	s_waitcnt lgkmcnt(3)
	v_mfma_f32_16x16x32_bf16 v[80:83], v[144:147], v[196:199], v[80:83]
	v_mfma_f32_16x16x32_bf16 v[88:91], v[148:151], v[196:199], v[88:91]
	v_mfma_f32_16x16x32_bf16 v[16:19], v[152:155], v[196:199], v[16:19]
	v_mfma_f32_16x16x32_bf16 v[24:27], v[156:159], v[196:199], v[24:27]
	s_waitcnt lgkmcnt(2)
	v_mfma_f32_16x16x32_bf16 v[84:87], v[144:147], v[200:203], v[84:87]
	v_mfma_f32_16x16x32_bf16 v[92:95], v[148:151], v[200:203], v[92:95]
	v_mfma_f32_16x16x32_bf16 v[20:23], v[152:155], v[200:203], v[20:23]
	v_mfma_f32_16x16x32_bf16 v[28:31], v[156:159], v[200:203], v[28:31]
	s_waitcnt lgkmcnt(1)
	v_mfma_f32_16x16x32_bf16 v[64:67], v[144:147], v[204:207], v[64:67]
	v_mfma_f32_16x16x32_bf16 v[72:75], v[148:151], v[204:207], v[72:75]
	v_mfma_f32_16x16x32_bf16 v[0:3], v[152:155], v[204:207], v[0:3]
	v_mfma_f32_16x16x32_bf16 v[8:11], v[156:159], v[204:207], v[8:11]
	s_waitcnt lgkmcnt(0)
	v_mfma_f32_16x16x32_bf16 v[68:71], v[144:147], v[242:245], v[68:71]
	v_mfma_f32_16x16x32_bf16 v[76:79], v[148:151], v[242:245], v[76:79]
	v_mfma_f32_16x16x32_bf16 v[4:7], v[152:155], v[242:245], v[4:7]
	v_mfma_f32_16x16x32_bf16 v[12:15], v[156:159], v[242:245], v[12:15]
	global_load_dwordx4 v[144:147], v[248:249], off
	global_load_dwordx4 v[148:151], v[248:249], off offset:256
	global_load_dwordx4 v[152:155], v[250:251], off
	global_load_dwordx4 v[156:159], v[250:251], off offset:256
	s_waitcnt vmcnt(10)
	s_barrier
	s_add_i32 s9, s8, 6
	s_lshl_b32 s96, s9, 13
	s_mov_b32 m0, vcc_lo
	v_lshl_add_u64 v[160:161], v[188:189], 0, s[96:97]
	global_load_lds_dwordx4 v[160:161], off
	global_load_lds_dwordx4 v[160:161], off offset:1024
	ds_read_b128 v[196:199], v246 offset:8192
	ds_read_b128 v[200:203], v246 offset:9216
	ds_read_b128 v[204:207], v246 offset:10240
	ds_read_b128 v[242:245], v246 offset:11264
	s_add_i32 s9, s8, 6
	s_lshl_b32 s96, s9, 11
	v_lshl_add_u64 v[248:249], v[184:185], 0, s[96:97]
	v_lshl_add_u64 v[250:251], v[186:187], 0, s[96:97]
	s_waitcnt vmcnt(8) lgkmcnt(3)
	v_mfma_f32_16x16x32_bf16 v[112:115], v[128:131], v[196:199], v[112:115]
	v_mfma_f32_16x16x32_bf16 v[120:123], v[132:135], v[196:199], v[120:123]
	v_mfma_f32_16x16x32_bf16 v[48:51], v[136:139], v[196:199], v[48:51]
	v_mfma_f32_16x16x32_bf16 v[56:59], v[140:143], v[196:199], v[56:59]
	ds_read_b128 v[196:199], v246 offset:12288
	s_waitcnt lgkmcnt(3)
	v_mfma_f32_16x16x32_bf16 v[116:119], v[128:131], v[200:203], v[116:119]
	v_mfma_f32_16x16x32_bf16 v[124:127], v[132:135], v[200:203], v[124:127]
	v_mfma_f32_16x16x32_bf16 v[52:55], v[136:139], v[200:203], v[52:55]
	v_mfma_f32_16x16x32_bf16 v[60:63], v[140:143], v[200:203], v[60:63]
	ds_read_b128 v[200:203], v246 offset:13312
	s_waitcnt lgkmcnt(3)
	v_mfma_f32_16x16x32_bf16 v[96:99], v[128:131], v[204:207], v[96:99]
	v_mfma_f32_16x16x32_bf16 v[104:107], v[132:135], v[204:207], v[104:107]
	v_mfma_f32_16x16x32_bf16 v[32:35], v[136:139], v[204:207], v[32:35]
	v_mfma_f32_16x16x32_bf16 v[40:43], v[140:143], v[204:207], v[40:43]
	ds_read_b128 v[204:207], v246 offset:14336
	s_waitcnt lgkmcnt(3)
	v_mfma_f32_16x16x32_bf16 v[100:103], v[128:131], v[242:245], v[100:103]
	v_mfma_f32_16x16x32_bf16 v[108:111], v[132:135], v[242:245], v[108:111]
	v_mfma_f32_16x16x32_bf16 v[36:39], v[136:139], v[242:245], v[36:39]
	v_mfma_f32_16x16x32_bf16 v[44:47], v[140:143], v[242:245], v[44:47]
	ds_read_b128 v[242:245], v246 offset:15360
	s_waitcnt lgkmcnt(3)
	v_mfma_f32_16x16x32_bf16 v[80:83], v[128:131], v[196:199], v[80:83]
	v_mfma_f32_16x16x32_bf16 v[88:91], v[132:135], v[196:199], v[88:91]
	v_mfma_f32_16x16x32_bf16 v[16:19], v[136:139], v[196:199], v[16:19]
	v_mfma_f32_16x16x32_bf16 v[24:27], v[140:143], v[196:199], v[24:27]
	s_waitcnt lgkmcnt(2)
	v_mfma_f32_16x16x32_bf16 v[84:87], v[128:131], v[200:203], v[84:87]
	v_mfma_f32_16x16x32_bf16 v[92:95], v[132:135], v[200:203], v[92:95]
	v_mfma_f32_16x16x32_bf16 v[20:23], v[136:139], v[200:203], v[20:23]
	v_mfma_f32_16x16x32_bf16 v[28:31], v[140:143], v[200:203], v[28:31]
	s_waitcnt lgkmcnt(1)
	v_mfma_f32_16x16x32_bf16 v[64:67], v[128:131], v[204:207], v[64:67]
	v_mfma_f32_16x16x32_bf16 v[72:75], v[132:135], v[204:207], v[72:75]
	v_mfma_f32_16x16x32_bf16 v[0:3], v[136:139], v[204:207], v[0:3]
	v_mfma_f32_16x16x32_bf16 v[8:11], v[140:143], v[204:207], v[8:11]
	s_waitcnt lgkmcnt(0)
	v_mfma_f32_16x16x32_bf16 v[68:71], v[128:131], v[242:245], v[68:71]
	v_mfma_f32_16x16x32_bf16 v[76:79], v[132:135], v[242:245], v[76:79]
	v_mfma_f32_16x16x32_bf16 v[4:7], v[136:139], v[242:245], v[4:7]
	v_mfma_f32_16x16x32_bf16 v[12:15], v[140:143], v[242:245], v[12:15]
	global_load_dwordx4 v[128:131], v[248:249], off
	global_load_dwordx4 v[132:135], v[248:249], off offset:256
	global_load_dwordx4 v[136:139], v[250:251], off
	global_load_dwordx4 v[140:143], v[250:251], off offset:256
	s_waitcnt vmcnt(10)
	s_barrier
	s_add_i32 s9, s8, 7
	s_lshl_b32 s96, s9, 13
	s_add_i32 m0, vcc_lo, 8192
	v_lshl_add_u64 v[160:161], v[188:189], 0, s[96:97]
	global_load_lds_dwordx4 v[160:161], off
	global_load_lds_dwordx4 v[160:161], off offset:1024
	ds_read_b128 v[196:199], v246 offset:16384
	ds_read_b128 v[200:203], v246 offset:17408
	ds_read_b128 v[204:207], v246 offset:18432
	ds_read_b128 v[242:245], v246 offset:19456
	s_add_i32 s9, s8, 7
	s_lshl_b32 s96, s9, 11
	v_lshl_add_u64 v[248:249], v[184:185], 0, s[96:97]
	v_lshl_add_u64 v[250:251], v[186:187], 0, s[96:97]
	s_waitcnt vmcnt(8) lgkmcnt(3)
	v_mfma_f32_16x16x32_bf16 v[112:115], v[144:147], v[196:199], v[112:115]
	v_mfma_f32_16x16x32_bf16 v[120:123], v[148:151], v[196:199], v[120:123]
	v_mfma_f32_16x16x32_bf16 v[48:51], v[152:155], v[196:199], v[48:51]
	v_mfma_f32_16x16x32_bf16 v[56:59], v[156:159], v[196:199], v[56:59]
	ds_read_b128 v[196:199], v246 offset:20480
	s_waitcnt lgkmcnt(3)
	v_mfma_f32_16x16x32_bf16 v[116:119], v[144:147], v[200:203], v[116:119]
	v_mfma_f32_16x16x32_bf16 v[124:127], v[148:151], v[200:203], v[124:127]
	v_mfma_f32_16x16x32_bf16 v[52:55], v[152:155], v[200:203], v[52:55]
	v_mfma_f32_16x16x32_bf16 v[60:63], v[156:159], v[200:203], v[60:63]
	ds_read_b128 v[200:203], v246 offset:21504
	s_waitcnt lgkmcnt(3)
	v_mfma_f32_16x16x32_bf16 v[96:99], v[144:147], v[204:207], v[96:99]
	v_mfma_f32_16x16x32_bf16 v[104:107], v[148:151], v[204:207], v[104:107]
	v_mfma_f32_16x16x32_bf16 v[32:35], v[152:155], v[204:207], v[32:35]
	v_mfma_f32_16x16x32_bf16 v[40:43], v[156:159], v[204:207], v[40:43]
	ds_read_b128 v[204:207], v246 offset:22528
	s_waitcnt lgkmcnt(3)
	v_mfma_f32_16x16x32_bf16 v[100:103], v[144:147], v[242:245], v[100:103]
	v_mfma_f32_16x16x32_bf16 v[108:111], v[148:151], v[242:245], v[108:111]
	v_mfma_f32_16x16x32_bf16 v[36:39], v[152:155], v[242:245], v[36:39]
	v_mfma_f32_16x16x32_bf16 v[44:47], v[156:159], v[242:245], v[44:47]
	ds_read_b128 v[242:245], v246 offset:23552
	s_waitcnt lgkmcnt(3)
	v_mfma_f32_16x16x32_bf16 v[80:83], v[144:147], v[196:199], v[80:83]
	v_mfma_f32_16x16x32_bf16 v[88:91], v[148:151], v[196:199], v[88:91]
	v_mfma_f32_16x16x32_bf16 v[16:19], v[152:155], v[196:199], v[16:19]
	v_mfma_f32_16x16x32_bf16 v[24:27], v[156:159], v[196:199], v[24:27]
	s_waitcnt lgkmcnt(2)
	v_mfma_f32_16x16x32_bf16 v[84:87], v[144:147], v[200:203], v[84:87]
	v_mfma_f32_16x16x32_bf16 v[92:95], v[148:151], v[200:203], v[92:95]
	v_mfma_f32_16x16x32_bf16 v[20:23], v[152:155], v[200:203], v[20:23]
	v_mfma_f32_16x16x32_bf16 v[28:31], v[156:159], v[200:203], v[28:31]
	s_waitcnt lgkmcnt(1)
	v_mfma_f32_16x16x32_bf16 v[64:67], v[144:147], v[204:207], v[64:67]
	v_mfma_f32_16x16x32_bf16 v[72:75], v[148:151], v[204:207], v[72:75]
	v_mfma_f32_16x16x32_bf16 v[0:3], v[152:155], v[204:207], v[0:3]
	v_mfma_f32_16x16x32_bf16 v[8:11], v[156:159], v[204:207], v[8:11]
	s_waitcnt lgkmcnt(0)
	v_mfma_f32_16x16x32_bf16 v[68:71], v[144:147], v[242:245], v[68:71]
	v_mfma_f32_16x16x32_bf16 v[76:79], v[148:151], v[242:245], v[76:79]
	v_mfma_f32_16x16x32_bf16 v[4:7], v[152:155], v[242:245], v[4:7]
	v_mfma_f32_16x16x32_bf16 v[12:15], v[156:159], v[242:245], v[12:15]
	global_load_dwordx4 v[144:147], v[248:249], off
	global_load_dwordx4 v[148:151], v[248:249], off offset:256
	global_load_dwordx4 v[152:155], v[250:251], off
	global_load_dwordx4 v[156:159], v[250:251], off offset:256
	s_waitcnt vmcnt(10)
	s_barrier
	s_add_i32 s8, s8, 6
	s_cmp_lt_u32 s8, 84
	s_cbranch_scc1 .Lg16_down_k
	s_mov_b32 s96, 0xac000
	s_add_i32 m0, vcc_lo, 16384
	v_lshl_add_u64 v[160:161], v[188:189], 0, s[96:97]
	global_load_lds_dwordx4 v[160:161], off
	global_load_lds_dwordx4 v[160:161], off offset:1024
	ds_read_b128 v[196:199], v246 offset:0
	ds_read_b128 v[200:203], v246 offset:1024
	ds_read_b128 v[204:207], v246 offset:2048
	ds_read_b128 v[242:245], v246 offset:3072
	s_mov_b32 s96, 0x2b000
	v_lshl_add_u64 v[248:249], v[184:185], 0, s[96:97]
	v_lshl_add_u64 v[250:251], v[186:187], 0, s[96:97]
	s_waitcnt vmcnt(8) lgkmcnt(3)
	v_mfma_f32_16x16x32_bf16 v[112:115], v[128:131], v[196:199], v[112:115]
	v_mfma_f32_16x16x32_bf16 v[120:123], v[132:135], v[196:199], v[120:123]
	v_mfma_f32_16x16x32_bf16 v[48:51], v[136:139], v[196:199], v[48:51]
	v_mfma_f32_16x16x32_bf16 v[56:59], v[140:143], v[196:199], v[56:59]
	ds_read_b128 v[196:199], v246 offset:4096
	s_waitcnt lgkmcnt(3)
	v_mfma_f32_16x16x32_bf16 v[116:119], v[128:131], v[200:203], v[116:119]
	v_mfma_f32_16x16x32_bf16 v[124:127], v[132:135], v[200:203], v[124:127]
	v_mfma_f32_16x16x32_bf16 v[52:55], v[136:139], v[200:203], v[52:55]
	v_mfma_f32_16x16x32_bf16 v[60:63], v[140:143], v[200:203], v[60:63]
	ds_read_b128 v[200:203], v246 offset:5120
	s_waitcnt lgkmcnt(3)
	v_mfma_f32_16x16x32_bf16 v[96:99], v[128:131], v[204:207], v[96:99]
	v_mfma_f32_16x16x32_bf16 v[104:107], v[132:135], v[204:207], v[104:107]
	v_mfma_f32_16x16x32_bf16 v[32:35], v[136:139], v[204:207], v[32:35]
	v_mfma_f32_16x16x32_bf16 v[40:43], v[140:143], v[204:207], v[40:43]
	ds_read_b128 v[204:207], v246 offset:6144
	s_waitcnt lgkmcnt(3)
	v_mfma_f32_16x16x32_bf16 v[100:103], v[128:131], v[242:245], v[100:103]
	v_mfma_f32_16x16x32_bf16 v[108:111], v[132:135], v[242:245], v[108:111]
	v_mfma_f32_16x16x32_bf16 v[36:39], v[136:139], v[242:245], v[36:39]
	v_mfma_f32_16x16x32_bf16 v[44:47], v[140:143], v[242:245], v[44:47]
	ds_read_b128 v[242:245], v246 offset:7168
	s_waitcnt lgkmcnt(3)
	v_mfma_f32_16x16x32_bf16 v[80:83], v[128:131], v[196:199], v[80:83]
	v_mfma_f32_16x16x32_bf16 v[88:91], v[132:135], v[196:199], v[88:91]
	v_mfma_f32_16x16x32_bf16 v[16:19], v[136:139], v[196:199], v[16:19]
	v_mfma_f32_16x16x32_bf16 v[24:27], v[140:143], v[196:199], v[24:27]
	s_waitcnt lgkmcnt(2)
	v_mfma_f32_16x16x32_bf16 v[84:87], v[128:131], v[200:203], v[84:87]
	v_mfma_f32_16x16x32_bf16 v[92:95], v[132:135], v[200:203], v[92:95]
	v_mfma_f32_16x16x32_bf16 v[20:23], v[136:139], v[200:203], v[20:23]
	v_mfma_f32_16x16x32_bf16 v[28:31], v[140:143], v[200:203], v[28:31]
	s_waitcnt lgkmcnt(1)
	v_mfma_f32_16x16x32_bf16 v[64:67], v[128:131], v[204:207], v[64:67]
	v_mfma_f32_16x16x32_bf16 v[72:75], v[132:135], v[204:207], v[72:75]
	v_mfma_f32_16x16x32_bf16 v[0:3], v[136:139], v[204:207], v[0:3]
	v_mfma_f32_16x16x32_bf16 v[8:11], v[140:143], v[204:207], v[8:11]
	s_waitcnt lgkmcnt(0)
	v_mfma_f32_16x16x32_bf16 v[68:71], v[128:131], v[242:245], v[68:71]
	v_mfma_f32_16x16x32_bf16 v[76:79], v[132:135], v[242:245], v[76:79]
	v_mfma_f32_16x16x32_bf16 v[4:7], v[136:139], v[242:245], v[4:7]
	v_mfma_f32_16x16x32_bf16 v[12:15], v[140:143], v[242:245], v[12:15]
	global_load_dwordx4 v[128:131], v[248:249], off
	global_load_dwordx4 v[132:135], v[248:249], off offset:256
	global_load_dwordx4 v[136:139], v[250:251], off
	global_load_dwordx4 v[140:143], v[250:251], off offset:256
	s_waitcnt vmcnt(10)
	s_barrier
	s_mov_b32 s96, 0xae000
	s_mov_b32 m0, vcc_lo
	v_lshl_add_u64 v[160:161], v[188:189], 0, s[96:97]
	global_load_lds_dwordx4 v[160:161], off
	global_load_lds_dwordx4 v[160:161], off offset:1024
	ds_read_b128 v[196:199], v246 offset:8192
	ds_read_b128 v[200:203], v246 offset:9216
	ds_read_b128 v[204:207], v246 offset:10240
	ds_read_b128 v[242:245], v246 offset:11264
	s_mov_b32 s96, 0x2b800
	v_lshl_add_u64 v[248:249], v[184:185], 0, s[96:97]
	v_lshl_add_u64 v[250:251], v[186:187], 0, s[96:97]
	s_waitcnt vmcnt(8) lgkmcnt(3)
	v_mfma_f32_16x16x32_bf16 v[112:115], v[144:147], v[196:199], v[112:115]
	v_mfma_f32_16x16x32_bf16 v[120:123], v[148:151], v[196:199], v[120:123]
	v_mfma_f32_16x16x32_bf16 v[48:51], v[152:155], v[196:199], v[48:51]
	v_mfma_f32_16x16x32_bf16 v[56:59], v[156:159], v[196:199], v[56:59]
	ds_read_b128 v[196:199], v246 offset:12288
	s_waitcnt lgkmcnt(3)
	v_mfma_f32_16x16x32_bf16 v[116:119], v[144:147], v[200:203], v[116:119]
	v_mfma_f32_16x16x32_bf16 v[124:127], v[148:151], v[200:203], v[124:127]
	v_mfma_f32_16x16x32_bf16 v[52:55], v[152:155], v[200:203], v[52:55]
	v_mfma_f32_16x16x32_bf16 v[60:63], v[156:159], v[200:203], v[60:63]
	ds_read_b128 v[200:203], v246 offset:13312
	s_waitcnt lgkmcnt(3)
	v_mfma_f32_16x16x32_bf16 v[96:99], v[144:147], v[204:207], v[96:99]
	v_mfma_f32_16x16x32_bf16 v[104:107], v[148:151], v[204:207], v[104:107]
	v_mfma_f32_16x16x32_bf16 v[32:35], v[152:155], v[204:207], v[32:35]
	v_mfma_f32_16x16x32_bf16 v[40:43], v[156:159], v[204:207], v[40:43]
	ds_read_b128 v[204:207], v246 offset:14336
	s_waitcnt lgkmcnt(3)
	v_mfma_f32_16x16x32_bf16 v[100:103], v[144:147], v[242:245], v[100:103]
	v_mfma_f32_16x16x32_bf16 v[108:111], v[148:151], v[242:245], v[108:111]
	v_mfma_f32_16x16x32_bf16 v[36:39], v[152:155], v[242:245], v[36:39]
	v_mfma_f32_16x16x32_bf16 v[44:47], v[156:159], v[242:245], v[44:47]
	ds_read_b128 v[242:245], v246 offset:15360
	s_waitcnt lgkmcnt(3)
	v_mfma_f32_16x16x32_bf16 v[80:83], v[144:147], v[196:199], v[80:83]
	v_mfma_f32_16x16x32_bf16 v[88:91], v[148:151], v[196:199], v[88:91]
	v_mfma_f32_16x16x32_bf16 v[16:19], v[152:155], v[196:199], v[16:19]
	v_mfma_f32_16x16x32_bf16 v[24:27], v[156:159], v[196:199], v[24:27]
	s_waitcnt lgkmcnt(2)
	v_mfma_f32_16x16x32_bf16 v[84:87], v[144:147], v[200:203], v[84:87]
	v_mfma_f32_16x16x32_bf16 v[92:95], v[148:151], v[200:203], v[92:95]
	v_mfma_f32_16x16x32_bf16 v[20:23], v[152:155], v[200:203], v[20:23]
	v_mfma_f32_16x16x32_bf16 v[28:31], v[156:159], v[200:203], v[28:31]
	s_waitcnt lgkmcnt(1)
	v_mfma_f32_16x16x32_bf16 v[64:67], v[144:147], v[204:207], v[64:67]
	v_mfma_f32_16x16x32_bf16 v[72:75], v[148:151], v[204:207], v[72:75]
	v_mfma_f32_16x16x32_bf16 v[0:3], v[152:155], v[204:207], v[0:3]
	v_mfma_f32_16x16x32_bf16 v[8:11], v[156:159], v[204:207], v[8:11]
	s_waitcnt lgkmcnt(0)
	v_mfma_f32_16x16x32_bf16 v[68:71], v[144:147], v[242:245], v[68:71]
	v_mfma_f32_16x16x32_bf16 v[76:79], v[148:151], v[242:245], v[76:79]
	v_mfma_f32_16x16x32_bf16 v[4:7], v[152:155], v[242:245], v[4:7]
	v_mfma_f32_16x16x32_bf16 v[12:15], v[156:159], v[242:245], v[12:15]
	global_load_dwordx4 v[144:147], v[248:249], off
	global_load_dwordx4 v[148:151], v[248:249], off offset:256
	global_load_dwordx4 v[152:155], v[250:251], off
	global_load_dwordx4 v[156:159], v[250:251], off offset:256
	s_waitcnt vmcnt(10)
	s_barrier
	ds_read_b128 v[196:199], v246 offset:16384
	ds_read_b128 v[200:203], v246 offset:17408
	ds_read_b128 v[204:207], v246 offset:18432
	ds_read_b128 v[242:245], v246 offset:19456
	s_waitcnt vmcnt(6) lgkmcnt(3)
	v_mfma_f32_16x16x32_bf16 v[112:115], v[128:131], v[196:199], v[112:115]
	v_mfma_f32_16x16x32_bf16 v[120:123], v[132:135], v[196:199], v[120:123]
	v_mfma_f32_16x16x32_bf16 v[48:51], v[136:139], v[196:199], v[48:51]
	v_mfma_f32_16x16x32_bf16 v[56:59], v[140:143], v[196:199], v[56:59]
	ds_read_b128 v[196:199], v246 offset:20480
	s_waitcnt lgkmcnt(3)
	v_mfma_f32_16x16x32_bf16 v[116:119], v[128:131], v[200:203], v[116:119]
	v_mfma_f32_16x16x32_bf16 v[124:127], v[132:135], v[200:203], v[124:127]
	v_mfma_f32_16x16x32_bf16 v[52:55], v[136:139], v[200:203], v[52:55]
	v_mfma_f32_16x16x32_bf16 v[60:63], v[140:143], v[200:203], v[60:63]
	ds_read_b128 v[200:203], v246 offset:21504
	s_waitcnt lgkmcnt(3)
	v_mfma_f32_16x16x32_bf16 v[96:99], v[128:131], v[204:207], v[96:99]
	v_mfma_f32_16x16x32_bf16 v[104:107], v[132:135], v[204:207], v[104:107]
	v_mfma_f32_16x16x32_bf16 v[32:35], v[136:139], v[204:207], v[32:35]
	v_mfma_f32_16x16x32_bf16 v[40:43], v[140:143], v[204:207], v[40:43]
	ds_read_b128 v[204:207], v246 offset:22528
	s_waitcnt lgkmcnt(3)
	v_mfma_f32_16x16x32_bf16 v[100:103], v[128:131], v[242:245], v[100:103]
	v_mfma_f32_16x16x32_bf16 v[108:111], v[132:135], v[242:245], v[108:111]
	v_mfma_f32_16x16x32_bf16 v[36:39], v[136:139], v[242:245], v[36:39]
	v_mfma_f32_16x16x32_bf16 v[44:47], v[140:143], v[242:245], v[44:47]
	ds_read_b128 v[242:245], v246 offset:23552
	s_waitcnt lgkmcnt(3)
	v_mfma_f32_16x16x32_bf16 v[80:83], v[128:131], v[196:199], v[80:83]
	v_mfma_f32_16x16x32_bf16 v[88:91], v[132:135], v[196:199], v[88:91]
	v_mfma_f32_16x16x32_bf16 v[16:19], v[136:139], v[196:199], v[16:19]
	v_mfma_f32_16x16x32_bf16 v[24:27], v[140:143], v[196:199], v[24:27]
	s_waitcnt lgkmcnt(2)
	v_mfma_f32_16x16x32_bf16 v[84:87], v[128:131], v[200:203], v[84:87]
	v_mfma_f32_16x16x32_bf16 v[92:95], v[132:135], v[200:203], v[92:95]
	v_mfma_f32_16x16x32_bf16 v[20:23], v[136:139], v[200:203], v[20:23]
	v_mfma_f32_16x16x32_bf16 v[28:31], v[140:143], v[200:203], v[28:31]
	s_waitcnt lgkmcnt(1)
	v_mfma_f32_16x16x32_bf16 v[64:67], v[128:131], v[204:207], v[64:67]
	v_mfma_f32_16x16x32_bf16 v[72:75], v[132:135], v[204:207], v[72:75]
	v_mfma_f32_16x16x32_bf16 v[0:3], v[136:139], v[204:207], v[0:3]
	v_mfma_f32_16x16x32_bf16 v[8:11], v[140:143], v[204:207], v[8:11]
	s_waitcnt lgkmcnt(0)
	v_mfma_f32_16x16x32_bf16 v[68:71], v[128:131], v[242:245], v[68:71]
	v_mfma_f32_16x16x32_bf16 v[76:79], v[132:135], v[242:245], v[76:79]
	v_mfma_f32_16x16x32_bf16 v[4:7], v[136:139], v[242:245], v[4:7]
	v_mfma_f32_16x16x32_bf16 v[12:15], v[140:143], v[242:245], v[12:15]
	s_waitcnt vmcnt(4)
	s_barrier
	ds_read_b128 v[196:199], v246 offset:0
	ds_read_b128 v[200:203], v246 offset:1024
	ds_read_b128 v[204:207], v246 offset:2048
	ds_read_b128 v[242:245], v246 offset:3072
	s_waitcnt vmcnt(0) lgkmcnt(3)
	v_mfma_f32_16x16x32_bf16 v[112:115], v[144:147], v[196:199], v[112:115]
	v_mfma_f32_16x16x32_bf16 v[120:123], v[148:151], v[196:199], v[120:123]
	v_mfma_f32_16x16x32_bf16 v[48:51], v[152:155], v[196:199], v[48:51]
	v_mfma_f32_16x16x32_bf16 v[56:59], v[156:159], v[196:199], v[56:59]
	ds_read_b128 v[196:199], v246 offset:4096
	s_waitcnt lgkmcnt(3)
	v_mfma_f32_16x16x32_bf16 v[116:119], v[144:147], v[200:203], v[116:119]
	v_mfma_f32_16x16x32_bf16 v[124:127], v[148:151], v[200:203], v[124:127]
	v_mfma_f32_16x16x32_bf16 v[52:55], v[152:155], v[200:203], v[52:55]
	v_mfma_f32_16x16x32_bf16 v[60:63], v[156:159], v[200:203], v[60:63]
	ds_read_b128 v[200:203], v246 offset:5120
	s_waitcnt lgkmcnt(3)
	v_mfma_f32_16x16x32_bf16 v[96:99], v[144:147], v[204:207], v[96:99]
	v_mfma_f32_16x16x32_bf16 v[104:107], v[148:151], v[204:207], v[104:107]
	v_mfma_f32_16x16x32_bf16 v[32:35], v[152:155], v[204:207], v[32:35]
	v_mfma_f32_16x16x32_bf16 v[40:43], v[156:159], v[204:207], v[40:43]
	ds_read_b128 v[204:207], v246 offset:6144
	s_waitcnt lgkmcnt(3)
	v_mfma_f32_16x16x32_bf16 v[100:103], v[144:147], v[242:245], v[100:103]
	v_mfma_f32_16x16x32_bf16 v[108:111], v[148:151], v[242:245], v[108:111]
	v_mfma_f32_16x16x32_bf16 v[36:39], v[152:155], v[242:245], v[36:39]
	v_mfma_f32_16x16x32_bf16 v[44:47], v[156:159], v[242:245], v[44:47]
	ds_read_b128 v[242:245], v246 offset:7168
	s_waitcnt lgkmcnt(3)
	v_mfma_f32_16x16x32_bf16 v[80:83], v[144:147], v[196:199], v[80:83]
	v_mfma_f32_16x16x32_bf16 v[88:91], v[148:151], v[196:199], v[88:91]
	v_mfma_f32_16x16x32_bf16 v[16:19], v[152:155], v[196:199], v[16:19]
	v_mfma_f32_16x16x32_bf16 v[24:27], v[156:159], v[196:199], v[24:27]
	s_waitcnt lgkmcnt(2)
	v_mfma_f32_16x16x32_bf16 v[84:87], v[144:147], v[200:203], v[84:87]
	v_mfma_f32_16x16x32_bf16 v[92:95], v[148:151], v[200:203], v[92:95]
	v_mfma_f32_16x16x32_bf16 v[20:23], v[152:155], v[200:203], v[20:23]
	v_mfma_f32_16x16x32_bf16 v[28:31], v[156:159], v[200:203], v[28:31]
	s_waitcnt lgkmcnt(1)
	v_mfma_f32_16x16x32_bf16 v[64:67], v[144:147], v[204:207], v[64:67]
	v_mfma_f32_16x16x32_bf16 v[72:75], v[148:151], v[204:207], v[72:75]
	v_mfma_f32_16x16x32_bf16 v[0:3], v[152:155], v[204:207], v[0:3]
	v_mfma_f32_16x16x32_bf16 v[8:11], v[156:159], v[204:207], v[8:11]
	s_waitcnt lgkmcnt(0)
	v_mfma_f32_16x16x32_bf16 v[68:71], v[144:147], v[242:245], v[68:71]
	v_mfma_f32_16x16x32_bf16 v[76:79], v[148:151], v[242:245], v[76:79]
	v_mfma_f32_16x16x32_bf16 v[4:7], v[152:155], v[242:245], v[4:7]
	v_mfma_f32_16x16x32_bf16 v[12:15], v[156:159], v[242:245], v[12:15]
	s_barrier
	s_nop 7
	v_permlane16_swap_b32_e32 v112, v116
	v_permlane16_swap_b32_e32 v113, v117
	v_permlane16_swap_b32_e32 v114, v118
	v_permlane16_swap_b32_e32 v115, v119
	v_permlane16_swap_b32_e32 v120, v124
	v_permlane16_swap_b32_e32 v121, v125
	v_permlane16_swap_b32_e32 v122, v126
	v_permlane16_swap_b32_e32 v123, v127
	v_permlane16_swap_b32_e32 v96, v100
	v_permlane16_swap_b32_e32 v97, v101
	v_permlane16_swap_b32_e32 v98, v102
	v_permlane16_swap_b32_e32 v99, v103
	v_permlane16_swap_b32_e32 v104, v108
	v_permlane16_swap_b32_e32 v105, v109
	v_permlane16_swap_b32_e32 v106, v110
	v_permlane16_swap_b32_e32 v107, v111
	v_permlane16_swap_b32_e32 v80, v84
	v_permlane16_swap_b32_e32 v81, v85
	v_permlane16_swap_b32_e32 v82, v86
	v_permlane16_swap_b32_e32 v83, v87
	v_permlane16_swap_b32_e32 v88, v92
	v_permlane16_swap_b32_e32 v89, v93
	v_permlane16_swap_b32_e32 v90, v94
	v_permlane16_swap_b32_e32 v91, v95
	v_permlane16_swap_b32_e32 v64, v68
	v_permlane16_swap_b32_e32 v65, v69
	v_permlane16_swap_b32_e32 v66, v70
	v_permlane16_swap_b32_e32 v67, v71
	v_permlane16_swap_b32_e32 v72, v76
	v_permlane16_swap_b32_e32 v73, v77
	v_permlane16_swap_b32_e32 v74, v78
	v_permlane16_swap_b32_e32 v75, v79
	v_permlane16_swap_b32_e32 v48, v52
	v_permlane16_swap_b32_e32 v49, v53
	v_permlane16_swap_b32_e32 v50, v54
	v_permlane16_swap_b32_e32 v51, v55
	v_permlane16_swap_b32_e32 v56, v60
	v_permlane16_swap_b32_e32 v57, v61
	v_permlane16_swap_b32_e32 v58, v62
	v_permlane16_swap_b32_e32 v59, v63
	v_permlane16_swap_b32_e32 v32, v36
	v_permlane16_swap_b32_e32 v33, v37
	v_permlane16_swap_b32_e32 v34, v38
	v_permlane16_swap_b32_e32 v35, v39
	v_permlane16_swap_b32_e32 v40, v44
	v_permlane16_swap_b32_e32 v41, v45
	v_permlane16_swap_b32_e32 v42, v46
	v_permlane16_swap_b32_e32 v43, v47
	v_permlane16_swap_b32_e32 v16, v20
	v_permlane16_swap_b32_e32 v17, v21
	v_permlane16_swap_b32_e32 v18, v22
	v_permlane16_swap_b32_e32 v19, v23
	v_permlane16_swap_b32_e32 v24, v28
	v_permlane16_swap_b32_e32 v25, v29
	v_permlane16_swap_b32_e32 v26, v30
	v_permlane16_swap_b32_e32 v27, v31
	v_permlane16_swap_b32_e32 v0, v4
	v_permlane16_swap_b32_e32 v1, v5
	v_permlane16_swap_b32_e32 v2, v6
	v_permlane16_swap_b32_e32 v3, v7
	v_permlane16_swap_b32_e32 v8, v12
	v_permlane16_swap_b32_e32 v9, v13
	v_permlane16_swap_b32_e32 v10, v14
	v_permlane16_swap_b32_e32 v11, v15
	v_permlane32_swap_b32_e32 v112, v116
	v_permlane32_swap_b32_e32 v113, v117
	v_permlane32_swap_b32_e32 v114, v118
	v_permlane32_swap_b32_e32 v115, v119
	v_permlane32_swap_b32_e32 v120, v124
	v_permlane32_swap_b32_e32 v121, v125
	v_permlane32_swap_b32_e32 v122, v126
	v_permlane32_swap_b32_e32 v123, v127
	v_permlane32_swap_b32_e32 v96, v100
	v_permlane32_swap_b32_e32 v97, v101
	v_permlane32_swap_b32_e32 v98, v102
	v_permlane32_swap_b32_e32 v99, v103
	v_permlane32_swap_b32_e32 v104, v108
	v_permlane32_swap_b32_e32 v105, v109
	v_permlane32_swap_b32_e32 v106, v110
	v_permlane32_swap_b32_e32 v107, v111
	v_permlane32_swap_b32_e32 v80, v84
	v_permlane32_swap_b32_e32 v81, v85
	v_permlane32_swap_b32_e32 v82, v86
	v_permlane32_swap_b32_e32 v83, v87
	v_permlane32_swap_b32_e32 v88, v92
	v_permlane32_swap_b32_e32 v89, v93
	v_permlane32_swap_b32_e32 v90, v94
	v_permlane32_swap_b32_e32 v91, v95
	v_permlane32_swap_b32_e32 v64, v68
	v_permlane32_swap_b32_e32 v65, v69
	v_permlane32_swap_b32_e32 v66, v70
	v_permlane32_swap_b32_e32 v67, v71
	v_permlane32_swap_b32_e32 v72, v76
	v_permlane32_swap_b32_e32 v73, v77
	v_permlane32_swap_b32_e32 v74, v78
	v_permlane32_swap_b32_e32 v75, v79
	v_permlane32_swap_b32_e32 v48, v52
	v_permlane32_swap_b32_e32 v49, v53
	v_permlane32_swap_b32_e32 v50, v54
	v_permlane32_swap_b32_e32 v51, v55
	v_permlane32_swap_b32_e32 v56, v60
	v_permlane32_swap_b32_e32 v57, v61
	v_permlane32_swap_b32_e32 v58, v62
	v_permlane32_swap_b32_e32 v59, v63
	v_permlane32_swap_b32_e32 v32, v36
	v_permlane32_swap_b32_e32 v33, v37
	v_permlane32_swap_b32_e32 v34, v38
	v_permlane32_swap_b32_e32 v35, v39
	v_permlane32_swap_b32_e32 v40, v44
	v_permlane32_swap_b32_e32 v41, v45
	v_permlane32_swap_b32_e32 v42, v46
	v_permlane32_swap_b32_e32 v43, v47
	v_permlane32_swap_b32_e32 v16, v20
	v_permlane32_swap_b32_e32 v17, v21
	v_permlane32_swap_b32_e32 v18, v22
	v_permlane32_swap_b32_e32 v19, v23
	v_permlane32_swap_b32_e32 v24, v28
	v_permlane32_swap_b32_e32 v25, v29
	v_permlane32_swap_b32_e32 v26, v30
	v_permlane32_swap_b32_e32 v27, v31
	v_permlane32_swap_b32_e32 v0, v4
	v_permlane32_swap_b32_e32 v1, v5
	v_permlane32_swap_b32_e32 v2, v6
	v_permlane32_swap_b32_e32 v3, v7
	v_permlane32_swap_b32_e32 v8, v12
	v_permlane32_swap_b32_e32 v9, v13
	v_permlane32_swap_b32_e32 v10, v14
	v_permlane32_swap_b32_e32 v11, v15
	s_waitcnt vmcnt(0)
	s_movk_i32 s8, 0x2400
	s_waitcnt vmcnt(0)
	v_and_b32_e32 v132, 0xffffffc0, v181
	v_mul_lo_u32 v129, v237, s8
	v_lshlrev_b32_e32 v130, 2, v238
	v_lshl_add_u32 v156, s7, 8, v132
	v_mul_u32_u24_e32 v132, 0x110, v183
	v_or_b32_e32 v131, v129, v130
	v_lshlrev_b32_e32 v132, 2, v132
	v_add_u32_e32 v131, v131, v132
	v_add3_u32 v132, v129, v132, v130
	v_readlane_b32 s8, v253, 36
	v_lshlrev_b32_e32 v128, 2, v181
	v_add_u32_e32 v133, 0x800, v131
	v_add_u32_e32 v134, 0x800, v132
	v_lshrrev_b32_e32 v155, 4, v239
	v_readlane_b32 s12, v253, 40
	v_readlane_b32 s13, v253, 41
	v_readlane_b32 s14, v253, 42
	v_readlane_b32 s15, v253, 43
	v_readlane_b32 s16, v253, 44
	v_readlane_b32 s17, v253, 45
	v_readlane_b32 s18, v253, 46
	v_readlane_b32 s19, v253, 47
	v_and_b32_e32 v128, 60, v128
	ds_write2_b32 v131, v112, v113 offset1:68
	ds_write2_b32 v132, v96, v97 offset0:32 offset1:100
	ds_write2_b32 v131, v114, v115 offset0:136 offset1:204
	ds_write2_b32 v132, v98, v99 offset0:168 offset1:236
	ds_write2_b32 v133, v116, v117 offset0:32 offset1:100
	ds_write2_b32 v134, v100, v101 offset0:64 offset1:132
	ds_write2_b32 v133, v118, v119 offset0:168 offset1:236
	v_or_b32_e32 v100, v156, v155
	v_readlane_b32 s20, v253, 48
	v_readlane_b32 s21, v253, 49
	v_readlane_b32 s22, v253, 50
	v_readlane_b32 s23, v253, 51
	s_mov_b64 s[12:13], s[16:17]
	v_lshl_or_b32 v144, v128, 2, v129
	v_lshl_or_b32 v128, s6, 7, v128
	s_movk_i32 s6, 0x110
	v_cmp_gt_i32_e32 vcc, s39, v100
	v_add_u32_e32 v96, 0xffff8000, v100
	v_ashrrev_i32_e32 v97, 31, v100
	s_mov_b64 s[14:15], s[18:19]
	v_mad_u32_u24 v130, v155, s6, v144
	v_cndmask_b32_e32 v97, 0, v97, vcc
	v_cndmask_b32_e32 v96, v96, v100, vcc
	v_mov_b32_e32 v144, s63
	v_mov_b32_e32 v145, s15
	v_mov_b32_e32 v146, s62
	v_mov_b32_e32 v147, s14
	v_min_i32_e32 v100, 0x8000, v100
	v_add_u32_e32 v135, 0xa00, v132
	v_add_u32_e32 v136, 0x1000, v131
	v_add_u32_e32 v137, 0x1000, v132
	v_add_u32_e32 v138, 0x1200, v131
	v_add_u32_e32 v139, 0x1200, v132
	v_add_u32_e32 v140, 0x1800, v131
	v_add_u32_e32 v141, 0x1800, v132
	v_add_u32_e32 v142, 0x1a00, v131
	v_add_u32_e32 v143, 0x1c00, v132
	v_ashrrev_i32_e32 v129, 31, v128
	v_cndmask_b32_e32 v99, v144, v145, vcc
	v_cndmask_b32_e32 v98, v146, v147, vcc
	v_lshlrev_b64 v[96:97], 12, v[96:97]
	v_ashrrev_i32_e32 v100, 12, v100
	ds_write2_b32 v135, v102, v103 offset0:72 offset1:140
	ds_write2_b32 v136, v120, v121 offset0:64 offset1:132
	ds_write2_b32 v137, v104, v105 offset0:96 offset1:164
	ds_write2_b32 v138, v122, v123 offset0:72 offset1:140
	ds_write2_b32 v139, v106, v107 offset0:104 offset1:172
	ds_write2_b32 v140, v124, v125 offset0:96 offset1:164
	ds_write2_b32 v141, v108, v109 offset0:128 offset1:196
	ds_write2_b32 v142, v126, v127 offset0:104 offset1:172
	ds_write2_b32 v143, v110, v111 offset0:8 offset1:76
	v_lshl_add_u64 v[98:99], v[98:99], 0, v[96:97]
	v_lshlrev_b64 v[96:97], 2, v[128:129]
	v_mul_hi_i32_i24_e32 v101, 0x6000, v100
	v_mul_i32_i24_e32 v100, 0x6000, v100
	s_waitcnt lgkmcnt(0)
	v_lshl_add_u64 v[98:99], v[98:99], 0, v[96:97]
	v_lshl_add_u64 v[100:101], s[0:1], 0, v[100:101]
	v_lshl_add_u64 v[100:101], v[100:101], 0, v[96:97]
	ds_read_b128 v[102:105], v130
	global_load_dwordx4 v[106:109], v[98:99], off
	global_load_dwordx4 v[110:113], v[100:101], off
	v_or_b32_e32 v148, 4, v155
	v_or_b32_e32 v149, 8, v155
	v_or_b32_e32 v150, 12, v155
	v_or_b32_e32 v151, 16, v155
	v_or_b32_e32 v152, 20, v155
	v_or_b32_e32 v153, 24, v155
	v_or_b32_e32 v154, 28, v155
	v_or_b32_e32 v157, v156, v154
	v_readlane_b32 s6, v254, 11
	s_add_i32 s2, s2, s6
	s_cmp_lt_i32 s2, s26
	v_readlane_b32 s9, v253, 37
	v_readlane_b32 s10, v253, 38
	v_readlane_b32 s11, v253, 39
	s_mov_b64 s[16:17], s[20:21]
	s_mov_b64 s[18:19], s[22:23]
	s_waitcnt vmcnt(0) lgkmcnt(0)
	v_pk_fma_f32 v[102:103], v[102:103], v[110:111], v[106:107]
	v_pk_fma_f32 v[104:105], v[104:105], v[112:113], v[108:109]
	v_or_b32_e32 v106, v156, v148
	global_store_dwordx4 v[98:99], v[102:105], off
	v_cmp_gt_i32_e32 vcc, s39, v106
	s_nop 0
	v_ashrrev_i32_e32 v102, 31, v106
	v_add_u32_e32 v104, 0xffff8000, v106
	v_cndmask_b32_e32 v103, 0, v102, vcc
	v_cndmask_b32_e32 v102, v104, v106, vcc
	v_cndmask_b32_e32 v105, v144, v145, vcc
	v_cndmask_b32_e32 v104, v146, v147, vcc
	v_lshlrev_b64 v[102:103], 12, v[102:103]
	v_lshl_add_u64 v[102:103], v[104:105], 0, v[102:103]
	v_min_i32_e32 v104, 0x8000, v106
	v_ashrrev_i32_e32 v104, 12, v104
	v_mul_hi_i32_i24_e32 v105, 0x6000, v104
	v_mul_i32_i24_e32 v104, 0x6000, v104
	v_lshl_add_u64 v[102:103], v[102:103], 0, v[96:97]
	v_lshl_add_u64 v[104:105], s[0:1], 0, v[104:105]
	v_lshl_add_u64 v[104:105], v[104:105], 0, v[96:97]
	ds_read_b128 v[106:109], v130 offset:1088
	global_load_dwordx4 v[110:113], v[102:103], off
	global_load_dwordx4 v[114:117], v[104:105], off
	s_waitcnt vmcnt(0) lgkmcnt(0)
	v_pk_fma_f32 v[106:107], v[106:107], v[114:115], v[110:111]
	v_pk_fma_f32 v[108:109], v[108:109], v[116:117], v[112:113]
	v_or_b32_e32 v110, v156, v149
	global_store_dwordx4 v[102:103], v[106:109], off
	v_cmp_gt_i32_e32 vcc, s39, v110
	s_nop 0
	v_ashrrev_i32_e32 v106, 31, v110
	v_add_u32_e32 v108, 0xffff8000, v110
	v_cndmask_b32_e32 v107, 0, v106, vcc
	v_cndmask_b32_e32 v106, v108, v110, vcc
	v_cndmask_b32_e32 v109, v144, v145, vcc
	v_cndmask_b32_e32 v108, v146, v147, vcc
	v_lshlrev_b64 v[106:107], 12, v[106:107]
	v_lshl_add_u64 v[106:107], v[108:109], 0, v[106:107]
	v_min_i32_e32 v108, 0x8000, v110
	v_ashrrev_i32_e32 v108, 12, v108
	v_mul_hi_i32_i24_e32 v109, 0x6000, v108
	v_mul_i32_i24_e32 v108, 0x6000, v108
	v_lshl_add_u64 v[106:107], v[106:107], 0, v[96:97]
	v_lshl_add_u64 v[108:109], s[0:1], 0, v[108:109]
	v_lshl_add_u64 v[108:109], v[108:109], 0, v[96:97]
	ds_read_b128 v[110:113], v130 offset:2176
	global_load_dwordx4 v[114:117], v[106:107], off
	global_load_dwordx4 v[118:121], v[108:109], off
	s_waitcnt vmcnt(0) lgkmcnt(0)
	v_pk_fma_f32 v[110:111], v[110:111], v[118:119], v[114:115]
	v_pk_fma_f32 v[112:113], v[112:113], v[120:121], v[116:117]
	v_or_b32_e32 v114, v156, v150
	global_store_dwordx4 v[106:107], v[110:113], off
	v_cmp_gt_i32_e32 vcc, s39, v114
	s_nop 0
	v_ashrrev_i32_e32 v110, 31, v114
	v_add_u32_e32 v112, 0xffff8000, v114
	v_cndmask_b32_e32 v111, 0, v110, vcc
	v_cndmask_b32_e32 v110, v112, v114, vcc
	v_cndmask_b32_e32 v113, v144, v145, vcc
	v_cndmask_b32_e32 v112, v146, v147, vcc
	v_lshlrev_b64 v[110:111], 12, v[110:111]
	v_lshl_add_u64 v[110:111], v[112:113], 0, v[110:111]
	v_min_i32_e32 v112, 0x8000, v114
	v_ashrrev_i32_e32 v112, 12, v112
	v_mul_hi_i32_i24_e32 v113, 0x6000, v112
	v_mul_i32_i24_e32 v112, 0x6000, v112
	v_lshl_add_u64 v[110:111], v[110:111], 0, v[96:97]
	v_lshl_add_u64 v[112:113], s[0:1], 0, v[112:113]
	v_lshl_add_u64 v[112:113], v[112:113], 0, v[96:97]
	ds_read_b128 v[114:117], v130 offset:3264
	global_load_dwordx4 v[118:121], v[110:111], off
	global_load_dwordx4 v[122:125], v[112:113], off
	s_waitcnt vmcnt(0) lgkmcnt(0)
	v_pk_fma_f32 v[114:115], v[114:115], v[122:123], v[118:119]
	v_pk_fma_f32 v[116:117], v[116:117], v[124:125], v[120:121]
	v_or_b32_e32 v118, v156, v151
	global_store_dwordx4 v[110:111], v[114:117], off
	v_cmp_gt_i32_e32 vcc, s39, v118
	s_nop 0
	v_ashrrev_i32_e32 v114, 31, v118
	v_add_u32_e32 v116, 0xffff8000, v118
	v_cndmask_b32_e32 v115, 0, v114, vcc
	v_cndmask_b32_e32 v114, v116, v118, vcc
	v_cndmask_b32_e32 v117, v144, v145, vcc
	v_cndmask_b32_e32 v116, v146, v147, vcc
	v_lshlrev_b64 v[114:115], 12, v[114:115]
	v_lshl_add_u64 v[114:115], v[116:117], 0, v[114:115]
	v_min_i32_e32 v116, 0x8000, v118
	v_ashrrev_i32_e32 v116, 12, v116
	v_mul_hi_i32_i24_e32 v117, 0x6000, v116
	v_mul_i32_i24_e32 v116, 0x6000, v116
	v_lshl_add_u64 v[114:115], v[114:115], 0, v[96:97]
	v_lshl_add_u64 v[116:117], s[0:1], 0, v[116:117]
	v_lshl_add_u64 v[116:117], v[116:117], 0, v[96:97]
	ds_read_b128 v[118:121], v130 offset:4352
	global_load_dwordx4 v[122:125], v[114:115], off
	global_load_dwordx4 v[126:129], v[116:117], off
	s_waitcnt vmcnt(0) lgkmcnt(0)
	v_pk_fma_f32 v[118:119], v[118:119], v[126:127], v[122:123]
	v_pk_fma_f32 v[120:121], v[120:121], v[128:129], v[124:125]
	v_or_b32_e32 v122, v156, v152
	global_store_dwordx4 v[114:115], v[118:121], off
	v_cmp_gt_i32_e32 vcc, s39, v122
	s_nop 0
	v_ashrrev_i32_e32 v118, 31, v122
	v_add_u32_e32 v120, 0xffff8000, v122
	v_cndmask_b32_e32 v119, 0, v118, vcc
	v_cndmask_b32_e32 v118, v120, v122, vcc
	v_cndmask_b32_e32 v121, v144, v145, vcc
	v_cndmask_b32_e32 v120, v146, v147, vcc
	v_lshlrev_b64 v[118:119], 12, v[118:119]
	v_lshl_add_u64 v[118:119], v[120:121], 0, v[118:119]
	v_min_i32_e32 v120, 0x8000, v122
	v_ashrrev_i32_e32 v120, 12, v120
	v_mul_hi_i32_i24_e32 v121, 0x6000, v120
	v_mul_i32_i24_e32 v120, 0x6000, v120
	v_lshl_add_u64 v[118:119], v[118:119], 0, v[96:97]
	v_lshl_add_u64 v[120:121], s[0:1], 0, v[120:121]
	v_lshl_add_u64 v[120:121], v[120:121], 0, v[96:97]
	ds_read_b128 v[122:125], v130 offset:5440
	global_load_dwordx4 v[126:129], v[118:119], off
	global_load_dwordx4 v[158:161], v[120:121], off
	s_waitcnt vmcnt(0) lgkmcnt(0)
	v_pk_fma_f32 v[122:123], v[122:123], v[158:159], v[126:127]
	v_pk_fma_f32 v[124:125], v[124:125], v[160:161], v[128:129]
	v_or_b32_e32 v126, v156, v153
	global_store_dwordx4 v[118:119], v[122:125], off
	v_cmp_gt_i32_e32 vcc, s39, v126
	s_nop 0
	v_ashrrev_i32_e32 v122, 31, v126
	v_add_u32_e32 v124, 0xffff8000, v126
	v_cndmask_b32_e32 v123, 0, v122, vcc
	v_cndmask_b32_e32 v122, v124, v126, vcc
	v_cndmask_b32_e32 v125, v144, v145, vcc
	v_cndmask_b32_e32 v124, v146, v147, vcc
	v_lshlrev_b64 v[122:123], 12, v[122:123]
	v_lshl_add_u64 v[122:123], v[124:125], 0, v[122:123]
	v_min_i32_e32 v124, 0x8000, v126
	v_ashrrev_i32_e32 v124, 12, v124
	v_mul_hi_i32_i24_e32 v125, 0x6000, v124
	v_mul_i32_i24_e32 v124, 0x6000, v124
	v_lshl_add_u64 v[122:123], v[122:123], 0, v[96:97]
	v_lshl_add_u64 v[124:125], s[0:1], 0, v[124:125]
	v_lshl_add_u64 v[124:125], v[124:125], 0, v[96:97]
	ds_read_b128 v[126:129], v130 offset:6528
	global_load_dwordx4 v[158:161], v[122:123], off
	global_load_dwordx4 v[162:165], v[124:125], off
	v_cmp_gt_i32_e32 vcc, s39, v157
	s_waitcnt vmcnt(0) lgkmcnt(0)
	v_pk_fma_f32 v[126:127], v[126:127], v[162:163], v[158:159]
	v_pk_fma_f32 v[128:129], v[128:129], v[164:165], v[160:161]
	global_store_dwordx4 v[122:123], v[126:129], off
	ds_read_b128 v[158:161], v130 offset:7616
	s_nop 0
	v_ashrrev_i32_e32 v126, 31, v157
	v_add_u32_e32 v128, 0xffff8000, v157
	v_cndmask_b32_e32 v127, 0, v126, vcc
	v_cndmask_b32_e32 v126, v128, v157, vcc
	v_cndmask_b32_e32 v129, v144, v145, vcc
	v_cndmask_b32_e32 v128, v146, v147, vcc
	v_lshlrev_b64 v[126:127], 12, v[126:127]
	v_lshl_add_u64 v[126:127], v[128:129], 0, v[126:127]
	v_min_i32_e32 v128, 0x8000, v157
	v_ashrrev_i32_e32 v128, 12, v128
	v_mul_hi_i32_i24_e32 v129, 0x6000, v128
	v_mul_i32_i24_e32 v128, 0x6000, v128
	v_lshl_add_u64 v[126:127], v[126:127], 0, v[96:97]
	v_lshl_add_u64 v[128:129], s[0:1], 0, v[128:129]
	v_lshl_add_u64 v[128:129], v[128:129], 0, v[96:97]
	global_load_dwordx4 v[162:165], v[126:127], off
	global_load_dwordx4 v[166:169], v[128:129], off
	s_waitcnt vmcnt(0) lgkmcnt(0)
	v_pk_fma_f32 v[158:159], v[158:159], v[166:167], v[162:163]
	v_pk_fma_f32 v[160:161], v[160:161], v[168:169], v[164:165]
	global_store_dwordx4 v[126:127], v[158:161], off
	s_waitcnt lgkmcnt(0)
	ds_write2_b32 v131, v80, v81 offset1:68
	ds_write2_b32 v132, v64, v65 offset0:32 offset1:100
	ds_write2_b32 v131, v82, v83 offset0:136 offset1:204
	ds_write2_b32 v132, v66, v67 offset0:168 offset1:236
	ds_write2_b32 v133, v84, v85 offset0:32 offset1:100
	ds_write2_b32 v134, v68, v69 offset0:64 offset1:132
	ds_write2_b32 v133, v86, v87 offset0:168 offset1:236
	ds_write2_b32 v135, v70, v71 offset0:72 offset1:140
	ds_write2_b32 v136, v88, v89 offset0:64 offset1:132
	ds_write2_b32 v137, v72, v73 offset0:96 offset1:164
	ds_write2_b32 v138, v90, v91 offset0:72 offset1:140
	ds_write2_b32 v139, v74, v75 offset0:104 offset1:172
	ds_write2_b32 v140, v92, v93 offset0:96 offset1:164
	ds_write2_b32 v141, v76, v77 offset0:128 offset1:196
	ds_write2_b32 v142, v94, v95 offset0:104 offset1:172
	ds_write2_b32 v143, v78, v79 offset0:8 offset1:76
	s_waitcnt lgkmcnt(0)
	ds_read_b128 v[64:67], v130
	global_load_dwordx4 v[68:71], v[98:99], off offset:256
	global_load_dwordx4 v[72:75], v[100:101], off offset:256
	s_waitcnt vmcnt(0) lgkmcnt(0)
	v_pk_fma_f32 v[64:65], v[64:65], v[72:73], v[68:69]
	v_pk_fma_f32 v[66:67], v[66:67], v[74:75], v[70:71]
	global_store_dwordx4 v[98:99], v[64:67], off offset:256
	ds_read_b128 v[64:67], v130 offset:1088
	global_load_dwordx4 v[68:71], v[102:103], off offset:256
	global_load_dwordx4 v[72:75], v[104:105], off offset:256
	s_waitcnt vmcnt(0) lgkmcnt(0)
	v_pk_fma_f32 v[64:65], v[64:65], v[72:73], v[68:69]
	v_pk_fma_f32 v[66:67], v[66:67], v[74:75], v[70:71]
	global_store_dwordx4 v[102:103], v[64:67], off offset:256
	ds_read_b128 v[64:67], v130 offset:2176
	global_load_dwordx4 v[68:71], v[106:107], off offset:256
	global_load_dwordx4 v[72:75], v[108:109], off offset:256
	s_waitcnt vmcnt(0) lgkmcnt(0)
	v_pk_fma_f32 v[64:65], v[64:65], v[72:73], v[68:69]
	v_pk_fma_f32 v[66:67], v[66:67], v[74:75], v[70:71]
	global_store_dwordx4 v[106:107], v[64:67], off offset:256
	ds_read_b128 v[64:67], v130 offset:3264
	global_load_dwordx4 v[68:71], v[110:111], off offset:256
	global_load_dwordx4 v[72:75], v[112:113], off offset:256
	s_waitcnt vmcnt(0) lgkmcnt(0)
	v_pk_fma_f32 v[64:65], v[64:65], v[72:73], v[68:69]
	v_pk_fma_f32 v[66:67], v[66:67], v[74:75], v[70:71]
	global_store_dwordx4 v[110:111], v[64:67], off offset:256
	ds_read_b128 v[64:67], v130 offset:4352
	global_load_dwordx4 v[68:71], v[114:115], off offset:256
	global_load_dwordx4 v[72:75], v[116:117], off offset:256
	s_waitcnt vmcnt(0) lgkmcnt(0)
	v_pk_fma_f32 v[64:65], v[64:65], v[72:73], v[68:69]
	v_pk_fma_f32 v[66:67], v[66:67], v[74:75], v[70:71]
	global_store_dwordx4 v[114:115], v[64:67], off offset:256
	ds_read_b128 v[64:67], v130 offset:5440
	global_load_dwordx4 v[68:71], v[118:119], off offset:256
	global_load_dwordx4 v[72:75], v[120:121], off offset:256
	s_waitcnt vmcnt(0) lgkmcnt(0)
	v_pk_fma_f32 v[64:65], v[64:65], v[72:73], v[68:69]
	v_pk_fma_f32 v[66:67], v[66:67], v[74:75], v[70:71]
	global_store_dwordx4 v[118:119], v[64:67], off offset:256
	ds_read_b128 v[64:67], v130 offset:6528
	global_load_dwordx4 v[68:71], v[122:123], off offset:256
	global_load_dwordx4 v[72:75], v[124:125], off offset:256
	s_waitcnt vmcnt(0) lgkmcnt(0)
	v_pk_fma_f32 v[64:65], v[64:65], v[72:73], v[68:69]
	v_pk_fma_f32 v[66:67], v[66:67], v[74:75], v[70:71]
	global_store_dwordx4 v[122:123], v[64:67], off offset:256
	ds_read_b128 v[64:67], v130 offset:7616
	global_load_dwordx4 v[68:71], v[126:127], off offset:256
	global_load_dwordx4 v[72:75], v[128:129], off offset:256
	s_waitcnt vmcnt(0) lgkmcnt(0)
	v_pk_fma_f32 v[64:65], v[64:65], v[72:73], v[68:69]
	v_pk_fma_f32 v[66:67], v[66:67], v[74:75], v[70:71]
	global_store_dwordx4 v[126:127], v[64:67], off offset:256
	s_waitcnt lgkmcnt(0)
	ds_write2_b32 v131, v48, v49 offset1:68
	ds_write2_b32 v132, v32, v33 offset0:32 offset1:100
	ds_write2_b32 v131, v50, v51 offset0:136 offset1:204
	ds_write2_b32 v132, v34, v35 offset0:168 offset1:236
	ds_write2_b32 v133, v52, v53 offset0:32 offset1:100
	ds_write2_b32 v134, v36, v37 offset0:64 offset1:132
	ds_write2_b32 v133, v54, v55 offset0:168 offset1:236
	ds_write2_b32 v135, v38, v39 offset0:72 offset1:140
	ds_write2_b32 v136, v56, v57 offset0:64 offset1:132
	ds_write2_b32 v137, v40, v41 offset0:96 offset1:164
	ds_write2_b32 v138, v58, v59 offset0:72 offset1:140
	ds_write2_b32 v139, v42, v43 offset0:104 offset1:172
	ds_write2_b32 v140, v60, v61 offset0:96 offset1:164
	ds_write2_b32 v141, v44, v45 offset0:128 offset1:196
	ds_write2_b32 v142, v62, v63 offset0:104 offset1:172
	ds_write2_b32 v143, v46, v47 offset0:8 offset1:76
	v_or_b32_e32 v64, 32, v156
	v_or_b32_e32 v36, v64, v155
	v_cmp_gt_i32_e32 vcc, s39, v36
	v_ashrrev_i32_e32 v32, 31, v36
	v_add_u32_e32 v34, 0xffff8000, v36
	v_cndmask_b32_e32 v33, 0, v32, vcc
	v_cndmask_b32_e32 v32, v34, v36, vcc
	v_cndmask_b32_e32 v35, v144, v145, vcc
	v_cndmask_b32_e32 v34, v146, v147, vcc
	v_lshlrev_b64 v[32:33], 12, v[32:33]
	v_lshl_add_u64 v[32:33], v[34:35], 0, v[32:33]
	v_min_i32_e32 v34, 0x8000, v36
	v_ashrrev_i32_e32 v34, 12, v34
	v_mul_hi_i32_i24_e32 v35, 0x6000, v34
	v_mul_i32_i24_e32 v34, 0x6000, v34
	s_waitcnt lgkmcnt(0)
	v_lshl_add_u64 v[32:33], v[32:33], 0, v[96:97]
	v_lshl_add_u64 v[34:35], s[0:1], 0, v[34:35]
	v_lshl_add_u64 v[34:35], v[34:35], 0, v[96:97]
	ds_read_b128 v[36:39], v130
	global_load_dwordx4 v[40:43], v[32:33], off
	global_load_dwordx4 v[44:47], v[34:35], off
	s_waitcnt vmcnt(0) lgkmcnt(0)
	v_pk_fma_f32 v[36:37], v[36:37], v[44:45], v[40:41]
	v_pk_fma_f32 v[38:39], v[38:39], v[46:47], v[42:43]
	v_or_b32_e32 v40, v64, v148
	global_store_dwordx4 v[32:33], v[36:39], off
	v_cmp_gt_i32_e32 vcc, s39, v40
	s_nop 0
	v_ashrrev_i32_e32 v36, 31, v40
	v_add_u32_e32 v38, 0xffff8000, v40
	v_cndmask_b32_e32 v37, 0, v36, vcc
	v_cndmask_b32_e32 v36, v38, v40, vcc
	v_cndmask_b32_e32 v39, v144, v145, vcc
	v_cndmask_b32_e32 v38, v146, v147, vcc
	v_lshlrev_b64 v[36:37], 12, v[36:37]
	v_lshl_add_u64 v[36:37], v[38:39], 0, v[36:37]
	v_min_i32_e32 v38, 0x8000, v40
	v_ashrrev_i32_e32 v38, 12, v38
	v_mul_hi_i32_i24_e32 v39, 0x6000, v38
	v_mul_i32_i24_e32 v38, 0x6000, v38
	v_lshl_add_u64 v[36:37], v[36:37], 0, v[96:97]
	v_lshl_add_u64 v[38:39], s[0:1], 0, v[38:39]
	v_lshl_add_u64 v[38:39], v[38:39], 0, v[96:97]
	ds_read_b128 v[40:43], v130 offset:1088
	global_load_dwordx4 v[44:47], v[36:37], off
	global_load_dwordx4 v[48:51], v[38:39], off
	s_waitcnt vmcnt(0) lgkmcnt(0)
	v_pk_fma_f32 v[40:41], v[40:41], v[48:49], v[44:45]
	v_pk_fma_f32 v[42:43], v[42:43], v[50:51], v[46:47]
	v_or_b32_e32 v44, v64, v149
	global_store_dwordx4 v[36:37], v[40:43], off
	v_cmp_gt_i32_e32 vcc, s39, v44
	s_nop 0
	v_ashrrev_i32_e32 v40, 31, v44
	v_add_u32_e32 v42, 0xffff8000, v44
	v_cndmask_b32_e32 v41, 0, v40, vcc
	v_cndmask_b32_e32 v40, v42, v44, vcc
	v_cndmask_b32_e32 v43, v144, v145, vcc
	v_cndmask_b32_e32 v42, v146, v147, vcc
	v_lshlrev_b64 v[40:41], 12, v[40:41]
	v_lshl_add_u64 v[40:41], v[42:43], 0, v[40:41]
	v_min_i32_e32 v42, 0x8000, v44
	v_ashrrev_i32_e32 v42, 12, v42
	v_mul_hi_i32_i24_e32 v43, 0x6000, v42
	v_mul_i32_i24_e32 v42, 0x6000, v42
	v_lshl_add_u64 v[40:41], v[40:41], 0, v[96:97]
	v_lshl_add_u64 v[42:43], s[0:1], 0, v[42:43]
	v_lshl_add_u64 v[42:43], v[42:43], 0, v[96:97]
	ds_read_b128 v[44:47], v130 offset:2176
	global_load_dwordx4 v[48:51], v[40:41], off
	global_load_dwordx4 v[52:55], v[42:43], off
	s_waitcnt vmcnt(0) lgkmcnt(0)
	v_pk_fma_f32 v[44:45], v[44:45], v[52:53], v[48:49]
	v_pk_fma_f32 v[46:47], v[46:47], v[54:55], v[50:51]
	v_or_b32_e32 v48, v64, v150
	global_store_dwordx4 v[40:41], v[44:47], off
	v_cmp_gt_i32_e32 vcc, s39, v48
	s_nop 0
	v_ashrrev_i32_e32 v44, 31, v48
	v_add_u32_e32 v46, 0xffff8000, v48
	v_cndmask_b32_e32 v45, 0, v44, vcc
	v_cndmask_b32_e32 v44, v46, v48, vcc
	v_cndmask_b32_e32 v47, v144, v145, vcc
	v_cndmask_b32_e32 v46, v146, v147, vcc
	v_lshlrev_b64 v[44:45], 12, v[44:45]
	v_lshl_add_u64 v[44:45], v[46:47], 0, v[44:45]
	v_min_i32_e32 v46, 0x8000, v48
	v_ashrrev_i32_e32 v46, 12, v46
	v_mul_hi_i32_i24_e32 v47, 0x6000, v46
	v_mul_i32_i24_e32 v46, 0x6000, v46
	v_lshl_add_u64 v[44:45], v[44:45], 0, v[96:97]
	v_lshl_add_u64 v[46:47], s[0:1], 0, v[46:47]
	v_lshl_add_u64 v[46:47], v[46:47], 0, v[96:97]
	ds_read_b128 v[48:51], v130 offset:3264
	global_load_dwordx4 v[52:55], v[44:45], off
	global_load_dwordx4 v[56:59], v[46:47], off
	s_waitcnt vmcnt(0) lgkmcnt(0)
	v_pk_fma_f32 v[48:49], v[48:49], v[56:57], v[52:53]
	v_pk_fma_f32 v[50:51], v[50:51], v[58:59], v[54:55]
	v_or_b32_e32 v52, v64, v151
	global_store_dwordx4 v[44:45], v[48:51], off
	v_cmp_gt_i32_e32 vcc, s39, v52
	s_nop 0
	v_ashrrev_i32_e32 v48, 31, v52
	v_add_u32_e32 v50, 0xffff8000, v52
	v_cndmask_b32_e32 v49, 0, v48, vcc
	v_cndmask_b32_e32 v48, v50, v52, vcc
	v_cndmask_b32_e32 v51, v144, v145, vcc
	v_cndmask_b32_e32 v50, v146, v147, vcc
	v_lshlrev_b64 v[48:49], 12, v[48:49]
	v_lshl_add_u64 v[48:49], v[50:51], 0, v[48:49]
	v_min_i32_e32 v50, 0x8000, v52
	v_ashrrev_i32_e32 v50, 12, v50
	v_mul_hi_i32_i24_e32 v51, 0x6000, v50
	v_mul_i32_i24_e32 v50, 0x6000, v50
	v_lshl_add_u64 v[48:49], v[48:49], 0, v[96:97]
	v_lshl_add_u64 v[50:51], s[0:1], 0, v[50:51]
	v_lshl_add_u64 v[50:51], v[50:51], 0, v[96:97]
	ds_read_b128 v[52:55], v130 offset:4352
	global_load_dwordx4 v[56:59], v[48:49], off
	global_load_dwordx4 v[60:63], v[50:51], off
	s_waitcnt vmcnt(0) lgkmcnt(0)
	v_pk_fma_f32 v[52:53], v[52:53], v[60:61], v[56:57]
	v_pk_fma_f32 v[54:55], v[54:55], v[62:63], v[58:59]
	v_or_b32_e32 v56, v64, v152
	global_store_dwordx4 v[48:49], v[52:55], off
	v_cmp_gt_i32_e32 vcc, s39, v56
	s_nop 0
	v_ashrrev_i32_e32 v52, 31, v56
	v_add_u32_e32 v54, 0xffff8000, v56
	v_cndmask_b32_e32 v53, 0, v52, vcc
	v_cndmask_b32_e32 v52, v54, v56, vcc
	v_cndmask_b32_e32 v55, v144, v145, vcc
	v_cndmask_b32_e32 v54, v146, v147, vcc
	v_lshlrev_b64 v[52:53], 12, v[52:53]
	v_lshl_add_u64 v[52:53], v[54:55], 0, v[52:53]
	v_min_i32_e32 v54, 0x8000, v56
	v_ashrrev_i32_e32 v54, 12, v54
	v_mul_hi_i32_i24_e32 v55, 0x6000, v54
	v_mul_i32_i24_e32 v54, 0x6000, v54
	v_lshl_add_u64 v[52:53], v[52:53], 0, v[96:97]
	v_lshl_add_u64 v[54:55], s[0:1], 0, v[54:55]
	v_lshl_add_u64 v[54:55], v[54:55], 0, v[96:97]
	ds_read_b128 v[56:59], v130 offset:5440
	global_load_dwordx4 v[60:63], v[52:53], off
	global_load_dwordx4 v[66:69], v[54:55], off
	s_waitcnt vmcnt(0) lgkmcnt(0)
	v_pk_fma_f32 v[56:57], v[56:57], v[66:67], v[60:61]
	v_pk_fma_f32 v[58:59], v[58:59], v[68:69], v[62:63]
	v_or_b32_e32 v60, v64, v153
	global_store_dwordx4 v[52:53], v[56:59], off
	v_cmp_gt_i32_e32 vcc, s39, v60
	v_or_b32_e32 v64, v64, v154
	v_ashrrev_i32_e32 v56, 31, v60
	v_add_u32_e32 v58, 0xffff8000, v60
	v_cndmask_b32_e32 v57, 0, v56, vcc
	v_cndmask_b32_e32 v56, v58, v60, vcc
	v_cndmask_b32_e32 v59, v144, v145, vcc
	v_cndmask_b32_e32 v58, v146, v147, vcc
	v_lshlrev_b64 v[56:57], 12, v[56:57]
	v_lshl_add_u64 v[56:57], v[58:59], 0, v[56:57]
	v_min_i32_e32 v58, 0x8000, v60
	v_ashrrev_i32_e32 v58, 12, v58
	v_mul_hi_i32_i24_e32 v59, 0x6000, v58
	v_mul_i32_i24_e32 v58, 0x6000, v58
	v_lshl_add_u64 v[56:57], v[56:57], 0, v[96:97]
	v_lshl_add_u64 v[58:59], s[0:1], 0, v[58:59]
	v_lshl_add_u64 v[58:59], v[58:59], 0, v[96:97]
	ds_read_b128 v[60:63], v130 offset:6528
	global_load_dwordx4 v[66:69], v[56:57], off
	global_load_dwordx4 v[70:73], v[58:59], off
	v_cmp_gt_i32_e32 vcc, s39, v64
	s_waitcnt vmcnt(0) lgkmcnt(0)
	v_pk_fma_f32 v[60:61], v[60:61], v[70:71], v[66:67]
	v_pk_fma_f32 v[62:63], v[62:63], v[72:73], v[68:69]
	global_store_dwordx4 v[56:57], v[60:63], off
	s_nop 1
	v_ashrrev_i32_e32 v60, 31, v64
	v_add_u32_e32 v62, 0xffff8000, v64
	v_cndmask_b32_e32 v61, 0, v60, vcc
	v_cndmask_b32_e32 v60, v62, v64, vcc
	v_cndmask_b32_e32 v63, v144, v145, vcc
	v_cndmask_b32_e32 v62, v146, v147, vcc
	v_lshlrev_b64 v[60:61], 12, v[60:61]
	v_lshl_add_u64 v[60:61], v[62:63], 0, v[60:61]
	v_min_i32_e32 v62, 0x8000, v64
	v_ashrrev_i32_e32 v62, 12, v62
	v_mul_hi_i32_i24_e32 v63, 0x6000, v62
	v_mul_i32_i24_e32 v62, 0x6000, v62
	v_lshl_add_u64 v[60:61], v[60:61], 0, v[96:97]
	v_lshl_add_u64 v[62:63], s[0:1], 0, v[62:63]
	v_lshl_add_u64 v[62:63], v[62:63], 0, v[96:97]
	ds_read_b128 v[64:67], v130 offset:7616
	global_load_dwordx4 v[68:71], v[60:61], off
	global_load_dwordx4 v[72:75], v[62:63], off
	s_waitcnt vmcnt(0) lgkmcnt(0)
	v_pk_fma_f32 v[64:65], v[64:65], v[72:73], v[68:69]
	v_pk_fma_f32 v[66:67], v[66:67], v[74:75], v[70:71]
	global_store_dwordx4 v[60:61], v[64:67], off
	s_waitcnt lgkmcnt(0)
	ds_write2_b32 v131, v16, v17 offset1:68
	ds_write2_b32 v132, v0, v1 offset0:32 offset1:100
	ds_write2_b32 v131, v18, v19 offset0:136 offset1:204
	ds_write2_b32 v132, v2, v3 offset0:168 offset1:236
	ds_write2_b32 v133, v20, v21 offset0:32 offset1:100
	ds_write2_b32 v134, v4, v5 offset0:64 offset1:132
	ds_write2_b32 v133, v22, v23 offset0:168 offset1:236
	ds_write2_b32 v135, v6, v7 offset0:72 offset1:140
	ds_write2_b32 v136, v24, v25 offset0:64 offset1:132
	ds_write2_b32 v137, v8, v9 offset0:96 offset1:164
	ds_write2_b32 v138, v26, v27 offset0:72 offset1:140
	ds_write2_b32 v139, v10, v11 offset0:104 offset1:172
	ds_write2_b32 v140, v28, v29 offset0:96 offset1:164
	ds_write2_b32 v141, v12, v13 offset0:128 offset1:196
	ds_write2_b32 v142, v30, v31 offset0:104 offset1:172
	ds_write2_b32 v143, v14, v15 offset0:8 offset1:76
	s_waitcnt lgkmcnt(0)
	ds_read_b128 v[0:3], v130
	global_load_dwordx4 v[4:7], v[32:33], off offset:256
	global_load_dwordx4 v[8:11], v[34:35], off offset:256
	s_waitcnt vmcnt(0) lgkmcnt(0)
	v_pk_fma_f32 v[0:1], v[0:1], v[8:9], v[4:5]
	v_pk_fma_f32 v[2:3], v[2:3], v[10:11], v[6:7]
	global_store_dwordx4 v[32:33], v[0:3], off offset:256
	ds_read_b128 v[0:3], v130 offset:1088
	global_load_dwordx4 v[4:7], v[36:37], off offset:256
	global_load_dwordx4 v[8:11], v[38:39], off offset:256
	s_waitcnt vmcnt(0) lgkmcnt(0)
	v_pk_fma_f32 v[0:1], v[0:1], v[8:9], v[4:5]
	v_pk_fma_f32 v[2:3], v[2:3], v[10:11], v[6:7]
	global_store_dwordx4 v[36:37], v[0:3], off offset:256
	ds_read_b128 v[0:3], v130 offset:2176
	global_load_dwordx4 v[4:7], v[40:41], off offset:256
	global_load_dwordx4 v[8:11], v[42:43], off offset:256
	s_waitcnt vmcnt(0) lgkmcnt(0)
	v_pk_fma_f32 v[0:1], v[0:1], v[8:9], v[4:5]
	v_pk_fma_f32 v[2:3], v[2:3], v[10:11], v[6:7]
	global_store_dwordx4 v[40:41], v[0:3], off offset:256
	ds_read_b128 v[0:3], v130 offset:3264
	global_load_dwordx4 v[4:7], v[44:45], off offset:256
	global_load_dwordx4 v[8:11], v[46:47], off offset:256
	s_waitcnt vmcnt(0) lgkmcnt(0)
	v_pk_fma_f32 v[0:1], v[0:1], v[8:9], v[4:5]
	v_pk_fma_f32 v[2:3], v[2:3], v[10:11], v[6:7]
	global_store_dwordx4 v[44:45], v[0:3], off offset:256
	ds_read_b128 v[0:3], v130 offset:4352
	global_load_dwordx4 v[4:7], v[48:49], off offset:256
	global_load_dwordx4 v[8:11], v[50:51], off offset:256
	s_waitcnt vmcnt(0) lgkmcnt(0)
	v_pk_fma_f32 v[0:1], v[0:1], v[8:9], v[4:5]
	v_pk_fma_f32 v[2:3], v[2:3], v[10:11], v[6:7]
	global_store_dwordx4 v[48:49], v[0:3], off offset:256
	ds_read_b128 v[0:3], v130 offset:5440
	global_load_dwordx4 v[4:7], v[52:53], off offset:256
	global_load_dwordx4 v[8:11], v[54:55], off offset:256
	s_waitcnt vmcnt(0) lgkmcnt(0)
	v_pk_fma_f32 v[0:1], v[0:1], v[8:9], v[4:5]
	v_pk_fma_f32 v[2:3], v[2:3], v[10:11], v[6:7]
	global_store_dwordx4 v[52:53], v[0:3], off offset:256
	ds_read_b128 v[0:3], v130 offset:6528
	global_load_dwordx4 v[4:7], v[56:57], off offset:256
	global_load_dwordx4 v[8:11], v[58:59], off offset:256
	s_waitcnt vmcnt(0) lgkmcnt(0)
	v_pk_fma_f32 v[0:1], v[0:1], v[8:9], v[4:5]
	v_pk_fma_f32 v[2:3], v[2:3], v[10:11], v[6:7]
	global_store_dwordx4 v[56:57], v[0:3], off offset:256
	ds_read_b128 v[0:3], v130 offset:7616
	global_load_dwordx4 v[4:7], v[60:61], off offset:256
	global_load_dwordx4 v[8:11], v[62:63], off offset:256
	s_waitcnt vmcnt(0) lgkmcnt(0)
	v_pk_fma_f32 v[0:1], v[0:1], v[8:9], v[4:5]
	v_pk_fma_f32 v[2:3], v[2:3], v[10:11], v[6:7]
	global_store_dwordx4 v[60:61], v[0:3], off offset:256
	s_waitcnt lgkmcnt(0)
	s_barrier
	s_cbranch_scc1 .LBB0_1086
